# RWKV chunk scan loops rewritten: operand rows vector-loaded 2 steps ahead (counted vmcnt) and broadcast with DPP row_newbcast instead of serialized s_load+lgkmcnt(0); f32 math unchanged
# speedup vs baseline: 1.0193x; 1.0193x over previous
; __device__ __forceinline__ const float* uni_ptr(const float* p) { const unsigned long long v = (unsigned long long)p; const unsigned lo = __builtin_amdgcn_readfirstlane((unsigned)v), hi = __builtin_amdgcn_readfirstlane((unsigned)(v >> 32)); return (const float*)(((unsigned long long)hi << 32) | lo); }
; template <bool SK>
; __device__ __forceinline__ void scan_task(const float* R, const float* W, const float* KX, const float* KK, const float* KKA, const float* V, float* OUT, float* STT, const float* S0, float* SOUT, int nstep, int lane) {
;     ...
;     if (S0) {
; #pragma unroll
;         for (int k4 = 0; k4 < 16; ++k4) { const f32x4 v = *(const f32x4*)(S0 + lane * 64 + 4 * k4); s[4 * k4] = v[0]; s[4 * k4 + 1] = v[1]; s[4 * k4 + 2] = v[2]; s[4 * k4 + 3] = v[3]; }
;     } else {
; #pragma unroll
;         for (int k = 0; k < 64; ++k) s[k] = SK ? 0.f : (k == lane ? 1.f : 0.f);
;     }
; __device__ __forceinline__ void scan_item(Frame& F, int l, int item, unsigned char* ws) {
;     const int b = item >> 7, chunk = (item >> 1) & 63, hq = item & 1, h = hq * 4 + (F.wave & 3);
;     const size_t ro = ((size_t)(b * SEQ + chunk * 64)) * BW + h * 64; const size_t so = ((size_t)((b * 8 + h) * 64 + chunk)) * 4096;
;     const float* R = (const float*)(ws + WS_R + l * SZ_RWL) + ro; const float* W = (const float*)(ws + WS_W + l * SZ_RWL) + ro; const float* KX = (const float*)(ws + WS_KX + l * SZ_RWL) + ro;
;     const float* KK = (const float*)(ws + WS_KK + l * SZ_RWL) + ro; const float* KKA = (const float*)(ws + WS_KKA + l * SZ_RWL) + ro; const float* V = (const float*)(ws + WS_V) + ro;
;     if (F.wave >> 2) scan_task<true>(uni_ptr(R), uni_ptr(W), uni_ptr(KX), uni_ptr(KK), uni_ptr(KKA), V, (float*)(ws + WS_OL) + ro, (float*)(ws + WS_LC) + so, nullptr, nullptr, 64, F.lane);
.LBB0_904:
	s_mov_b64 s[8:9], s[62:63]
	s_mov_b32 s1, s66
	v_mov_b32_e32 v68, v210
	s_mov_b32 s2, s97
	v_mov_b32_e32 v1, v0
	s_mov_b32 s0, s94
	s_nop 0
	v_readlane_b32 s2, v252, 14
	v_readlane_b32 s3, v252, 15
	s_andn2_b64 vcc, exec, s[2:3]
	s_cbranch_vccnz .LBB0_903
	s_lshl_b32 s2, s29, 6
	s_bfe_u32 s4, s24, 0x60001
	s_and_b32 s7, s2, 0x100
	s_ashr_i32 s5, s24, 7
	s_lshl_b32 s2, s24, 2
	v_and_b32_e64 v1, s0, 3
	s_lshl_b32 s28, s4, 6
	v_readfirstlane_b32 s25, v1
	v_and_or_b32 v1, s2, 4, v1
	s_lshl_b32 s33, s5, 12
	s_lshl_b32 s5, s5, 9
	s_or_b32 s2, s28, s33
	v_lshl_or_b32 v2, v1, 6, s5
	s_ashr_i32 s3, s2, 31
	v_or_b32_e32 v2, s4, v2
	s_waitcnt lgkmcnt(0)
	v_ashrrev_i32_e32 v3, 31, v2
	s_mul_hi_i32 s4, s1, 0x1100000
	s_mul_i32 s1, s1, 0x1100000
	s_lshl_b64 s[2:3], s[2:3], 11
	v_lshlrev_b64 v[70:71], 12, v[2:3]
	v_lshl_or_b32 v2, v1, 8, s2
	s_add_u32 s2, s8, s1
	v_mov_b32_e32 v3, s3
	s_addc_u32 s3, s9, s4
	v_lshl_add_u64 v[2:3], s[2:3], 0, v[2:3]
	s_mov_b64 s[2:3], 0x34c00000
	v_lshl_add_u64 v[10:11], v[2:3], 0, s[2:3]
	s_mov_b64 s[2:3], 0x36e00000
	v_lshl_add_u64 v[8:9], v[2:3], 0, s[2:3]
	s_mov_b64 s[2:3], 0x39000000
	v_lshl_add_u64 v[6:7], v[2:3], 0, s[2:3]
	s_mov_b64 s[2:3], 0x3c300000
	v_lshl_add_u64 v[4:5], v[2:3], 0, s[2:3]
	s_mov_b64 s[2:3], 0x3e500000
	v_lshl_add_u64 v[2:3], v[2:3], 0, s[2:3]
	v_cmp_lt_u32_e64 s[2:3], s0, 4
	s_mov_b64 s[0:1], -1
	s_and_b64 s[2:3], s[2:3], exec
	v_ashrrev_i32_e32 v69, 31, v68
	s_cbranch_scc1 .LBB0_909
	s_add_i32 s4, s33, s28
	s_lshl_b32 s6, s25, 6
	s_ashr_i32 s5, s4, 31
	s_add_i32 s6, s7, s6
	s_lshl_b64 s[4:5], s[4:5], 11
	s_lshl_b32 s6, s6, 2
	v_writelane_b32 v255, s7, 27
	s_add_u32 s6, s8, s6
	v_writelane_b32 v255, s8, 23
	s_addc_u32 s7, s9, 0
	s_add_u32 s4, s6, s4
	s_addc_u32 s5, s7, s5
	v_readfirstlane_b32 s27, v11
	v_readfirstlane_b32 s26, v10
	v_readfirstlane_b32 s35, v9
	v_readfirstlane_b32 s34, v8
	v_readfirstlane_b32 s3, v7
	v_readfirstlane_b32 s2, v6
	v_readfirstlane_b32 s37, v5
	v_readfirstlane_b32 s36, v4
	v_readfirstlane_b32 s1, v3
	v_readfirstlane_b32 s0, v2
	v_lshl_add_u64 v[12:13], v[68:69], 2, s[4:5]
	s_mov_b64 s[4:5], 0x3b200000
	v_mov_b32_e32 v1, 0
	v_writelane_b32 v255, s9, 24
	s_waitcnt vmcnt(0)
	v_lshl_add_u64 v[52:53], v[12:13], 0, s[4:5]
	s_mov_b32 s31, 0
	s_mov_b64 s[96:97], s[36:37]
	s_mov_b64 s[90:91], s[34:35]
	s_mov_b64 s[94:95], s[0:1]
	s_mov_b64 s[92:93], s[2:3]
	s_mov_b64 s[88:89], s[26:27]
	v_mov_b32_e32 v88, 0
	v_mov_b32_e32 v89, 0
	v_mov_b32_e32 v90, 0
	v_mov_b32_e32 v91, 0
	v_mov_b32_e32 v82, 0
	v_mov_b32_e32 v83, v1
	v_mov_b32_e32 v12, 0
	v_mov_b32_e32 v13, v1
	v_mov_b32_e32 v14, 0
	v_mov_b32_e32 v15, v1
	v_mov_b32_e32 v16, 0
	v_mov_b32_e32 v17, v1
	v_mov_b32_e32 v18, 0
	v_mov_b32_e32 v19, v1
	v_mov_b32_e32 v20, 0
	v_mov_b32_e32 v21, v1
	v_mov_b32_e32 v22, 0
	v_mov_b32_e32 v23, v1
	v_mov_b32_e32 v24, 0
	v_mov_b32_e32 v25, v1
	v_mov_b32_e32 v26, 0
	v_mov_b32_e32 v27, v1
	v_mov_b32_e32 v28, 0
	v_mov_b32_e32 v29, v1
	v_mov_b32_e32 v30, 0
	v_mov_b32_e32 v31, v1
	v_mov_b32_e32 v32, 0
	v_mov_b32_e32 v33, v1
	v_mov_b32_e32 v36, 0
	v_mov_b32_e32 v37, v1
	v_mov_b32_e32 v38, 0
	v_mov_b32_e32 v39, v1
	v_mov_b32_e32 v40, 0
	v_mov_b32_e32 v41, v1
	v_mov_b32_e32 v42, 0
	v_mov_b32_e32 v43, v1
	v_mov_b32_e32 v44, 0
	v_mov_b32_e32 v45, v1
	v_mov_b32_e32 v46, 0
	v_mov_b32_e32 v47, v1
	v_mov_b32_e32 v48, 0
	v_mov_b32_e32 v49, v1
	v_mov_b32_e32 v50, 0
	v_mov_b32_e32 v51, v1
	v_mov_b32_e32 v54, 0
	v_mov_b32_e32 v55, v1
	v_mov_b32_e32 v56, 0
	v_mov_b32_e32 v57, v1
	v_mov_b32_e32 v58, 0
	v_mov_b32_e32 v59, v1
	v_mov_b32_e32 v60, 0
	v_mov_b32_e32 v61, v1
	v_mov_b32_e32 v62, 0
	v_mov_b32_e32 v63, v1
	v_mov_b32_e32 v64, 0
	v_mov_b32_e32 v65, v1
	v_mov_b32_e32 v66, 0
	v_mov_b32_e32 v67, v1
	v_mov_b32_e32 v72, 0
	v_mov_b32_e32 v73, v1
	v_mov_b32_e32 v74, 0
	v_mov_b32_e32 v75, v1
	v_mov_b32_e32 v76, 0
	v_mov_b32_e32 v77, v1
	v_mov_b32_e32 v78, 0
	v_mov_b32_e32 v79, v1
	v_mov_b32_e32 v80, 0
	v_mov_b32_e32 v81, v1
	s_mov_b32 s30, 0x6600000
	s_mov_b64 s[38:39], 0x800
	v_readlane_b32 s8, v251, 3
	s_nop 3
	s_mul_i32 s8, s8, 0x3800
	s_nop 0
	v_lshl_add_u32 v1, v68, 2, s8
	ds_write_b32 v1, v92 offset:0
	ds_write_b32 v1, v93 offset:256
	ds_write_b32 v1, v94 offset:512
	ds_write_b32 v1, v95 offset:768
	ds_write_b32 v1, v96 offset:1024
	ds_write_b32 v1, v97 offset:1280
	ds_write_b32 v1, v98 offset:1536
	ds_write_b32 v1, v99 offset:1792
	ds_write_b32 v1, v100 offset:2048
	ds_write_b32 v1, v101 offset:2304
	ds_write_b32 v1, v102 offset:2560
	ds_write_b32 v1, v103 offset:2816
	ds_write_b32 v1, v104 offset:3072
	ds_write_b32 v1, v105 offset:3328
	ds_write_b32 v1, v106 offset:3584
	ds_write_b32 v1, v107 offset:3840
	ds_write_b32 v1, v108 offset:4096
	ds_write_b32 v1, v109 offset:4352
	ds_write_b32 v1, v110 offset:4608
	ds_write_b32 v1, v111 offset:4864
	ds_write_b32 v1, v112 offset:5120
	ds_write_b32 v1, v113 offset:5376
	ds_write_b32 v1, v114 offset:5632
	ds_write_b32 v1, v115 offset:5888
	ds_write_b32 v1, v116 offset:6144
	ds_write_b32 v1, v117 offset:6400
	ds_write_b32 v1, v118 offset:6656
	ds_write_b32 v1, v119 offset:6912
	ds_write_b32 v1, v120 offset:7168
	ds_write_b32 v1, v121 offset:7424
	ds_write_b32 v1, v122 offset:7680
	ds_write_b32 v1, v123 offset:7936
	ds_write_b32 v1, v124 offset:8192
	ds_write_b32 v1, v125 offset:8448
	ds_write_b32 v1, v126 offset:8704
	ds_write_b32 v1, v127 offset:8960
	ds_write_b32 v1, v128 offset:9216
	ds_write_b32 v1, v129 offset:9472
	ds_write_b32 v1, v130 offset:9728
	ds_write_b32 v1, v131 offset:9984
	ds_write_b32 v1, v132 offset:10240
	ds_write_b32 v1, v133 offset:10496
	ds_write_b32 v1, v134 offset:10752
	ds_write_b32 v1, v135 offset:11008
	ds_write_b32 v1, v136 offset:11264
	ds_write_b32 v1, v137 offset:11520
	ds_write_b32 v1, v138 offset:11776
	ds_write_b32 v1, v139 offset:12032
	ds_write_b32 v1, v140 offset:12288
	ds_write_b32 v1, v141 offset:12544
	ds_write_b32 v1, v142 offset:12800
	ds_write_b32 v1, v143 offset:13056
	ds_write_b32 v1, v144 offset:13312
	ds_write_b32 v1, v145 offset:13568
	v_readfirstlane_b32 s4, v52
	v_readfirstlane_b32 s5, v53
	s_nop 3
	s_add_u32 s6, s4, 0x6600000
	s_addc_u32 s7, s5, 0
	s_waitcnt lgkmcnt(0)
; template <bool SK>
; __device__ __forceinline__ void scan_task(const float* R, const float* W, const float* KX, const float* KK, const float* KKA, const float* V, float* OUT, float* STT, const float* S0, float* SOUT, int nstep, int lane) {
;     ...
;     for (int t = 0; t < nstep; ++t) {
;         asm volatile("" :: "v"(pf0), "v"(pf1), "v"(pf2), "v"(pf3), "v"(pf4));
;         { const int tp = (t + 2 < nstep) ? t + 2 : t; const size_t po = (size_t)tp * BW + lane;
;           pf0 = KK[po]; pf1 = W[po]; pf2 = KKA[po]; pf3 = KX[po]; pf4 = R[po]; }
;         cfloat* kk = (cfloat*)(KK + (size_t)t * BW); cfloat* w = (cfloat*)(W + (size_t)t * BW); cfloat* kka = (cfloat*)(KKA + (size_t)t * BW);
;         cfloat* kx = (cfloat*)(KX + (size_t)t * BW); cfloat* r = (cfloat*)(R + (size_t)t * BW);
;         float d0 = 0.f, d1 = 0.f;
; #pragma unroll
;         for (int k = 0; k < 64; k += 2) { d0 = fmaf(s[k], kk[k], d0); d1 = fmaf(s[k + 1], kk[k + 1], d1); }
;         const float nd = -(d0 + d1);
	v_mov_b32_e32 v145, v1
	v_and_b32_e32 v143, 15, v68
	v_lshlrev_b32_e32 v143, 4, v143
	v_lshlrev_b32_e32 v144, 2, v68
	s_nop 0
	global_load_dwordx4 v[92:95], v143, s[96:97]
	global_load_dwordx4 v[96:99], v143, s[90:91]
	global_load_dwordx4 v[100:103], v143, s[94:95]
	global_load_dwordx4 v[104:107], v143, s[92:93]
	global_load_dwordx4 v[108:111], v143, s[88:89]
	global_load_dword v132, v144, s[4:5]
	global_load_dwordx4 v[112:115], v143, s[96:97] offset:2048
	global_load_dwordx4 v[116:119], v143, s[90:91] offset:2048
	global_load_dwordx4 v[120:123], v143, s[94:95] offset:2048
	global_load_dwordx4 v[124:127], v143, s[92:93] offset:2048
	global_load_dwordx4 v[128:131], v143, s[88:89] offset:2048
	global_load_dword v133, v144, s[4:5] offset:2048
	s_add_u32 s96, s96, 0x1000
	s_addc_u32 s97, s97, 0
	s_add_u32 s90, s90, 0x1000
	s_addc_u32 s91, s91, 0
	s_add_u32 s94, s94, 0x1000
	s_addc_u32 s95, s95, 0
	s_add_u32 s92, s92, 0x1000
	s_addc_u32 s93, s93, 0
	s_add_u32 s88, s88, 0x1000
	s_addc_u32 s89, s89, 0
	s_add_u32 s4, s4, 0x1000
	s_addc_u32 s5, s5, 0
	s_mov_b32 s9, 0
	s_waitcnt vmcnt(0)
.Lscan_s_loop:
	s_waitcnt vmcnt(8)
	v_mul_f32_dpp v134, v92, v80 row_newbcast:0 row_mask:0xf bank_mask:0xf
	v_mul_f32_dpp v135, v93, v81 row_newbcast:0 row_mask:0xf bank_mask:0xf
	v_mul_f32_dpp v136, v94, v78 row_newbcast:0 row_mask:0xf bank_mask:0xf
	v_mul_f32_dpp v137, v95, v79 row_newbcast:0 row_mask:0xf bank_mask:0xf
	v_fmac_f32_dpp v134, v92, v76 row_newbcast:1 row_mask:0xf bank_mask:0xf
	v_fmac_f32_dpp v135, v93, v77 row_newbcast:1 row_mask:0xf bank_mask:0xf
	v_fmac_f32_dpp v136, v94, v74 row_newbcast:1 row_mask:0xf bank_mask:0xf
	v_fmac_f32_dpp v137, v95, v75 row_newbcast:1 row_mask:0xf bank_mask:0xf
	v_fmac_f32_dpp v134, v92, v72 row_newbcast:2 row_mask:0xf bank_mask:0xf
	v_fmac_f32_dpp v135, v93, v73 row_newbcast:2 row_mask:0xf bank_mask:0xf
	v_fmac_f32_dpp v136, v94, v66 row_newbcast:2 row_mask:0xf bank_mask:0xf
	v_fmac_f32_dpp v137, v95, v67 row_newbcast:2 row_mask:0xf bank_mask:0xf
	v_fmac_f32_dpp v134, v92, v64 row_newbcast:3 row_mask:0xf bank_mask:0xf
	v_fmac_f32_dpp v135, v93, v65 row_newbcast:3 row_mask:0xf bank_mask:0xf
	v_fmac_f32_dpp v136, v94, v62 row_newbcast:3 row_mask:0xf bank_mask:0xf
	v_fmac_f32_dpp v137, v95, v63 row_newbcast:3 row_mask:0xf bank_mask:0xf
	v_fmac_f32_dpp v134, v92, v60 row_newbcast:4 row_mask:0xf bank_mask:0xf
	v_fmac_f32_dpp v135, v93, v61 row_newbcast:4 row_mask:0xf bank_mask:0xf
	v_fmac_f32_dpp v136, v94, v58 row_newbcast:4 row_mask:0xf bank_mask:0xf
	v_fmac_f32_dpp v137, v95, v59 row_newbcast:4 row_mask:0xf bank_mask:0xf
	v_fmac_f32_dpp v134, v92, v56 row_newbcast:5 row_mask:0xf bank_mask:0xf
	v_fmac_f32_dpp v135, v93, v57 row_newbcast:5 row_mask:0xf bank_mask:0xf
	v_fmac_f32_dpp v136, v94, v54 row_newbcast:5 row_mask:0xf bank_mask:0xf
	v_fmac_f32_dpp v137, v95, v55 row_newbcast:5 row_mask:0xf bank_mask:0xf
	v_fmac_f32_dpp v134, v92, v50 row_newbcast:6 row_mask:0xf bank_mask:0xf
	v_fmac_f32_dpp v135, v93, v51 row_newbcast:6 row_mask:0xf bank_mask:0xf
	v_fmac_f32_dpp v136, v94, v48 row_newbcast:6 row_mask:0xf bank_mask:0xf
	v_fmac_f32_dpp v137, v95, v49 row_newbcast:6 row_mask:0xf bank_mask:0xf
	v_fmac_f32_dpp v134, v92, v46 row_newbcast:7 row_mask:0xf bank_mask:0xf
	v_fmac_f32_dpp v135, v93, v47 row_newbcast:7 row_mask:0xf bank_mask:0xf
	v_fmac_f32_dpp v136, v94, v44 row_newbcast:7 row_mask:0xf bank_mask:0xf
	v_fmac_f32_dpp v137, v95, v45 row_newbcast:7 row_mask:0xf bank_mask:0xf
	v_fmac_f32_dpp v134, v92, v42 row_newbcast:8 row_mask:0xf bank_mask:0xf
	v_fmac_f32_dpp v135, v93, v43 row_newbcast:8 row_mask:0xf bank_mask:0xf
	v_fmac_f32_dpp v136, v94, v40 row_newbcast:8 row_mask:0xf bank_mask:0xf
	v_fmac_f32_dpp v137, v95, v41 row_newbcast:8 row_mask:0xf bank_mask:0xf
	v_fmac_f32_dpp v134, v92, v38 row_newbcast:9 row_mask:0xf bank_mask:0xf
	v_fmac_f32_dpp v135, v93, v39 row_newbcast:9 row_mask:0xf bank_mask:0xf
	v_fmac_f32_dpp v136, v94, v36 row_newbcast:9 row_mask:0xf bank_mask:0xf
	v_fmac_f32_dpp v137, v95, v37 row_newbcast:9 row_mask:0xf bank_mask:0xf
	v_fmac_f32_dpp v134, v92, v32 row_newbcast:10 row_mask:0xf bank_mask:0xf
	v_fmac_f32_dpp v135, v93, v33 row_newbcast:10 row_mask:0xf bank_mask:0xf
	v_fmac_f32_dpp v136, v94, v30 row_newbcast:10 row_mask:0xf bank_mask:0xf
	v_fmac_f32_dpp v137, v95, v31 row_newbcast:10 row_mask:0xf bank_mask:0xf
	v_fmac_f32_dpp v134, v92, v28 row_newbcast:11 row_mask:0xf bank_mask:0xf
	v_fmac_f32_dpp v135, v93, v29 row_newbcast:11 row_mask:0xf bank_mask:0xf
	v_fmac_f32_dpp v136, v94, v26 row_newbcast:11 row_mask:0xf bank_mask:0xf
	v_fmac_f32_dpp v137, v95, v27 row_newbcast:11 row_mask:0xf bank_mask:0xf
	v_fmac_f32_dpp v134, v92, v24 row_newbcast:12 row_mask:0xf bank_mask:0xf
	v_fmac_f32_dpp v135, v93, v25 row_newbcast:12 row_mask:0xf bank_mask:0xf
	v_fmac_f32_dpp v136, v94, v22 row_newbcast:12 row_mask:0xf bank_mask:0xf
	v_fmac_f32_dpp v137, v95, v23 row_newbcast:12 row_mask:0xf bank_mask:0xf
	v_fmac_f32_dpp v134, v92, v20 row_newbcast:13 row_mask:0xf bank_mask:0xf
	v_fmac_f32_dpp v135, v93, v21 row_newbcast:13 row_mask:0xf bank_mask:0xf
	v_fmac_f32_dpp v136, v94, v18 row_newbcast:13 row_mask:0xf bank_mask:0xf
	v_fmac_f32_dpp v137, v95, v19 row_newbcast:13 row_mask:0xf bank_mask:0xf
	v_fmac_f32_dpp v134, v92, v16 row_newbcast:14 row_mask:0xf bank_mask:0xf
	v_fmac_f32_dpp v135, v93, v17 row_newbcast:14 row_mask:0xf bank_mask:0xf
	v_fmac_f32_dpp v136, v94, v14 row_newbcast:14 row_mask:0xf bank_mask:0xf
	v_fmac_f32_dpp v137, v95, v15 row_newbcast:14 row_mask:0xf bank_mask:0xf
	v_fmac_f32_dpp v134, v92, v12 row_newbcast:15 row_mask:0xf bank_mask:0xf
	v_fmac_f32_dpp v135, v93, v13 row_newbcast:15 row_mask:0xf bank_mask:0xf
; template <bool SK>
; __device__ __forceinline__ void scan_task(const float* R, const float* W, const float* KX, const float* KK, const float* KKA, const float* V, float* OUT, float* STT, const float* S0, float* SOUT, int nstep, int lane) {
;     ...
;         for (int k = 0; k < 64; k += 2) { d0 = fmaf(s[k], kk[k], d0); d1 = fmaf(s[k + 1], kk[k + 1], d1); }
;         const float nd = -(d0 + d1);
;         const float vt = SK ? V[(size_t)t * BW + lane] : 0.f;
;         float o0 = 0.f, o1 = 0.f;
; #pragma unroll
;         for (int k = 0; k < 64; k += 2) {
;             float x = s[k] * w[k]; x = fmaf(nd, kka[k], x); if (SK) x = fmaf(vt, kx[k], x); s[k] = x; o0 = fmaf(x, r[k], o0);
;             float y = s[k + 1] * w[k + 1]; y = fmaf(nd, kka[k + 1], y); if (SK) y = fmaf(vt, kx[k + 1], y); s[k + 1] = y; o1 = fmaf(y, r[k + 1], o1);
;         }
;         OUT[(size_t)t * BW + lane] = o0 + o1;
	v_fmac_f32_dpp v136, v94, v82 row_newbcast:15 row_mask:0xf bank_mask:0xf
	v_fmac_f32_dpp v137, v95, v83 row_newbcast:15 row_mask:0xf bank_mask:0xf
	global_load_dwordx4 v[92:95], v143, s[96:97]
	v_add_f32_e32 v134, v134, v136
	v_add_f32_e32 v135, v135, v137
	v_add_f32_e32 v142, v134, v135
	v_xor_b32_e32 v142, 0x80000000, v142
	v_mul_f32_dpp v80, v96, v80 row_newbcast:0 row_mask:0xf bank_mask:0xf
	v_mul_f32_dpp v81, v97, v81 row_newbcast:0 row_mask:0xf bank_mask:0xf
	v_mul_f32_dpp v78, v98, v78 row_newbcast:0 row_mask:0xf bank_mask:0xf
	v_mul_f32_dpp v79, v99, v79 row_newbcast:0 row_mask:0xf bank_mask:0xf
	v_fmac_f32_dpp v80, v100, v142 row_newbcast:0 row_mask:0xf bank_mask:0xf
	v_fmac_f32_dpp v81, v101, v142 row_newbcast:0 row_mask:0xf bank_mask:0xf
	v_fmac_f32_dpp v78, v102, v142 row_newbcast:0 row_mask:0xf bank_mask:0xf
	v_fmac_f32_dpp v79, v103, v142 row_newbcast:0 row_mask:0xf bank_mask:0xf
	v_fmac_f32_dpp v80, v104, v132 row_newbcast:0 row_mask:0xf bank_mask:0xf
	v_fmac_f32_dpp v81, v105, v132 row_newbcast:0 row_mask:0xf bank_mask:0xf
	v_fmac_f32_dpp v78, v106, v132 row_newbcast:0 row_mask:0xf bank_mask:0xf
	v_fmac_f32_dpp v79, v107, v132 row_newbcast:0 row_mask:0xf bank_mask:0xf
	v_mul_f32_dpp v138, v108, v80 row_newbcast:0 row_mask:0xf bank_mask:0xf
	v_mul_f32_dpp v139, v109, v81 row_newbcast:0 row_mask:0xf bank_mask:0xf
	v_mul_f32_dpp v140, v110, v78 row_newbcast:0 row_mask:0xf bank_mask:0xf
	v_mul_f32_dpp v141, v111, v79 row_newbcast:0 row_mask:0xf bank_mask:0xf
	v_mul_f32_dpp v76, v96, v76 row_newbcast:1 row_mask:0xf bank_mask:0xf
	v_mul_f32_dpp v77, v97, v77 row_newbcast:1 row_mask:0xf bank_mask:0xf
	v_mul_f32_dpp v74, v98, v74 row_newbcast:1 row_mask:0xf bank_mask:0xf
	v_mul_f32_dpp v75, v99, v75 row_newbcast:1 row_mask:0xf bank_mask:0xf
	v_fmac_f32_dpp v76, v100, v142 row_newbcast:1 row_mask:0xf bank_mask:0xf
	v_fmac_f32_dpp v77, v101, v142 row_newbcast:1 row_mask:0xf bank_mask:0xf
	v_fmac_f32_dpp v74, v102, v142 row_newbcast:1 row_mask:0xf bank_mask:0xf
	v_fmac_f32_dpp v75, v103, v142 row_newbcast:1 row_mask:0xf bank_mask:0xf
	v_fmac_f32_dpp v76, v104, v132 row_newbcast:1 row_mask:0xf bank_mask:0xf
	v_fmac_f32_dpp v77, v105, v132 row_newbcast:1 row_mask:0xf bank_mask:0xf
	v_fmac_f32_dpp v74, v106, v132 row_newbcast:1 row_mask:0xf bank_mask:0xf
	v_fmac_f32_dpp v75, v107, v132 row_newbcast:1 row_mask:0xf bank_mask:0xf
	v_fmac_f32_dpp v138, v108, v76 row_newbcast:1 row_mask:0xf bank_mask:0xf
	v_fmac_f32_dpp v139, v109, v77 row_newbcast:1 row_mask:0xf bank_mask:0xf
	v_fmac_f32_dpp v140, v110, v74 row_newbcast:1 row_mask:0xf bank_mask:0xf
	v_fmac_f32_dpp v141, v111, v75 row_newbcast:1 row_mask:0xf bank_mask:0xf
	v_mul_f32_dpp v72, v96, v72 row_newbcast:2 row_mask:0xf bank_mask:0xf
	v_mul_f32_dpp v73, v97, v73 row_newbcast:2 row_mask:0xf bank_mask:0xf
	v_mul_f32_dpp v66, v98, v66 row_newbcast:2 row_mask:0xf bank_mask:0xf
	v_mul_f32_dpp v67, v99, v67 row_newbcast:2 row_mask:0xf bank_mask:0xf
	v_fmac_f32_dpp v72, v100, v142 row_newbcast:2 row_mask:0xf bank_mask:0xf
	v_fmac_f32_dpp v73, v101, v142 row_newbcast:2 row_mask:0xf bank_mask:0xf
	v_fmac_f32_dpp v66, v102, v142 row_newbcast:2 row_mask:0xf bank_mask:0xf
	v_fmac_f32_dpp v67, v103, v142 row_newbcast:2 row_mask:0xf bank_mask:0xf
	v_fmac_f32_dpp v72, v104, v132 row_newbcast:2 row_mask:0xf bank_mask:0xf
	v_fmac_f32_dpp v73, v105, v132 row_newbcast:2 row_mask:0xf bank_mask:0xf
	v_fmac_f32_dpp v66, v106, v132 row_newbcast:2 row_mask:0xf bank_mask:0xf
	v_fmac_f32_dpp v67, v107, v132 row_newbcast:2 row_mask:0xf bank_mask:0xf
	v_fmac_f32_dpp v138, v108, v72 row_newbcast:2 row_mask:0xf bank_mask:0xf
	v_fmac_f32_dpp v139, v109, v73 row_newbcast:2 row_mask:0xf bank_mask:0xf
	v_fmac_f32_dpp v140, v110, v66 row_newbcast:2 row_mask:0xf bank_mask:0xf
	v_fmac_f32_dpp v141, v111, v67 row_newbcast:2 row_mask:0xf bank_mask:0xf
	v_mul_f32_dpp v64, v96, v64 row_newbcast:3 row_mask:0xf bank_mask:0xf
	v_mul_f32_dpp v65, v97, v65 row_newbcast:3 row_mask:0xf bank_mask:0xf
	v_mul_f32_dpp v62, v98, v62 row_newbcast:3 row_mask:0xf bank_mask:0xf
	v_mul_f32_dpp v63, v99, v63 row_newbcast:3 row_mask:0xf bank_mask:0xf
	v_fmac_f32_dpp v64, v100, v142 row_newbcast:3 row_mask:0xf bank_mask:0xf
	v_fmac_f32_dpp v65, v101, v142 row_newbcast:3 row_mask:0xf bank_mask:0xf
	v_fmac_f32_dpp v62, v102, v142 row_newbcast:3 row_mask:0xf bank_mask:0xf
	v_fmac_f32_dpp v63, v103, v142 row_newbcast:3 row_mask:0xf bank_mask:0xf
	v_fmac_f32_dpp v64, v104, v132 row_newbcast:3 row_mask:0xf bank_mask:0xf
	v_fmac_f32_dpp v65, v105, v132 row_newbcast:3 row_mask:0xf bank_mask:0xf
	v_fmac_f32_dpp v62, v106, v132 row_newbcast:3 row_mask:0xf bank_mask:0xf
	v_fmac_f32_dpp v63, v107, v132 row_newbcast:3 row_mask:0xf bank_mask:0xf
	v_fmac_f32_dpp v138, v108, v64 row_newbcast:3 row_mask:0xf bank_mask:0xf
	v_fmac_f32_dpp v139, v109, v65 row_newbcast:3 row_mask:0xf bank_mask:0xf
	v_fmac_f32_dpp v140, v110, v62 row_newbcast:3 row_mask:0xf bank_mask:0xf
	v_fmac_f32_dpp v141, v111, v63 row_newbcast:3 row_mask:0xf bank_mask:0xf
	v_mul_f32_dpp v60, v96, v60 row_newbcast:4 row_mask:0xf bank_mask:0xf
	v_mul_f32_dpp v61, v97, v61 row_newbcast:4 row_mask:0xf bank_mask:0xf
	v_mul_f32_dpp v58, v98, v58 row_newbcast:4 row_mask:0xf bank_mask:0xf
	v_mul_f32_dpp v59, v99, v59 row_newbcast:4 row_mask:0xf bank_mask:0xf
	v_fmac_f32_dpp v60, v100, v142 row_newbcast:4 row_mask:0xf bank_mask:0xf
	v_fmac_f32_dpp v61, v101, v142 row_newbcast:4 row_mask:0xf bank_mask:0xf
	v_fmac_f32_dpp v58, v102, v142 row_newbcast:4 row_mask:0xf bank_mask:0xf
	v_fmac_f32_dpp v59, v103, v142 row_newbcast:4 row_mask:0xf bank_mask:0xf
	v_fmac_f32_dpp v60, v104, v132 row_newbcast:4 row_mask:0xf bank_mask:0xf
; template <bool SK>
; __device__ __forceinline__ void scan_task(const float* R, const float* W, const float* KX, const float* KK, const float* KKA, const float* V, float* OUT, float* STT, const float* S0, float* SOUT, int nstep, int lane) {
;     ...
;         for (int k = 0; k < 64; k += 2) { d0 = fmaf(s[k], kk[k], d0); d1 = fmaf(s[k + 1], kk[k + 1], d1); }
;         const float nd = -(d0 + d1);
;         const float vt = SK ? V[(size_t)t * BW + lane] : 0.f;
;         float o0 = 0.f, o1 = 0.f;
; #pragma unroll
;         for (int k = 0; k < 64; k += 2) {
;             float x = s[k] * w[k]; x = fmaf(nd, kka[k], x); if (SK) x = fmaf(vt, kx[k], x); s[k] = x; o0 = fmaf(x, r[k], o0);
;             float y = s[k + 1] * w[k + 1]; y = fmaf(nd, kka[k + 1], y); if (SK) y = fmaf(vt, kx[k + 1], y); s[k + 1] = y; o1 = fmaf(y, r[k + 1], o1);
;         }
;         OUT[(size_t)t * BW + lane] = o0 + o1;
	v_fmac_f32_dpp v61, v105, v132 row_newbcast:4 row_mask:0xf bank_mask:0xf
	v_fmac_f32_dpp v58, v106, v132 row_newbcast:4 row_mask:0xf bank_mask:0xf
	v_fmac_f32_dpp v59, v107, v132 row_newbcast:4 row_mask:0xf bank_mask:0xf
	v_fmac_f32_dpp v138, v108, v60 row_newbcast:4 row_mask:0xf bank_mask:0xf
	v_fmac_f32_dpp v139, v109, v61 row_newbcast:4 row_mask:0xf bank_mask:0xf
	v_fmac_f32_dpp v140, v110, v58 row_newbcast:4 row_mask:0xf bank_mask:0xf
	v_fmac_f32_dpp v141, v111, v59 row_newbcast:4 row_mask:0xf bank_mask:0xf
	v_mul_f32_dpp v56, v96, v56 row_newbcast:5 row_mask:0xf bank_mask:0xf
	v_mul_f32_dpp v57, v97, v57 row_newbcast:5 row_mask:0xf bank_mask:0xf
	v_mul_f32_dpp v54, v98, v54 row_newbcast:5 row_mask:0xf bank_mask:0xf
	v_mul_f32_dpp v55, v99, v55 row_newbcast:5 row_mask:0xf bank_mask:0xf
	v_fmac_f32_dpp v56, v100, v142 row_newbcast:5 row_mask:0xf bank_mask:0xf
	v_fmac_f32_dpp v57, v101, v142 row_newbcast:5 row_mask:0xf bank_mask:0xf
	v_fmac_f32_dpp v54, v102, v142 row_newbcast:5 row_mask:0xf bank_mask:0xf
	v_fmac_f32_dpp v55, v103, v142 row_newbcast:5 row_mask:0xf bank_mask:0xf
	v_fmac_f32_dpp v56, v104, v132 row_newbcast:5 row_mask:0xf bank_mask:0xf
	v_fmac_f32_dpp v57, v105, v132 row_newbcast:5 row_mask:0xf bank_mask:0xf
	v_fmac_f32_dpp v54, v106, v132 row_newbcast:5 row_mask:0xf bank_mask:0xf
	v_fmac_f32_dpp v55, v107, v132 row_newbcast:5 row_mask:0xf bank_mask:0xf
	v_fmac_f32_dpp v138, v108, v56 row_newbcast:5 row_mask:0xf bank_mask:0xf
	v_fmac_f32_dpp v139, v109, v57 row_newbcast:5 row_mask:0xf bank_mask:0xf
	v_fmac_f32_dpp v140, v110, v54 row_newbcast:5 row_mask:0xf bank_mask:0xf
	v_fmac_f32_dpp v141, v111, v55 row_newbcast:5 row_mask:0xf bank_mask:0xf
	v_mul_f32_dpp v50, v96, v50 row_newbcast:6 row_mask:0xf bank_mask:0xf
	v_mul_f32_dpp v51, v97, v51 row_newbcast:6 row_mask:0xf bank_mask:0xf
	v_mul_f32_dpp v48, v98, v48 row_newbcast:6 row_mask:0xf bank_mask:0xf
	v_mul_f32_dpp v49, v99, v49 row_newbcast:6 row_mask:0xf bank_mask:0xf
	v_fmac_f32_dpp v50, v100, v142 row_newbcast:6 row_mask:0xf bank_mask:0xf
	v_fmac_f32_dpp v51, v101, v142 row_newbcast:6 row_mask:0xf bank_mask:0xf
	v_fmac_f32_dpp v48, v102, v142 row_newbcast:6 row_mask:0xf bank_mask:0xf
	v_fmac_f32_dpp v49, v103, v142 row_newbcast:6 row_mask:0xf bank_mask:0xf
	v_fmac_f32_dpp v50, v104, v132 row_newbcast:6 row_mask:0xf bank_mask:0xf
	v_fmac_f32_dpp v51, v105, v132 row_newbcast:6 row_mask:0xf bank_mask:0xf
	v_fmac_f32_dpp v48, v106, v132 row_newbcast:6 row_mask:0xf bank_mask:0xf
	v_fmac_f32_dpp v49, v107, v132 row_newbcast:6 row_mask:0xf bank_mask:0xf
	v_fmac_f32_dpp v138, v108, v50 row_newbcast:6 row_mask:0xf bank_mask:0xf
	v_fmac_f32_dpp v139, v109, v51 row_newbcast:6 row_mask:0xf bank_mask:0xf
	v_fmac_f32_dpp v140, v110, v48 row_newbcast:6 row_mask:0xf bank_mask:0xf
	v_fmac_f32_dpp v141, v111, v49 row_newbcast:6 row_mask:0xf bank_mask:0xf
	v_mul_f32_dpp v46, v96, v46 row_newbcast:7 row_mask:0xf bank_mask:0xf
	v_mul_f32_dpp v47, v97, v47 row_newbcast:7 row_mask:0xf bank_mask:0xf
	v_mul_f32_dpp v44, v98, v44 row_newbcast:7 row_mask:0xf bank_mask:0xf
	v_mul_f32_dpp v45, v99, v45 row_newbcast:7 row_mask:0xf bank_mask:0xf
	v_fmac_f32_dpp v46, v100, v142 row_newbcast:7 row_mask:0xf bank_mask:0xf
	v_fmac_f32_dpp v47, v101, v142 row_newbcast:7 row_mask:0xf bank_mask:0xf
	v_fmac_f32_dpp v44, v102, v142 row_newbcast:7 row_mask:0xf bank_mask:0xf
	v_fmac_f32_dpp v45, v103, v142 row_newbcast:7 row_mask:0xf bank_mask:0xf
	v_fmac_f32_dpp v46, v104, v132 row_newbcast:7 row_mask:0xf bank_mask:0xf
	v_fmac_f32_dpp v47, v105, v132 row_newbcast:7 row_mask:0xf bank_mask:0xf
	v_fmac_f32_dpp v44, v106, v132 row_newbcast:7 row_mask:0xf bank_mask:0xf
	v_fmac_f32_dpp v45, v107, v132 row_newbcast:7 row_mask:0xf bank_mask:0xf
	v_fmac_f32_dpp v138, v108, v46 row_newbcast:7 row_mask:0xf bank_mask:0xf
	v_fmac_f32_dpp v139, v109, v47 row_newbcast:7 row_mask:0xf bank_mask:0xf
	v_fmac_f32_dpp v140, v110, v44 row_newbcast:7 row_mask:0xf bank_mask:0xf
	v_fmac_f32_dpp v141, v111, v45 row_newbcast:7 row_mask:0xf bank_mask:0xf
	v_mul_f32_dpp v42, v96, v42 row_newbcast:8 row_mask:0xf bank_mask:0xf
	v_mul_f32_dpp v43, v97, v43 row_newbcast:8 row_mask:0xf bank_mask:0xf
	v_mul_f32_dpp v40, v98, v40 row_newbcast:8 row_mask:0xf bank_mask:0xf
	v_mul_f32_dpp v41, v99, v41 row_newbcast:8 row_mask:0xf bank_mask:0xf
	v_fmac_f32_dpp v42, v100, v142 row_newbcast:8 row_mask:0xf bank_mask:0xf
	v_fmac_f32_dpp v43, v101, v142 row_newbcast:8 row_mask:0xf bank_mask:0xf
	v_fmac_f32_dpp v40, v102, v142 row_newbcast:8 row_mask:0xf bank_mask:0xf
	v_fmac_f32_dpp v41, v103, v142 row_newbcast:8 row_mask:0xf bank_mask:0xf
	v_fmac_f32_dpp v42, v104, v132 row_newbcast:8 row_mask:0xf bank_mask:0xf
	v_fmac_f32_dpp v43, v105, v132 row_newbcast:8 row_mask:0xf bank_mask:0xf
	v_fmac_f32_dpp v40, v106, v132 row_newbcast:8 row_mask:0xf bank_mask:0xf
	v_fmac_f32_dpp v41, v107, v132 row_newbcast:8 row_mask:0xf bank_mask:0xf
	v_fmac_f32_dpp v138, v108, v42 row_newbcast:8 row_mask:0xf bank_mask:0xf
	v_fmac_f32_dpp v139, v109, v43 row_newbcast:8 row_mask:0xf bank_mask:0xf
	v_fmac_f32_dpp v140, v110, v40 row_newbcast:8 row_mask:0xf bank_mask:0xf
	v_fmac_f32_dpp v141, v111, v41 row_newbcast:8 row_mask:0xf bank_mask:0xf
	v_mul_f32_dpp v38, v96, v38 row_newbcast:9 row_mask:0xf bank_mask:0xf
	v_mul_f32_dpp v39, v97, v39 row_newbcast:9 row_mask:0xf bank_mask:0xf
	v_mul_f32_dpp v36, v98, v36 row_newbcast:9 row_mask:0xf bank_mask:0xf
	v_mul_f32_dpp v37, v99, v37 row_newbcast:9 row_mask:0xf bank_mask:0xf
	v_fmac_f32_dpp v38, v100, v142 row_newbcast:9 row_mask:0xf bank_mask:0xf
	v_fmac_f32_dpp v39, v101, v142 row_newbcast:9 row_mask:0xf bank_mask:0xf
; template <bool SK>
; __device__ __forceinline__ void scan_task(const float* R, const float* W, const float* KX, const float* KK, const float* KKA, const float* V, float* OUT, float* STT, const float* S0, float* SOUT, int nstep, int lane) {
;     ...
;         for (int k = 0; k < 64; k += 2) { d0 = fmaf(s[k], kk[k], d0); d1 = fmaf(s[k + 1], kk[k + 1], d1); }
;         const float nd = -(d0 + d1);
;         const float vt = SK ? V[(size_t)t * BW + lane] : 0.f;
;         float o0 = 0.f, o1 = 0.f;
; #pragma unroll
;         for (int k = 0; k < 64; k += 2) {
;             float x = s[k] * w[k]; x = fmaf(nd, kka[k], x); if (SK) x = fmaf(vt, kx[k], x); s[k] = x; o0 = fmaf(x, r[k], o0);
;             float y = s[k + 1] * w[k + 1]; y = fmaf(nd, kka[k + 1], y); if (SK) y = fmaf(vt, kx[k + 1], y); s[k + 1] = y; o1 = fmaf(y, r[k + 1], o1);
;         }
;         OUT[(size_t)t * BW + lane] = o0 + o1;
	v_fmac_f32_dpp v36, v102, v142 row_newbcast:9 row_mask:0xf bank_mask:0xf
	v_fmac_f32_dpp v37, v103, v142 row_newbcast:9 row_mask:0xf bank_mask:0xf
	v_fmac_f32_dpp v38, v104, v132 row_newbcast:9 row_mask:0xf bank_mask:0xf
	v_fmac_f32_dpp v39, v105, v132 row_newbcast:9 row_mask:0xf bank_mask:0xf
	v_fmac_f32_dpp v36, v106, v132 row_newbcast:9 row_mask:0xf bank_mask:0xf
	v_fmac_f32_dpp v37, v107, v132 row_newbcast:9 row_mask:0xf bank_mask:0xf
	v_fmac_f32_dpp v138, v108, v38 row_newbcast:9 row_mask:0xf bank_mask:0xf
	v_fmac_f32_dpp v139, v109, v39 row_newbcast:9 row_mask:0xf bank_mask:0xf
	v_fmac_f32_dpp v140, v110, v36 row_newbcast:9 row_mask:0xf bank_mask:0xf
	v_fmac_f32_dpp v141, v111, v37 row_newbcast:9 row_mask:0xf bank_mask:0xf
	v_mul_f32_dpp v32, v96, v32 row_newbcast:10 row_mask:0xf bank_mask:0xf
	v_mul_f32_dpp v33, v97, v33 row_newbcast:10 row_mask:0xf bank_mask:0xf
	v_mul_f32_dpp v30, v98, v30 row_newbcast:10 row_mask:0xf bank_mask:0xf
	v_mul_f32_dpp v31, v99, v31 row_newbcast:10 row_mask:0xf bank_mask:0xf
	v_fmac_f32_dpp v32, v100, v142 row_newbcast:10 row_mask:0xf bank_mask:0xf
	v_fmac_f32_dpp v33, v101, v142 row_newbcast:10 row_mask:0xf bank_mask:0xf
	v_fmac_f32_dpp v30, v102, v142 row_newbcast:10 row_mask:0xf bank_mask:0xf
	v_fmac_f32_dpp v31, v103, v142 row_newbcast:10 row_mask:0xf bank_mask:0xf
	v_fmac_f32_dpp v32, v104, v132 row_newbcast:10 row_mask:0xf bank_mask:0xf
	v_fmac_f32_dpp v33, v105, v132 row_newbcast:10 row_mask:0xf bank_mask:0xf
	v_fmac_f32_dpp v30, v106, v132 row_newbcast:10 row_mask:0xf bank_mask:0xf
	v_fmac_f32_dpp v31, v107, v132 row_newbcast:10 row_mask:0xf bank_mask:0xf
	v_fmac_f32_dpp v138, v108, v32 row_newbcast:10 row_mask:0xf bank_mask:0xf
	v_fmac_f32_dpp v139, v109, v33 row_newbcast:10 row_mask:0xf bank_mask:0xf
	v_fmac_f32_dpp v140, v110, v30 row_newbcast:10 row_mask:0xf bank_mask:0xf
	v_fmac_f32_dpp v141, v111, v31 row_newbcast:10 row_mask:0xf bank_mask:0xf
	v_mul_f32_dpp v28, v96, v28 row_newbcast:11 row_mask:0xf bank_mask:0xf
	v_mul_f32_dpp v29, v97, v29 row_newbcast:11 row_mask:0xf bank_mask:0xf
	v_mul_f32_dpp v26, v98, v26 row_newbcast:11 row_mask:0xf bank_mask:0xf
	v_mul_f32_dpp v27, v99, v27 row_newbcast:11 row_mask:0xf bank_mask:0xf
	v_fmac_f32_dpp v28, v100, v142 row_newbcast:11 row_mask:0xf bank_mask:0xf
	v_fmac_f32_dpp v29, v101, v142 row_newbcast:11 row_mask:0xf bank_mask:0xf
	v_fmac_f32_dpp v26, v102, v142 row_newbcast:11 row_mask:0xf bank_mask:0xf
	v_fmac_f32_dpp v27, v103, v142 row_newbcast:11 row_mask:0xf bank_mask:0xf
	v_fmac_f32_dpp v28, v104, v132 row_newbcast:11 row_mask:0xf bank_mask:0xf
	v_fmac_f32_dpp v29, v105, v132 row_newbcast:11 row_mask:0xf bank_mask:0xf
	v_fmac_f32_dpp v26, v106, v132 row_newbcast:11 row_mask:0xf bank_mask:0xf
	v_fmac_f32_dpp v27, v107, v132 row_newbcast:11 row_mask:0xf bank_mask:0xf
	v_fmac_f32_dpp v138, v108, v28 row_newbcast:11 row_mask:0xf bank_mask:0xf
	v_fmac_f32_dpp v139, v109, v29 row_newbcast:11 row_mask:0xf bank_mask:0xf
	v_fmac_f32_dpp v140, v110, v26 row_newbcast:11 row_mask:0xf bank_mask:0xf
	v_fmac_f32_dpp v141, v111, v27 row_newbcast:11 row_mask:0xf bank_mask:0xf
	v_mul_f32_dpp v24, v96, v24 row_newbcast:12 row_mask:0xf bank_mask:0xf
	v_mul_f32_dpp v25, v97, v25 row_newbcast:12 row_mask:0xf bank_mask:0xf
	v_mul_f32_dpp v22, v98, v22 row_newbcast:12 row_mask:0xf bank_mask:0xf
	v_mul_f32_dpp v23, v99, v23 row_newbcast:12 row_mask:0xf bank_mask:0xf
	v_fmac_f32_dpp v24, v100, v142 row_newbcast:12 row_mask:0xf bank_mask:0xf
	v_fmac_f32_dpp v25, v101, v142 row_newbcast:12 row_mask:0xf bank_mask:0xf
	v_fmac_f32_dpp v22, v102, v142 row_newbcast:12 row_mask:0xf bank_mask:0xf
	v_fmac_f32_dpp v23, v103, v142 row_newbcast:12 row_mask:0xf bank_mask:0xf
	v_fmac_f32_dpp v24, v104, v132 row_newbcast:12 row_mask:0xf bank_mask:0xf
	v_fmac_f32_dpp v25, v105, v132 row_newbcast:12 row_mask:0xf bank_mask:0xf
	v_fmac_f32_dpp v22, v106, v132 row_newbcast:12 row_mask:0xf bank_mask:0xf
	v_fmac_f32_dpp v23, v107, v132 row_newbcast:12 row_mask:0xf bank_mask:0xf
	v_fmac_f32_dpp v138, v108, v24 row_newbcast:12 row_mask:0xf bank_mask:0xf
	v_fmac_f32_dpp v139, v109, v25 row_newbcast:12 row_mask:0xf bank_mask:0xf
	v_fmac_f32_dpp v140, v110, v22 row_newbcast:12 row_mask:0xf bank_mask:0xf
	v_fmac_f32_dpp v141, v111, v23 row_newbcast:12 row_mask:0xf bank_mask:0xf
	v_mul_f32_dpp v20, v96, v20 row_newbcast:13 row_mask:0xf bank_mask:0xf
	v_mul_f32_dpp v21, v97, v21 row_newbcast:13 row_mask:0xf bank_mask:0xf
	v_mul_f32_dpp v18, v98, v18 row_newbcast:13 row_mask:0xf bank_mask:0xf
	v_mul_f32_dpp v19, v99, v19 row_newbcast:13 row_mask:0xf bank_mask:0xf
	v_fmac_f32_dpp v20, v100, v142 row_newbcast:13 row_mask:0xf bank_mask:0xf
	v_fmac_f32_dpp v21, v101, v142 row_newbcast:13 row_mask:0xf bank_mask:0xf
	v_fmac_f32_dpp v18, v102, v142 row_newbcast:13 row_mask:0xf bank_mask:0xf
	v_fmac_f32_dpp v19, v103, v142 row_newbcast:13 row_mask:0xf bank_mask:0xf
	v_fmac_f32_dpp v20, v104, v132 row_newbcast:13 row_mask:0xf bank_mask:0xf
	v_fmac_f32_dpp v21, v105, v132 row_newbcast:13 row_mask:0xf bank_mask:0xf
	v_fmac_f32_dpp v18, v106, v132 row_newbcast:13 row_mask:0xf bank_mask:0xf
	v_fmac_f32_dpp v19, v107, v132 row_newbcast:13 row_mask:0xf bank_mask:0xf
	v_fmac_f32_dpp v138, v108, v20 row_newbcast:13 row_mask:0xf bank_mask:0xf
	v_fmac_f32_dpp v139, v109, v21 row_newbcast:13 row_mask:0xf bank_mask:0xf
	v_fmac_f32_dpp v140, v110, v18 row_newbcast:13 row_mask:0xf bank_mask:0xf
	v_fmac_f32_dpp v141, v111, v19 row_newbcast:13 row_mask:0xf bank_mask:0xf
	v_mul_f32_dpp v16, v96, v16 row_newbcast:14 row_mask:0xf bank_mask:0xf
	v_mul_f32_dpp v17, v97, v17 row_newbcast:14 row_mask:0xf bank_mask:0xf
; template <bool SK>
; __device__ __forceinline__ void scan_task(const float* R, const float* W, const float* KX, const float* KK, const float* KKA, const float* V, float* OUT, float* STT, const float* S0, float* SOUT, int nstep, int lane) {
;     ...
;         for (int k = 0; k < 64; k += 2) { d0 = fmaf(s[k], kk[k], d0); d1 = fmaf(s[k + 1], kk[k + 1], d1); }
;         const float nd = -(d0 + d1);
;         const float vt = SK ? V[(size_t)t * BW + lane] : 0.f;
;         float o0 = 0.f, o1 = 0.f;
; #pragma unroll
;         for (int k = 0; k < 64; k += 2) {
;             float x = s[k] * w[k]; x = fmaf(nd, kka[k], x); if (SK) x = fmaf(vt, kx[k], x); s[k] = x; o0 = fmaf(x, r[k], o0);
;             float y = s[k + 1] * w[k + 1]; y = fmaf(nd, kka[k + 1], y); if (SK) y = fmaf(vt, kx[k + 1], y); s[k + 1] = y; o1 = fmaf(y, r[k + 1], o1);
;         }
;         OUT[(size_t)t * BW + lane] = o0 + o1;
	v_mul_f32_dpp v14, v98, v14 row_newbcast:14 row_mask:0xf bank_mask:0xf
	v_mul_f32_dpp v15, v99, v15 row_newbcast:14 row_mask:0xf bank_mask:0xf
	v_fmac_f32_dpp v16, v100, v142 row_newbcast:14 row_mask:0xf bank_mask:0xf
	v_fmac_f32_dpp v17, v101, v142 row_newbcast:14 row_mask:0xf bank_mask:0xf
	v_fmac_f32_dpp v14, v102, v142 row_newbcast:14 row_mask:0xf bank_mask:0xf
	v_fmac_f32_dpp v15, v103, v142 row_newbcast:14 row_mask:0xf bank_mask:0xf
	v_fmac_f32_dpp v16, v104, v132 row_newbcast:14 row_mask:0xf bank_mask:0xf
	v_fmac_f32_dpp v17, v105, v132 row_newbcast:14 row_mask:0xf bank_mask:0xf
	v_fmac_f32_dpp v14, v106, v132 row_newbcast:14 row_mask:0xf bank_mask:0xf
	v_fmac_f32_dpp v15, v107, v132 row_newbcast:14 row_mask:0xf bank_mask:0xf
	v_fmac_f32_dpp v138, v108, v16 row_newbcast:14 row_mask:0xf bank_mask:0xf
	v_fmac_f32_dpp v139, v109, v17 row_newbcast:14 row_mask:0xf bank_mask:0xf
	v_fmac_f32_dpp v140, v110, v14 row_newbcast:14 row_mask:0xf bank_mask:0xf
	v_fmac_f32_dpp v141, v111, v15 row_newbcast:14 row_mask:0xf bank_mask:0xf
	v_mul_f32_dpp v12, v96, v12 row_newbcast:15 row_mask:0xf bank_mask:0xf
	v_mul_f32_dpp v13, v97, v13 row_newbcast:15 row_mask:0xf bank_mask:0xf
	v_mul_f32_dpp v82, v98, v82 row_newbcast:15 row_mask:0xf bank_mask:0xf
	v_mul_f32_dpp v83, v99, v83 row_newbcast:15 row_mask:0xf bank_mask:0xf
	v_fmac_f32_dpp v12, v100, v142 row_newbcast:15 row_mask:0xf bank_mask:0xf
	v_fmac_f32_dpp v13, v101, v142 row_newbcast:15 row_mask:0xf bank_mask:0xf
	v_fmac_f32_dpp v82, v102, v142 row_newbcast:15 row_mask:0xf bank_mask:0xf
	v_fmac_f32_dpp v83, v103, v142 row_newbcast:15 row_mask:0xf bank_mask:0xf
	v_fmac_f32_dpp v12, v104, v132 row_newbcast:15 row_mask:0xf bank_mask:0xf
	v_fmac_f32_dpp v13, v105, v132 row_newbcast:15 row_mask:0xf bank_mask:0xf
	v_fmac_f32_dpp v82, v106, v132 row_newbcast:15 row_mask:0xf bank_mask:0xf
	v_fmac_f32_dpp v83, v107, v132 row_newbcast:15 row_mask:0xf bank_mask:0xf
	v_fmac_f32_dpp v138, v108, v12 row_newbcast:15 row_mask:0xf bank_mask:0xf
	v_fmac_f32_dpp v139, v109, v13 row_newbcast:15 row_mask:0xf bank_mask:0xf
	v_fmac_f32_dpp v140, v110, v82 row_newbcast:15 row_mask:0xf bank_mask:0xf
	v_fmac_f32_dpp v141, v111, v83 row_newbcast:15 row_mask:0xf bank_mask:0xf
	global_load_dwordx4 v[96:99], v143, s[90:91]
	global_load_dwordx4 v[100:103], v143, s[94:95]
	global_load_dwordx4 v[104:107], v143, s[92:93]
	global_load_dwordx4 v[108:111], v143, s[88:89]
	global_load_dword v132, v144, s[4:5]
	v_add_f32_e32 v138, v138, v140
	v_add_f32_e32 v139, v139, v141
	v_add_f32_e32 v138, v138, v139
	global_store_dword v144, v138, s[6:7]
	s_waitcnt vmcnt(8)
	v_mul_f32_dpp v134, v112, v80 row_newbcast:0 row_mask:0xf bank_mask:0xf
	v_mul_f32_dpp v135, v113, v81 row_newbcast:0 row_mask:0xf bank_mask:0xf
	v_mul_f32_dpp v136, v114, v78 row_newbcast:0 row_mask:0xf bank_mask:0xf
	v_mul_f32_dpp v137, v115, v79 row_newbcast:0 row_mask:0xf bank_mask:0xf
	v_fmac_f32_dpp v134, v112, v76 row_newbcast:1 row_mask:0xf bank_mask:0xf
	v_fmac_f32_dpp v135, v113, v77 row_newbcast:1 row_mask:0xf bank_mask:0xf
	v_fmac_f32_dpp v136, v114, v74 row_newbcast:1 row_mask:0xf bank_mask:0xf
	v_fmac_f32_dpp v137, v115, v75 row_newbcast:1 row_mask:0xf bank_mask:0xf
	v_fmac_f32_dpp v134, v112, v72 row_newbcast:2 row_mask:0xf bank_mask:0xf
	v_fmac_f32_dpp v135, v113, v73 row_newbcast:2 row_mask:0xf bank_mask:0xf
	v_fmac_f32_dpp v136, v114, v66 row_newbcast:2 row_mask:0xf bank_mask:0xf
	v_fmac_f32_dpp v137, v115, v67 row_newbcast:2 row_mask:0xf bank_mask:0xf
	v_fmac_f32_dpp v134, v112, v64 row_newbcast:3 row_mask:0xf bank_mask:0xf
	v_fmac_f32_dpp v135, v113, v65 row_newbcast:3 row_mask:0xf bank_mask:0xf
	v_fmac_f32_dpp v136, v114, v62 row_newbcast:3 row_mask:0xf bank_mask:0xf
	v_fmac_f32_dpp v137, v115, v63 row_newbcast:3 row_mask:0xf bank_mask:0xf
	v_fmac_f32_dpp v134, v112, v60 row_newbcast:4 row_mask:0xf bank_mask:0xf
	v_fmac_f32_dpp v135, v113, v61 row_newbcast:4 row_mask:0xf bank_mask:0xf
	v_fmac_f32_dpp v136, v114, v58 row_newbcast:4 row_mask:0xf bank_mask:0xf
	v_fmac_f32_dpp v137, v115, v59 row_newbcast:4 row_mask:0xf bank_mask:0xf
	v_fmac_f32_dpp v134, v112, v56 row_newbcast:5 row_mask:0xf bank_mask:0xf
	v_fmac_f32_dpp v135, v113, v57 row_newbcast:5 row_mask:0xf bank_mask:0xf
	v_fmac_f32_dpp v136, v114, v54 row_newbcast:5 row_mask:0xf bank_mask:0xf
	v_fmac_f32_dpp v137, v115, v55 row_newbcast:5 row_mask:0xf bank_mask:0xf
	v_fmac_f32_dpp v134, v112, v50 row_newbcast:6 row_mask:0xf bank_mask:0xf
	v_fmac_f32_dpp v135, v113, v51 row_newbcast:6 row_mask:0xf bank_mask:0xf
	v_fmac_f32_dpp v136, v114, v48 row_newbcast:6 row_mask:0xf bank_mask:0xf
	v_fmac_f32_dpp v137, v115, v49 row_newbcast:6 row_mask:0xf bank_mask:0xf
	v_fmac_f32_dpp v134, v112, v46 row_newbcast:7 row_mask:0xf bank_mask:0xf
	v_fmac_f32_dpp v135, v113, v47 row_newbcast:7 row_mask:0xf bank_mask:0xf
	v_fmac_f32_dpp v136, v114, v44 row_newbcast:7 row_mask:0xf bank_mask:0xf
	v_fmac_f32_dpp v137, v115, v45 row_newbcast:7 row_mask:0xf bank_mask:0xf
	v_fmac_f32_dpp v134, v112, v42 row_newbcast:8 row_mask:0xf bank_mask:0xf
	v_fmac_f32_dpp v135, v113, v43 row_newbcast:8 row_mask:0xf bank_mask:0xf
	v_fmac_f32_dpp v136, v114, v40 row_newbcast:8 row_mask:0xf bank_mask:0xf
	v_fmac_f32_dpp v137, v115, v41 row_newbcast:8 row_mask:0xf bank_mask:0xf
	v_fmac_f32_dpp v134, v112, v38 row_newbcast:9 row_mask:0xf bank_mask:0xf
	v_fmac_f32_dpp v135, v113, v39 row_newbcast:9 row_mask:0xf bank_mask:0xf
	v_fmac_f32_dpp v136, v114, v36 row_newbcast:9 row_mask:0xf bank_mask:0xf
	v_fmac_f32_dpp v137, v115, v37 row_newbcast:9 row_mask:0xf bank_mask:0xf
	v_fmac_f32_dpp v134, v112, v32 row_newbcast:10 row_mask:0xf bank_mask:0xf
; template <bool SK>
; __device__ __forceinline__ void scan_task(const float* R, const float* W, const float* KX, const float* KK, const float* KKA, const float* V, float* OUT, float* STT, const float* S0, float* SOUT, int nstep, int lane) {
;     ...
;         for (int k = 0; k < 64; k += 2) { d0 = fmaf(s[k], kk[k], d0); d1 = fmaf(s[k + 1], kk[k + 1], d1); }
;         const float nd = -(d0 + d1);
;         const float vt = SK ? V[(size_t)t * BW + lane] : 0.f;
;         float o0 = 0.f, o1 = 0.f;
; #pragma unroll
;         for (int k = 0; k < 64; k += 2) {
;             float x = s[k] * w[k]; x = fmaf(nd, kka[k], x); if (SK) x = fmaf(vt, kx[k], x); s[k] = x; o0 = fmaf(x, r[k], o0);
;             float y = s[k + 1] * w[k + 1]; y = fmaf(nd, kka[k + 1], y); if (SK) y = fmaf(vt, kx[k + 1], y); s[k + 1] = y; o1 = fmaf(y, r[k + 1], o1);
;         }
;         OUT[(size_t)t * BW + lane] = o0 + o1;
	v_fmac_f32_dpp v135, v113, v33 row_newbcast:10 row_mask:0xf bank_mask:0xf
	v_fmac_f32_dpp v136, v114, v30 row_newbcast:10 row_mask:0xf bank_mask:0xf
	v_fmac_f32_dpp v137, v115, v31 row_newbcast:10 row_mask:0xf bank_mask:0xf
	v_fmac_f32_dpp v134, v112, v28 row_newbcast:11 row_mask:0xf bank_mask:0xf
	v_fmac_f32_dpp v135, v113, v29 row_newbcast:11 row_mask:0xf bank_mask:0xf
	v_fmac_f32_dpp v136, v114, v26 row_newbcast:11 row_mask:0xf bank_mask:0xf
	v_fmac_f32_dpp v137, v115, v27 row_newbcast:11 row_mask:0xf bank_mask:0xf
	v_fmac_f32_dpp v134, v112, v24 row_newbcast:12 row_mask:0xf bank_mask:0xf
	v_fmac_f32_dpp v135, v113, v25 row_newbcast:12 row_mask:0xf bank_mask:0xf
	v_fmac_f32_dpp v136, v114, v22 row_newbcast:12 row_mask:0xf bank_mask:0xf
	v_fmac_f32_dpp v137, v115, v23 row_newbcast:12 row_mask:0xf bank_mask:0xf
	v_fmac_f32_dpp v134, v112, v20 row_newbcast:13 row_mask:0xf bank_mask:0xf
	v_fmac_f32_dpp v135, v113, v21 row_newbcast:13 row_mask:0xf bank_mask:0xf
	v_fmac_f32_dpp v136, v114, v18 row_newbcast:13 row_mask:0xf bank_mask:0xf
	v_fmac_f32_dpp v137, v115, v19 row_newbcast:13 row_mask:0xf bank_mask:0xf
	v_fmac_f32_dpp v134, v112, v16 row_newbcast:14 row_mask:0xf bank_mask:0xf
	v_fmac_f32_dpp v135, v113, v17 row_newbcast:14 row_mask:0xf bank_mask:0xf
	v_fmac_f32_dpp v136, v114, v14 row_newbcast:14 row_mask:0xf bank_mask:0xf
	v_fmac_f32_dpp v137, v115, v15 row_newbcast:14 row_mask:0xf bank_mask:0xf
	v_fmac_f32_dpp v134, v112, v12 row_newbcast:15 row_mask:0xf bank_mask:0xf
	v_fmac_f32_dpp v135, v113, v13 row_newbcast:15 row_mask:0xf bank_mask:0xf
	v_fmac_f32_dpp v136, v114, v82 row_newbcast:15 row_mask:0xf bank_mask:0xf
	v_fmac_f32_dpp v137, v115, v83 row_newbcast:15 row_mask:0xf bank_mask:0xf
	global_load_dwordx4 v[112:115], v143, s[96:97] offset:2048
	v_add_f32_e32 v134, v134, v136
	v_add_f32_e32 v135, v135, v137
	v_add_f32_e32 v142, v134, v135
	v_xor_b32_e32 v142, 0x80000000, v142
	v_mul_f32_dpp v80, v116, v80 row_newbcast:0 row_mask:0xf bank_mask:0xf
	v_mul_f32_dpp v81, v117, v81 row_newbcast:0 row_mask:0xf bank_mask:0xf
	v_mul_f32_dpp v78, v118, v78 row_newbcast:0 row_mask:0xf bank_mask:0xf
	v_mul_f32_dpp v79, v119, v79 row_newbcast:0 row_mask:0xf bank_mask:0xf
	v_fmac_f32_dpp v80, v120, v142 row_newbcast:0 row_mask:0xf bank_mask:0xf
	v_fmac_f32_dpp v81, v121, v142 row_newbcast:0 row_mask:0xf bank_mask:0xf
	v_fmac_f32_dpp v78, v122, v142 row_newbcast:0 row_mask:0xf bank_mask:0xf
	v_fmac_f32_dpp v79, v123, v142 row_newbcast:0 row_mask:0xf bank_mask:0xf
	v_fmac_f32_dpp v80, v124, v133 row_newbcast:0 row_mask:0xf bank_mask:0xf
	v_fmac_f32_dpp v81, v125, v133 row_newbcast:0 row_mask:0xf bank_mask:0xf
	v_fmac_f32_dpp v78, v126, v133 row_newbcast:0 row_mask:0xf bank_mask:0xf
	v_fmac_f32_dpp v79, v127, v133 row_newbcast:0 row_mask:0xf bank_mask:0xf
	v_mul_f32_dpp v138, v128, v80 row_newbcast:0 row_mask:0xf bank_mask:0xf
	v_mul_f32_dpp v139, v129, v81 row_newbcast:0 row_mask:0xf bank_mask:0xf
	v_mul_f32_dpp v140, v130, v78 row_newbcast:0 row_mask:0xf bank_mask:0xf
	v_mul_f32_dpp v141, v131, v79 row_newbcast:0 row_mask:0xf bank_mask:0xf
	v_mul_f32_dpp v76, v116, v76 row_newbcast:1 row_mask:0xf bank_mask:0xf
	v_mul_f32_dpp v77, v117, v77 row_newbcast:1 row_mask:0xf bank_mask:0xf
	v_mul_f32_dpp v74, v118, v74 row_newbcast:1 row_mask:0xf bank_mask:0xf
	v_mul_f32_dpp v75, v119, v75 row_newbcast:1 row_mask:0xf bank_mask:0xf
	v_fmac_f32_dpp v76, v120, v142 row_newbcast:1 row_mask:0xf bank_mask:0xf
	v_fmac_f32_dpp v77, v121, v142 row_newbcast:1 row_mask:0xf bank_mask:0xf
	v_fmac_f32_dpp v74, v122, v142 row_newbcast:1 row_mask:0xf bank_mask:0xf
	v_fmac_f32_dpp v75, v123, v142 row_newbcast:1 row_mask:0xf bank_mask:0xf
	v_fmac_f32_dpp v76, v124, v133 row_newbcast:1 row_mask:0xf bank_mask:0xf
	v_fmac_f32_dpp v77, v125, v133 row_newbcast:1 row_mask:0xf bank_mask:0xf
	v_fmac_f32_dpp v74, v126, v133 row_newbcast:1 row_mask:0xf bank_mask:0xf
	v_fmac_f32_dpp v75, v127, v133 row_newbcast:1 row_mask:0xf bank_mask:0xf
	v_fmac_f32_dpp v138, v128, v76 row_newbcast:1 row_mask:0xf bank_mask:0xf
	v_fmac_f32_dpp v139, v129, v77 row_newbcast:1 row_mask:0xf bank_mask:0xf
	v_fmac_f32_dpp v140, v130, v74 row_newbcast:1 row_mask:0xf bank_mask:0xf
	v_fmac_f32_dpp v141, v131, v75 row_newbcast:1 row_mask:0xf bank_mask:0xf
	v_mul_f32_dpp v72, v116, v72 row_newbcast:2 row_mask:0xf bank_mask:0xf
	v_mul_f32_dpp v73, v117, v73 row_newbcast:2 row_mask:0xf bank_mask:0xf
	v_mul_f32_dpp v66, v118, v66 row_newbcast:2 row_mask:0xf bank_mask:0xf
	v_mul_f32_dpp v67, v119, v67 row_newbcast:2 row_mask:0xf bank_mask:0xf
	v_fmac_f32_dpp v72, v120, v142 row_newbcast:2 row_mask:0xf bank_mask:0xf
	v_fmac_f32_dpp v73, v121, v142 row_newbcast:2 row_mask:0xf bank_mask:0xf
	v_fmac_f32_dpp v66, v122, v142 row_newbcast:2 row_mask:0xf bank_mask:0xf
	v_fmac_f32_dpp v67, v123, v142 row_newbcast:2 row_mask:0xf bank_mask:0xf
	v_fmac_f32_dpp v72, v124, v133 row_newbcast:2 row_mask:0xf bank_mask:0xf
	v_fmac_f32_dpp v73, v125, v133 row_newbcast:2 row_mask:0xf bank_mask:0xf
	v_fmac_f32_dpp v66, v126, v133 row_newbcast:2 row_mask:0xf bank_mask:0xf
	v_fmac_f32_dpp v67, v127, v133 row_newbcast:2 row_mask:0xf bank_mask:0xf
	v_fmac_f32_dpp v138, v128, v72 row_newbcast:2 row_mask:0xf bank_mask:0xf
	v_fmac_f32_dpp v139, v129, v73 row_newbcast:2 row_mask:0xf bank_mask:0xf
	v_fmac_f32_dpp v140, v130, v66 row_newbcast:2 row_mask:0xf bank_mask:0xf
	v_fmac_f32_dpp v141, v131, v67 row_newbcast:2 row_mask:0xf bank_mask:0xf
	v_mul_f32_dpp v64, v116, v64 row_newbcast:3 row_mask:0xf bank_mask:0xf
	v_mul_f32_dpp v65, v117, v65 row_newbcast:3 row_mask:0xf bank_mask:0xf
	v_mul_f32_dpp v62, v118, v62 row_newbcast:3 row_mask:0xf bank_mask:0xf
; template <bool SK>
; __device__ __forceinline__ void scan_task(const float* R, const float* W, const float* KX, const float* KK, const float* KKA, const float* V, float* OUT, float* STT, const float* S0, float* SOUT, int nstep, int lane) {
;     ...
;         for (int k = 0; k < 64; k += 2) { d0 = fmaf(s[k], kk[k], d0); d1 = fmaf(s[k + 1], kk[k + 1], d1); }
;         const float nd = -(d0 + d1);
;         const float vt = SK ? V[(size_t)t * BW + lane] : 0.f;
;         float o0 = 0.f, o1 = 0.f;
; #pragma unroll
;         for (int k = 0; k < 64; k += 2) {
;             float x = s[k] * w[k]; x = fmaf(nd, kka[k], x); if (SK) x = fmaf(vt, kx[k], x); s[k] = x; o0 = fmaf(x, r[k], o0);
;             float y = s[k + 1] * w[k + 1]; y = fmaf(nd, kka[k + 1], y); if (SK) y = fmaf(vt, kx[k + 1], y); s[k + 1] = y; o1 = fmaf(y, r[k + 1], o1);
;         }
;         OUT[(size_t)t * BW + lane] = o0 + o1;
	v_mul_f32_dpp v63, v119, v63 row_newbcast:3 row_mask:0xf bank_mask:0xf
	v_fmac_f32_dpp v64, v120, v142 row_newbcast:3 row_mask:0xf bank_mask:0xf
	v_fmac_f32_dpp v65, v121, v142 row_newbcast:3 row_mask:0xf bank_mask:0xf
	v_fmac_f32_dpp v62, v122, v142 row_newbcast:3 row_mask:0xf bank_mask:0xf
	v_fmac_f32_dpp v63, v123, v142 row_newbcast:3 row_mask:0xf bank_mask:0xf
	v_fmac_f32_dpp v64, v124, v133 row_newbcast:3 row_mask:0xf bank_mask:0xf
	v_fmac_f32_dpp v65, v125, v133 row_newbcast:3 row_mask:0xf bank_mask:0xf
	v_fmac_f32_dpp v62, v126, v133 row_newbcast:3 row_mask:0xf bank_mask:0xf
	v_fmac_f32_dpp v63, v127, v133 row_newbcast:3 row_mask:0xf bank_mask:0xf
	v_fmac_f32_dpp v138, v128, v64 row_newbcast:3 row_mask:0xf bank_mask:0xf
	v_fmac_f32_dpp v139, v129, v65 row_newbcast:3 row_mask:0xf bank_mask:0xf
	v_fmac_f32_dpp v140, v130, v62 row_newbcast:3 row_mask:0xf bank_mask:0xf
	v_fmac_f32_dpp v141, v131, v63 row_newbcast:3 row_mask:0xf bank_mask:0xf
	v_mul_f32_dpp v60, v116, v60 row_newbcast:4 row_mask:0xf bank_mask:0xf
	v_mul_f32_dpp v61, v117, v61 row_newbcast:4 row_mask:0xf bank_mask:0xf
	v_mul_f32_dpp v58, v118, v58 row_newbcast:4 row_mask:0xf bank_mask:0xf
	v_mul_f32_dpp v59, v119, v59 row_newbcast:4 row_mask:0xf bank_mask:0xf
	v_fmac_f32_dpp v60, v120, v142 row_newbcast:4 row_mask:0xf bank_mask:0xf
	v_fmac_f32_dpp v61, v121, v142 row_newbcast:4 row_mask:0xf bank_mask:0xf
	v_fmac_f32_dpp v58, v122, v142 row_newbcast:4 row_mask:0xf bank_mask:0xf
	v_fmac_f32_dpp v59, v123, v142 row_newbcast:4 row_mask:0xf bank_mask:0xf
	v_fmac_f32_dpp v60, v124, v133 row_newbcast:4 row_mask:0xf bank_mask:0xf
	v_fmac_f32_dpp v61, v125, v133 row_newbcast:4 row_mask:0xf bank_mask:0xf
	v_fmac_f32_dpp v58, v126, v133 row_newbcast:4 row_mask:0xf bank_mask:0xf
	v_fmac_f32_dpp v59, v127, v133 row_newbcast:4 row_mask:0xf bank_mask:0xf
	v_fmac_f32_dpp v138, v128, v60 row_newbcast:4 row_mask:0xf bank_mask:0xf
	v_fmac_f32_dpp v139, v129, v61 row_newbcast:4 row_mask:0xf bank_mask:0xf
	v_fmac_f32_dpp v140, v130, v58 row_newbcast:4 row_mask:0xf bank_mask:0xf
	v_fmac_f32_dpp v141, v131, v59 row_newbcast:4 row_mask:0xf bank_mask:0xf
	v_mul_f32_dpp v56, v116, v56 row_newbcast:5 row_mask:0xf bank_mask:0xf
	v_mul_f32_dpp v57, v117, v57 row_newbcast:5 row_mask:0xf bank_mask:0xf
	v_mul_f32_dpp v54, v118, v54 row_newbcast:5 row_mask:0xf bank_mask:0xf
	v_mul_f32_dpp v55, v119, v55 row_newbcast:5 row_mask:0xf bank_mask:0xf
	v_fmac_f32_dpp v56, v120, v142 row_newbcast:5 row_mask:0xf bank_mask:0xf
	v_fmac_f32_dpp v57, v121, v142 row_newbcast:5 row_mask:0xf bank_mask:0xf
	v_fmac_f32_dpp v54, v122, v142 row_newbcast:5 row_mask:0xf bank_mask:0xf
	v_fmac_f32_dpp v55, v123, v142 row_newbcast:5 row_mask:0xf bank_mask:0xf
	v_fmac_f32_dpp v56, v124, v133 row_newbcast:5 row_mask:0xf bank_mask:0xf
	v_fmac_f32_dpp v57, v125, v133 row_newbcast:5 row_mask:0xf bank_mask:0xf
	v_fmac_f32_dpp v54, v126, v133 row_newbcast:5 row_mask:0xf bank_mask:0xf
	v_fmac_f32_dpp v55, v127, v133 row_newbcast:5 row_mask:0xf bank_mask:0xf
	v_fmac_f32_dpp v138, v128, v56 row_newbcast:5 row_mask:0xf bank_mask:0xf
	v_fmac_f32_dpp v139, v129, v57 row_newbcast:5 row_mask:0xf bank_mask:0xf
	v_fmac_f32_dpp v140, v130, v54 row_newbcast:5 row_mask:0xf bank_mask:0xf
	v_fmac_f32_dpp v141, v131, v55 row_newbcast:5 row_mask:0xf bank_mask:0xf
	v_mul_f32_dpp v50, v116, v50 row_newbcast:6 row_mask:0xf bank_mask:0xf
	v_mul_f32_dpp v51, v117, v51 row_newbcast:6 row_mask:0xf bank_mask:0xf
	v_mul_f32_dpp v48, v118, v48 row_newbcast:6 row_mask:0xf bank_mask:0xf
	v_mul_f32_dpp v49, v119, v49 row_newbcast:6 row_mask:0xf bank_mask:0xf
	v_fmac_f32_dpp v50, v120, v142 row_newbcast:6 row_mask:0xf bank_mask:0xf
	v_fmac_f32_dpp v51, v121, v142 row_newbcast:6 row_mask:0xf bank_mask:0xf
	v_fmac_f32_dpp v48, v122, v142 row_newbcast:6 row_mask:0xf bank_mask:0xf
	v_fmac_f32_dpp v49, v123, v142 row_newbcast:6 row_mask:0xf bank_mask:0xf
	v_fmac_f32_dpp v50, v124, v133 row_newbcast:6 row_mask:0xf bank_mask:0xf
	v_fmac_f32_dpp v51, v125, v133 row_newbcast:6 row_mask:0xf bank_mask:0xf
	v_fmac_f32_dpp v48, v126, v133 row_newbcast:6 row_mask:0xf bank_mask:0xf
	v_fmac_f32_dpp v49, v127, v133 row_newbcast:6 row_mask:0xf bank_mask:0xf
	v_fmac_f32_dpp v138, v128, v50 row_newbcast:6 row_mask:0xf bank_mask:0xf
	v_fmac_f32_dpp v139, v129, v51 row_newbcast:6 row_mask:0xf bank_mask:0xf
	v_fmac_f32_dpp v140, v130, v48 row_newbcast:6 row_mask:0xf bank_mask:0xf
	v_fmac_f32_dpp v141, v131, v49 row_newbcast:6 row_mask:0xf bank_mask:0xf
	v_mul_f32_dpp v46, v116, v46 row_newbcast:7 row_mask:0xf bank_mask:0xf
	v_mul_f32_dpp v47, v117, v47 row_newbcast:7 row_mask:0xf bank_mask:0xf
	v_mul_f32_dpp v44, v118, v44 row_newbcast:7 row_mask:0xf bank_mask:0xf
	v_mul_f32_dpp v45, v119, v45 row_newbcast:7 row_mask:0xf bank_mask:0xf
	v_fmac_f32_dpp v46, v120, v142 row_newbcast:7 row_mask:0xf bank_mask:0xf
	v_fmac_f32_dpp v47, v121, v142 row_newbcast:7 row_mask:0xf bank_mask:0xf
	v_fmac_f32_dpp v44, v122, v142 row_newbcast:7 row_mask:0xf bank_mask:0xf
	v_fmac_f32_dpp v45, v123, v142 row_newbcast:7 row_mask:0xf bank_mask:0xf
	v_fmac_f32_dpp v46, v124, v133 row_newbcast:7 row_mask:0xf bank_mask:0xf
	v_fmac_f32_dpp v47, v125, v133 row_newbcast:7 row_mask:0xf bank_mask:0xf
	v_fmac_f32_dpp v44, v126, v133 row_newbcast:7 row_mask:0xf bank_mask:0xf
	v_fmac_f32_dpp v45, v127, v133 row_newbcast:7 row_mask:0xf bank_mask:0xf
	v_fmac_f32_dpp v138, v128, v46 row_newbcast:7 row_mask:0xf bank_mask:0xf
	v_fmac_f32_dpp v139, v129, v47 row_newbcast:7 row_mask:0xf bank_mask:0xf
	v_fmac_f32_dpp v140, v130, v44 row_newbcast:7 row_mask:0xf bank_mask:0xf
	v_fmac_f32_dpp v141, v131, v45 row_newbcast:7 row_mask:0xf bank_mask:0xf
; template <bool SK>
; __device__ __forceinline__ void scan_task(const float* R, const float* W, const float* KX, const float* KK, const float* KKA, const float* V, float* OUT, float* STT, const float* S0, float* SOUT, int nstep, int lane) {
;     ...
;         for (int k = 0; k < 64; k += 2) { d0 = fmaf(s[k], kk[k], d0); d1 = fmaf(s[k + 1], kk[k + 1], d1); }
;         const float nd = -(d0 + d1);
;         const float vt = SK ? V[(size_t)t * BW + lane] : 0.f;
;         float o0 = 0.f, o1 = 0.f;
; #pragma unroll
;         for (int k = 0; k < 64; k += 2) {
;             float x = s[k] * w[k]; x = fmaf(nd, kka[k], x); if (SK) x = fmaf(vt, kx[k], x); s[k] = x; o0 = fmaf(x, r[k], o0);
;             float y = s[k + 1] * w[k + 1]; y = fmaf(nd, kka[k + 1], y); if (SK) y = fmaf(vt, kx[k + 1], y); s[k + 1] = y; o1 = fmaf(y, r[k + 1], o1);
;         }
;         OUT[(size_t)t * BW + lane] = o0 + o1;
	v_mul_f32_dpp v42, v116, v42 row_newbcast:8 row_mask:0xf bank_mask:0xf
	v_mul_f32_dpp v43, v117, v43 row_newbcast:8 row_mask:0xf bank_mask:0xf
	v_mul_f32_dpp v40, v118, v40 row_newbcast:8 row_mask:0xf bank_mask:0xf
	v_mul_f32_dpp v41, v119, v41 row_newbcast:8 row_mask:0xf bank_mask:0xf
	v_fmac_f32_dpp v42, v120, v142 row_newbcast:8 row_mask:0xf bank_mask:0xf
	v_fmac_f32_dpp v43, v121, v142 row_newbcast:8 row_mask:0xf bank_mask:0xf
	v_fmac_f32_dpp v40, v122, v142 row_newbcast:8 row_mask:0xf bank_mask:0xf
	v_fmac_f32_dpp v41, v123, v142 row_newbcast:8 row_mask:0xf bank_mask:0xf
	v_fmac_f32_dpp v42, v124, v133 row_newbcast:8 row_mask:0xf bank_mask:0xf
	v_fmac_f32_dpp v43, v125, v133 row_newbcast:8 row_mask:0xf bank_mask:0xf
	v_fmac_f32_dpp v40, v126, v133 row_newbcast:8 row_mask:0xf bank_mask:0xf
	v_fmac_f32_dpp v41, v127, v133 row_newbcast:8 row_mask:0xf bank_mask:0xf
	v_fmac_f32_dpp v138, v128, v42 row_newbcast:8 row_mask:0xf bank_mask:0xf
	v_fmac_f32_dpp v139, v129, v43 row_newbcast:8 row_mask:0xf bank_mask:0xf
	v_fmac_f32_dpp v140, v130, v40 row_newbcast:8 row_mask:0xf bank_mask:0xf
	v_fmac_f32_dpp v141, v131, v41 row_newbcast:8 row_mask:0xf bank_mask:0xf
	v_mul_f32_dpp v38, v116, v38 row_newbcast:9 row_mask:0xf bank_mask:0xf
	v_mul_f32_dpp v39, v117, v39 row_newbcast:9 row_mask:0xf bank_mask:0xf
	v_mul_f32_dpp v36, v118, v36 row_newbcast:9 row_mask:0xf bank_mask:0xf
	v_mul_f32_dpp v37, v119, v37 row_newbcast:9 row_mask:0xf bank_mask:0xf
	v_fmac_f32_dpp v38, v120, v142 row_newbcast:9 row_mask:0xf bank_mask:0xf
	v_fmac_f32_dpp v39, v121, v142 row_newbcast:9 row_mask:0xf bank_mask:0xf
	v_fmac_f32_dpp v36, v122, v142 row_newbcast:9 row_mask:0xf bank_mask:0xf
	v_fmac_f32_dpp v37, v123, v142 row_newbcast:9 row_mask:0xf bank_mask:0xf
	v_fmac_f32_dpp v38, v124, v133 row_newbcast:9 row_mask:0xf bank_mask:0xf
	v_fmac_f32_dpp v39, v125, v133 row_newbcast:9 row_mask:0xf bank_mask:0xf
	v_fmac_f32_dpp v36, v126, v133 row_newbcast:9 row_mask:0xf bank_mask:0xf
	v_fmac_f32_dpp v37, v127, v133 row_newbcast:9 row_mask:0xf bank_mask:0xf
	v_fmac_f32_dpp v138, v128, v38 row_newbcast:9 row_mask:0xf bank_mask:0xf
	v_fmac_f32_dpp v139, v129, v39 row_newbcast:9 row_mask:0xf bank_mask:0xf
	v_fmac_f32_dpp v140, v130, v36 row_newbcast:9 row_mask:0xf bank_mask:0xf
	v_fmac_f32_dpp v141, v131, v37 row_newbcast:9 row_mask:0xf bank_mask:0xf
	v_mul_f32_dpp v32, v116, v32 row_newbcast:10 row_mask:0xf bank_mask:0xf
	v_mul_f32_dpp v33, v117, v33 row_newbcast:10 row_mask:0xf bank_mask:0xf
	v_mul_f32_dpp v30, v118, v30 row_newbcast:10 row_mask:0xf bank_mask:0xf
	v_mul_f32_dpp v31, v119, v31 row_newbcast:10 row_mask:0xf bank_mask:0xf
	v_fmac_f32_dpp v32, v120, v142 row_newbcast:10 row_mask:0xf bank_mask:0xf
	v_fmac_f32_dpp v33, v121, v142 row_newbcast:10 row_mask:0xf bank_mask:0xf
	v_fmac_f32_dpp v30, v122, v142 row_newbcast:10 row_mask:0xf bank_mask:0xf
	v_fmac_f32_dpp v31, v123, v142 row_newbcast:10 row_mask:0xf bank_mask:0xf
	v_fmac_f32_dpp v32, v124, v133 row_newbcast:10 row_mask:0xf bank_mask:0xf
	v_fmac_f32_dpp v33, v125, v133 row_newbcast:10 row_mask:0xf bank_mask:0xf
	v_fmac_f32_dpp v30, v126, v133 row_newbcast:10 row_mask:0xf bank_mask:0xf
	v_fmac_f32_dpp v31, v127, v133 row_newbcast:10 row_mask:0xf bank_mask:0xf
	v_fmac_f32_dpp v138, v128, v32 row_newbcast:10 row_mask:0xf bank_mask:0xf
	v_fmac_f32_dpp v139, v129, v33 row_newbcast:10 row_mask:0xf bank_mask:0xf
	v_fmac_f32_dpp v140, v130, v30 row_newbcast:10 row_mask:0xf bank_mask:0xf
	v_fmac_f32_dpp v141, v131, v31 row_newbcast:10 row_mask:0xf bank_mask:0xf
	v_mul_f32_dpp v28, v116, v28 row_newbcast:11 row_mask:0xf bank_mask:0xf
	v_mul_f32_dpp v29, v117, v29 row_newbcast:11 row_mask:0xf bank_mask:0xf
	v_mul_f32_dpp v26, v118, v26 row_newbcast:11 row_mask:0xf bank_mask:0xf
	v_mul_f32_dpp v27, v119, v27 row_newbcast:11 row_mask:0xf bank_mask:0xf
	v_fmac_f32_dpp v28, v120, v142 row_newbcast:11 row_mask:0xf bank_mask:0xf
	v_fmac_f32_dpp v29, v121, v142 row_newbcast:11 row_mask:0xf bank_mask:0xf
	v_fmac_f32_dpp v26, v122, v142 row_newbcast:11 row_mask:0xf bank_mask:0xf
	v_fmac_f32_dpp v27, v123, v142 row_newbcast:11 row_mask:0xf bank_mask:0xf
	v_fmac_f32_dpp v28, v124, v133 row_newbcast:11 row_mask:0xf bank_mask:0xf
	v_fmac_f32_dpp v29, v125, v133 row_newbcast:11 row_mask:0xf bank_mask:0xf
	v_fmac_f32_dpp v26, v126, v133 row_newbcast:11 row_mask:0xf bank_mask:0xf
	v_fmac_f32_dpp v27, v127, v133 row_newbcast:11 row_mask:0xf bank_mask:0xf
	v_fmac_f32_dpp v138, v128, v28 row_newbcast:11 row_mask:0xf bank_mask:0xf
	v_fmac_f32_dpp v139, v129, v29 row_newbcast:11 row_mask:0xf bank_mask:0xf
	v_fmac_f32_dpp v140, v130, v26 row_newbcast:11 row_mask:0xf bank_mask:0xf
	v_fmac_f32_dpp v141, v131, v27 row_newbcast:11 row_mask:0xf bank_mask:0xf
	v_mul_f32_dpp v24, v116, v24 row_newbcast:12 row_mask:0xf bank_mask:0xf
	v_mul_f32_dpp v25, v117, v25 row_newbcast:12 row_mask:0xf bank_mask:0xf
	v_mul_f32_dpp v22, v118, v22 row_newbcast:12 row_mask:0xf bank_mask:0xf
	v_mul_f32_dpp v23, v119, v23 row_newbcast:12 row_mask:0xf bank_mask:0xf
	v_fmac_f32_dpp v24, v120, v142 row_newbcast:12 row_mask:0xf bank_mask:0xf
	v_fmac_f32_dpp v25, v121, v142 row_newbcast:12 row_mask:0xf bank_mask:0xf
	v_fmac_f32_dpp v22, v122, v142 row_newbcast:12 row_mask:0xf bank_mask:0xf
	v_fmac_f32_dpp v23, v123, v142 row_newbcast:12 row_mask:0xf bank_mask:0xf
	v_fmac_f32_dpp v24, v124, v133 row_newbcast:12 row_mask:0xf bank_mask:0xf
	v_fmac_f32_dpp v25, v125, v133 row_newbcast:12 row_mask:0xf bank_mask:0xf
	v_fmac_f32_dpp v22, v126, v133 row_newbcast:12 row_mask:0xf bank_mask:0xf
	v_fmac_f32_dpp v23, v127, v133 row_newbcast:12 row_mask:0xf bank_mask:0xf
; template <bool SK>
; __device__ __forceinline__ void scan_task(const float* R, const float* W, const float* KX, const float* KK, const float* KKA, const float* V, float* OUT, float* STT, const float* S0, float* SOUT, int nstep, int lane) {
;     ...
;         for (int k = 0; k < 64; k += 2) { d0 = fmaf(s[k], kk[k], d0); d1 = fmaf(s[k + 1], kk[k + 1], d1); }
;         const float nd = -(d0 + d1);
;         const float vt = SK ? V[(size_t)t * BW + lane] : 0.f;
;         float o0 = 0.f, o1 = 0.f;
; #pragma unroll
;         for (int k = 0; k < 64; k += 2) {
;             float x = s[k] * w[k]; x = fmaf(nd, kka[k], x); if (SK) x = fmaf(vt, kx[k], x); s[k] = x; o0 = fmaf(x, r[k], o0);
;             float y = s[k + 1] * w[k + 1]; y = fmaf(nd, kka[k + 1], y); if (SK) y = fmaf(vt, kx[k + 1], y); s[k + 1] = y; o1 = fmaf(y, r[k + 1], o1);
;         }
;         OUT[(size_t)t * BW + lane] = o0 + o1;
	v_fmac_f32_dpp v138, v128, v24 row_newbcast:12 row_mask:0xf bank_mask:0xf
	v_fmac_f32_dpp v139, v129, v25 row_newbcast:12 row_mask:0xf bank_mask:0xf
	v_fmac_f32_dpp v140, v130, v22 row_newbcast:12 row_mask:0xf bank_mask:0xf
	v_fmac_f32_dpp v141, v131, v23 row_newbcast:12 row_mask:0xf bank_mask:0xf
	v_mul_f32_dpp v20, v116, v20 row_newbcast:13 row_mask:0xf bank_mask:0xf
	v_mul_f32_dpp v21, v117, v21 row_newbcast:13 row_mask:0xf bank_mask:0xf
	v_mul_f32_dpp v18, v118, v18 row_newbcast:13 row_mask:0xf bank_mask:0xf
	v_mul_f32_dpp v19, v119, v19 row_newbcast:13 row_mask:0xf bank_mask:0xf
	v_fmac_f32_dpp v20, v120, v142 row_newbcast:13 row_mask:0xf bank_mask:0xf
	v_fmac_f32_dpp v21, v121, v142 row_newbcast:13 row_mask:0xf bank_mask:0xf
	v_fmac_f32_dpp v18, v122, v142 row_newbcast:13 row_mask:0xf bank_mask:0xf
	v_fmac_f32_dpp v19, v123, v142 row_newbcast:13 row_mask:0xf bank_mask:0xf
	v_fmac_f32_dpp v20, v124, v133 row_newbcast:13 row_mask:0xf bank_mask:0xf
	v_fmac_f32_dpp v21, v125, v133 row_newbcast:13 row_mask:0xf bank_mask:0xf
	v_fmac_f32_dpp v18, v126, v133 row_newbcast:13 row_mask:0xf bank_mask:0xf
	v_fmac_f32_dpp v19, v127, v133 row_newbcast:13 row_mask:0xf bank_mask:0xf
	v_fmac_f32_dpp v138, v128, v20 row_newbcast:13 row_mask:0xf bank_mask:0xf
	v_fmac_f32_dpp v139, v129, v21 row_newbcast:13 row_mask:0xf bank_mask:0xf
	v_fmac_f32_dpp v140, v130, v18 row_newbcast:13 row_mask:0xf bank_mask:0xf
	v_fmac_f32_dpp v141, v131, v19 row_newbcast:13 row_mask:0xf bank_mask:0xf
	v_mul_f32_dpp v16, v116, v16 row_newbcast:14 row_mask:0xf bank_mask:0xf
	v_mul_f32_dpp v17, v117, v17 row_newbcast:14 row_mask:0xf bank_mask:0xf
	v_mul_f32_dpp v14, v118, v14 row_newbcast:14 row_mask:0xf bank_mask:0xf
	v_mul_f32_dpp v15, v119, v15 row_newbcast:14 row_mask:0xf bank_mask:0xf
	v_fmac_f32_dpp v16, v120, v142 row_newbcast:14 row_mask:0xf bank_mask:0xf
	v_fmac_f32_dpp v17, v121, v142 row_newbcast:14 row_mask:0xf bank_mask:0xf
	v_fmac_f32_dpp v14, v122, v142 row_newbcast:14 row_mask:0xf bank_mask:0xf
	v_fmac_f32_dpp v15, v123, v142 row_newbcast:14 row_mask:0xf bank_mask:0xf
	v_fmac_f32_dpp v16, v124, v133 row_newbcast:14 row_mask:0xf bank_mask:0xf
	v_fmac_f32_dpp v17, v125, v133 row_newbcast:14 row_mask:0xf bank_mask:0xf
	v_fmac_f32_dpp v14, v126, v133 row_newbcast:14 row_mask:0xf bank_mask:0xf
	v_fmac_f32_dpp v15, v127, v133 row_newbcast:14 row_mask:0xf bank_mask:0xf
	v_fmac_f32_dpp v138, v128, v16 row_newbcast:14 row_mask:0xf bank_mask:0xf
	v_fmac_f32_dpp v139, v129, v17 row_newbcast:14 row_mask:0xf bank_mask:0xf
	v_fmac_f32_dpp v140, v130, v14 row_newbcast:14 row_mask:0xf bank_mask:0xf
	v_fmac_f32_dpp v141, v131, v15 row_newbcast:14 row_mask:0xf bank_mask:0xf
	v_mul_f32_dpp v12, v116, v12 row_newbcast:15 row_mask:0xf bank_mask:0xf
	v_mul_f32_dpp v13, v117, v13 row_newbcast:15 row_mask:0xf bank_mask:0xf
	v_mul_f32_dpp v82, v118, v82 row_newbcast:15 row_mask:0xf bank_mask:0xf
	v_mul_f32_dpp v83, v119, v83 row_newbcast:15 row_mask:0xf bank_mask:0xf
	v_fmac_f32_dpp v12, v120, v142 row_newbcast:15 row_mask:0xf bank_mask:0xf
	v_fmac_f32_dpp v13, v121, v142 row_newbcast:15 row_mask:0xf bank_mask:0xf
	v_fmac_f32_dpp v82, v122, v142 row_newbcast:15 row_mask:0xf bank_mask:0xf
	v_fmac_f32_dpp v83, v123, v142 row_newbcast:15 row_mask:0xf bank_mask:0xf
	v_fmac_f32_dpp v12, v124, v133 row_newbcast:15 row_mask:0xf bank_mask:0xf
	v_fmac_f32_dpp v13, v125, v133 row_newbcast:15 row_mask:0xf bank_mask:0xf
	v_fmac_f32_dpp v82, v126, v133 row_newbcast:15 row_mask:0xf bank_mask:0xf
	v_fmac_f32_dpp v83, v127, v133 row_newbcast:15 row_mask:0xf bank_mask:0xf
	v_fmac_f32_dpp v138, v128, v12 row_newbcast:15 row_mask:0xf bank_mask:0xf
	v_fmac_f32_dpp v139, v129, v13 row_newbcast:15 row_mask:0xf bank_mask:0xf
	v_fmac_f32_dpp v140, v130, v82 row_newbcast:15 row_mask:0xf bank_mask:0xf
	v_fmac_f32_dpp v141, v131, v83 row_newbcast:15 row_mask:0xf bank_mask:0xf
	global_load_dwordx4 v[116:119], v143, s[90:91] offset:2048
	global_load_dwordx4 v[120:123], v143, s[94:95] offset:2048
	global_load_dwordx4 v[124:127], v143, s[92:93] offset:2048
	global_load_dwordx4 v[128:131], v143, s[88:89] offset:2048
	global_load_dword v133, v144, s[4:5] offset:2048
	v_add_f32_e32 v138, v138, v140
	v_add_f32_e32 v139, v139, v141
	v_add_f32_e32 v138, v138, v139
	global_store_dword v144, v138, s[6:7] offset:2048
	s_add_u32 s96, s96, 0x1000
	s_addc_u32 s97, s97, 0
	s_add_u32 s90, s90, 0x1000
	s_addc_u32 s91, s91, 0
	s_add_u32 s94, s94, 0x1000
	s_addc_u32 s95, s95, 0
	s_add_u32 s92, s92, 0x1000
	s_addc_u32 s93, s93, 0
	s_add_u32 s88, s88, 0x1000
	s_addc_u32 s89, s89, 0
	s_add_u32 s4, s4, 0x1000
	s_addc_u32 s5, s5, 0
	s_add_u32 s6, s6, 0x1000
	s_addc_u32 s7, s7, 0
	s_add_i32 s9, s9, 1
	s_cmp_lg_u32 s9, 32
	s_cbranch_scc1 .Lscan_s_loop
; template <bool SK>
; __device__ __forceinline__ void scan_task(const float* R, const float* W, const float* KX, const float* KK, const float* KKA, const float* V, float* OUT, float* STT, const float* S0, float* SOUT, int nstep, int lane) {
;     ...
;     }
;     asm volatile("" :: "v"(pf0), "v"(pf1), "v"(pf2), "v"(pf3), "v"(pf4));
;     if (STT) {
; #pragma unroll
;         for (int k = 0; k < 64; ++k) STT[k * 64 + lane] = s[k];
;     }
	s_waitcnt vmcnt(0)
	v_mov_b32_e32 v1, v145
	s_nop 0
	ds_read_b32 v92, v1 offset:0
	ds_read_b32 v93, v1 offset:256
	ds_read_b32 v94, v1 offset:512
	ds_read_b32 v95, v1 offset:768
	ds_read_b32 v96, v1 offset:1024
	ds_read_b32 v97, v1 offset:1280
	ds_read_b32 v98, v1 offset:1536
	ds_read_b32 v99, v1 offset:1792
	ds_read_b32 v100, v1 offset:2048
	ds_read_b32 v101, v1 offset:2304
	ds_read_b32 v102, v1 offset:2560
	ds_read_b32 v103, v1 offset:2816
	ds_read_b32 v104, v1 offset:3072
	ds_read_b32 v105, v1 offset:3328
	ds_read_b32 v106, v1 offset:3584
	ds_read_b32 v107, v1 offset:3840
	ds_read_b32 v108, v1 offset:4096
	ds_read_b32 v109, v1 offset:4352
	ds_read_b32 v110, v1 offset:4608
	ds_read_b32 v111, v1 offset:4864
	ds_read_b32 v112, v1 offset:5120
	ds_read_b32 v113, v1 offset:5376
	ds_read_b32 v114, v1 offset:5632
	ds_read_b32 v115, v1 offset:5888
	ds_read_b32 v116, v1 offset:6144
	ds_read_b32 v117, v1 offset:6400
	ds_read_b32 v118, v1 offset:6656
	ds_read_b32 v119, v1 offset:6912
	ds_read_b32 v120, v1 offset:7168
	ds_read_b32 v121, v1 offset:7424
	ds_read_b32 v122, v1 offset:7680
	ds_read_b32 v123, v1 offset:7936
	ds_read_b32 v124, v1 offset:8192
	ds_read_b32 v125, v1 offset:8448
	ds_read_b32 v126, v1 offset:8704
	ds_read_b32 v127, v1 offset:8960
	ds_read_b32 v128, v1 offset:9216
	ds_read_b32 v129, v1 offset:9472
	ds_read_b32 v130, v1 offset:9728
	ds_read_b32 v131, v1 offset:9984
	ds_read_b32 v132, v1 offset:10240
	ds_read_b32 v133, v1 offset:10496
	ds_read_b32 v134, v1 offset:10752
	ds_read_b32 v135, v1 offset:11008
	ds_read_b32 v136, v1 offset:11264
	ds_read_b32 v137, v1 offset:11520
	ds_read_b32 v138, v1 offset:11776
	ds_read_b32 v139, v1 offset:12032
	ds_read_b32 v140, v1 offset:12288
	ds_read_b32 v141, v1 offset:12544
	ds_read_b32 v142, v1 offset:12800
	ds_read_b32 v143, v1 offset:13056
	ds_read_b32 v144, v1 offset:13312
	ds_read_b32 v145, v1 offset:13568
	s_waitcnt lgkmcnt(0)
	v_readlane_b32 s8, v255, 23
	v_lshlrev_b64 v[52:53], 2, v[70:71]
	v_readlane_b32 s9, v255, 24
	s_mov_b64 s[0:1], 0x44b00000
	v_readlane_b32 s82, v254, 57
	v_lshl_add_u64 v[52:53], s[8:9], 0, v[52:53]
	v_lshl_add_u64 v[52:53], v[68:69], 2, v[52:53]
	v_add_co_u32_e32 v86, vcc, 0x44b00000, v52
	v_lshl_add_u64 v[84:85], v[52:53], 0, s[0:1]
	s_nop 0
	v_addc_co_u32_e32 v87, vcc, 0, v53, vcc
	s_mov_b32 s0, 0x44b01000
	global_store_dword v[86:87], v80, off
	global_store_dword v[84:85], v81, off offset:256
	global_store_dword v[84:85], v78, off offset:512
	global_store_dword v[84:85], v79, off offset:768
	global_store_dword v[84:85], v76, off offset:1024
	global_store_dword v[84:85], v77, off offset:1280
	global_store_dword v[84:85], v74, off offset:1536
	global_store_dword v[84:85], v75, off offset:1792
	global_store_dword v[84:85], v72, off offset:2048
	global_store_dword v[84:85], v73, off offset:2304
	global_store_dword v[84:85], v66, off offset:2560
	global_store_dword v[84:85], v67, off offset:2816
	global_store_dword v[84:85], v64, off offset:3072
	global_store_dword v[84:85], v65, off offset:3328
	global_store_dword v[84:85], v62, off offset:3584
	global_store_dword v[84:85], v63, off offset:3840
	v_add_co_u32_e32 v62, vcc, s0, v52
	s_mov_b32 s0, 0x44b02000
	s_nop 0
	v_addc_co_u32_e32 v63, vcc, 0, v53, vcc
	v_add_co_u32_e32 v64, vcc, s0, v52
	s_mov_b32 s0, 0x44b03000
	s_nop 0
	v_addc_co_u32_e32 v65, vcc, 0, v53, vcc
	global_store_dword v[64:65], v60, off offset:-4096
	global_store_dword v[62:63], v61, off offset:256
	global_store_dword v[62:63], v58, off offset:512
	global_store_dword v[62:63], v59, off offset:768
	global_store_dword v[62:63], v56, off offset:1024
	global_store_dword v[62:63], v57, off offset:1280
	global_store_dword v[62:63], v54, off offset:1536
	global_store_dword v[62:63], v55, off offset:1792
	global_store_dword v[62:63], v50, off offset:2048
	global_store_dword v[62:63], v51, off offset:2304
	global_store_dword v[62:63], v48, off offset:2560
	global_store_dword v[62:63], v49, off offset:2816
	global_store_dword v[62:63], v46, off offset:3072
	global_store_dword v[62:63], v47, off offset:3328
	global_store_dword v[62:63], v44, off offset:3584
	global_store_dword v[62:63], v45, off offset:3840
	global_store_dword v[64:65], v42, off
	global_store_dword v[64:65], v43, off offset:256
	global_store_dword v[64:65], v40, off offset:512
	global_store_dword v[64:65], v41, off offset:768
	global_store_dword v[64:65], v38, off offset:1024
	global_store_dword v[64:65], v39, off offset:1280
	global_store_dword v[64:65], v36, off offset:1536
	global_store_dword v[64:65], v37, off offset:1792
	global_store_dword v[64:65], v32, off offset:2048
	global_store_dword v[64:65], v33, off offset:2304
	global_store_dword v[64:65], v30, off offset:2560
	global_store_dword v[64:65], v31, off offset:2816
	global_store_dword v[64:65], v28, off offset:3072
	global_store_dword v[64:65], v29, off offset:3328
	global_store_dword v[64:65], v26, off offset:3584
	global_store_dword v[64:65], v27, off offset:3840
	v_add_co_u32_e32 v26, vcc, s0, v52
	v_readlane_b32 s84, v254, 59
	v_readlane_b32 s86, v254, 61
	v_readlane_b32 s88, v254, 63
	v_readlane_b32 s76, v255, 1
	v_readlane_b32 s78, v255, 3
	v_readlane_b32 s90, v255, 5
	v_readlane_b32 s56, v255, 7
	v_readlane_b32 s60, v255, 9
	v_readlane_b32 s74, v255, 15
	s_movk_i32 s64, 0xf800
	v_addc_co_u32_e32 v27, vcc, 0, v53, vcc
	s_mov_b64 s[0:1], 0
	v_readlane_b32 s93, v254, 40
	v_readlane_b32 s96, v254, 41
	v_readlane_b32 s97, v254, 42
	v_readlane_b32 s94, v251, 3
	v_readlane_b32 s80, v254, 43
	v_readlane_b32 s81, v254, 44
	v_readlane_b32 s83, v254, 58
	v_readlane_b32 s85, v254, 60
	v_readlane_b32 s87, v254, 62
	v_readlane_b32 s89, v255, 0
	v_readlane_b32 s77, v255, 2
	v_readlane_b32 s79, v255, 4
	v_readlane_b32 s91, v255, 6
	v_readlane_b32 s57, v255, 8
	v_readlane_b32 s61, v255, 10
	v_readlane_b32 s62, v255, 11
	v_readlane_b32 s63, v255, 12
	v_readlane_b32 s92, v255, 13
	s_movk_i32 s95, 0x4000
	s_mov_b32 s67, 0xf800000
	s_movk_i32 s68, 0x2a00
	s_movk_i32 s69, 0x1000
	s_movk_i32 s70, 0x1c00
	s_mov_b32 s71, 0x92492493
	v_readlane_b32 s72, v255, 14
	v_readlane_b32 s75, v255, 16
	s_mov_b32 s65, -1
	v_readlane_b32 s66, v255, 22
	v_readlane_b32 s7, v255, 27
	global_store_dword v[26:27], v24, off
	global_store_dword v[26:27], v25, off offset:256
	global_store_dword v[26:27], v22, off offset:512
	global_store_dword v[26:27], v23, off offset:768
	global_store_dword v[26:27], v20, off offset:1024
	global_store_dword v[26:27], v21, off offset:1280
	global_store_dword v[26:27], v18, off offset:1536
	global_store_dword v[26:27], v19, off offset:1792
	global_store_dword v[26:27], v16, off offset:2048
	global_store_dword v[26:27], v17, off offset:2304
	global_store_dword v[26:27], v14, off offset:2560
	global_store_dword v[26:27], v15, off offset:2816
	global_store_dword v[26:27], v12, off offset:3072
	global_store_dword v[26:27], v13, off offset:3328
	global_store_dword v[26:27], v82, off offset:3584
	global_store_dword v[26:27], v83, off offset:3840
; template <bool SK>
; __device__ __forceinline__ void scan_task(const float* R, const float* W, const float* KX, const float* KK, const float* KKA, const float* V, float* OUT, float* STT, const float* S0, float* SOUT, int nstep, int lane) {
;     ...
;     if (S0) {
; #pragma unroll
;         for (int k4 = 0; k4 < 16; ++k4) { const f32x4 v = *(const f32x4*)(S0 + lane * 64 + 4 * k4); s[4 * k4] = v[0]; s[4 * k4 + 1] = v[1]; s[4 * k4 + 2] = v[2]; s[4 * k4 + 3] = v[3]; }
;     } else {
; #pragma unroll
;         for (int k = 0; k < 64; ++k) s[k] = SK ? 0.f : (k == lane ? 1.f : 0.f);
;     }
.LBB0_909:
	s_and_b64 vcc, exec, s[0:1]
	s_cbranch_vccz .LBB0_903
	v_cmp_eq_u32_e32 vcc, 1, v68
	v_readfirstlane_b32 s37, v3
	v_readfirstlane_b32 s36, v2
	v_cndmask_b32_e64 v3, 0, 1.0, vcc
	v_cmp_eq_u32_e32 vcc, 0, v68
	v_readfirstlane_b32 s35, v5
	v_readfirstlane_b32 s34, v4
	v_cndmask_b32_e64 v2, 0, 1.0, vcc
	v_cmp_eq_u32_e32 vcc, 3, v68
	v_readfirstlane_b32 s27, v7
	v_readfirstlane_b32 s26, v6
	v_cndmask_b32_e64 v5, 0, 1.0, vcc
	v_cmp_eq_u32_e32 vcc, 2, v68
	v_readfirstlane_b32 s3, v9
	v_readfirstlane_b32 s2, v8
	v_cndmask_b32_e64 v4, 0, 1.0, vcc
	v_cmp_eq_u32_e32 vcc, 5, v68
	v_readfirstlane_b32 s1, v11
	v_readfirstlane_b32 s0, v10
	v_cndmask_b32_e64 v7, 0, 1.0, vcc
	v_cmp_eq_u32_e32 vcc, 4, v68
	s_add_i32 s4, s33, s28
	s_lshl_b32 s6, s25, 6
	v_cndmask_b32_e64 v6, 0, 1.0, vcc
	v_cmp_eq_u32_e32 vcc, 7, v68
	s_ashr_i32 s5, s4, 31
	s_add_i32 s25, s7, s6
	v_cndmask_b32_e64 v9, 0, 1.0, vcc
	v_cmp_eq_u32_e32 vcc, 6, v68
	s_lshl_b64 s[4:5], s[4:5], 11
	s_lshl_b32 s6, s25, 2
	v_cndmask_b32_e64 v8, 0, 1.0, vcc
	v_cmp_eq_u32_e32 vcc, 9, v68
	s_add_u32 s6, s8, s6
	s_addc_u32 s7, s9, 0
	v_cndmask_b32_e64 v11, 0, 1.0, vcc
	v_cmp_eq_u32_e32 vcc, 8, v68
	s_add_u32 s4, s6, s4
	s_addc_u32 s5, s7, s5
	v_cndmask_b32_e64 v10, 0, 1.0, vcc
	v_cmp_eq_u32_e32 vcc, 11, v68
	v_lshl_add_u64 v[72:73], v[68:69], 2, s[4:5]
	s_mov_b64 s[4:5], 0x42900000
	v_cndmask_b32_e64 v13, 0, 1.0, vcc
	v_cmp_eq_u32_e32 vcc, 10, v68
	s_mov_b32 s31, 0
	s_mov_b64 s[82:83], s[8:9]
	v_cndmask_b32_e64 v12, 0, 1.0, vcc
	v_cmp_eq_u32_e32 vcc, 13, v68
	v_lshl_add_u64 v[72:73], v[72:73], 0, s[4:5]
	v_mov_b32_e32 v1, 0
	v_cndmask_b32_e64 v15, 0, 1.0, vcc
	v_cmp_eq_u32_e32 vcc, 12, v68
	s_mov_b64 s[72:73], s[34:35]
	s_mov_b64 s[74:75], s[2:3]
	v_cndmask_b32_e64 v14, 0, 1.0, vcc
	v_cmp_eq_u32_e32 vcc, 15, v68
	s_mov_b64 s[76:77], s[36:37]
	s_mov_b64 s[78:79], s[0:1]
	v_cndmask_b32_e64 v17, 0, 1.0, vcc
	v_cmp_eq_u32_e32 vcc, 14, v68
	v_mov_b32_e32 v34, 0
	v_mov_b32_e32 v78, 0
	v_cndmask_b32_e64 v16, 0, 1.0, vcc
	v_cmp_eq_u32_e32 vcc, 17, v68
	v_mov_b32_e32 v79, 0
	v_mov_b32_e32 v80, 0
	v_cndmask_b32_e64 v19, 0, 1.0, vcc
	v_cmp_eq_u32_e32 vcc, 16, v68
	s_mov_b32 s25, 0
	s_mov_b64 s[38:39], 0x800
	v_cndmask_b32_e64 v18, 0, 1.0, vcc
	v_cmp_eq_u32_e32 vcc, 19, v68
	s_nop 1
	v_cndmask_b32_e64 v21, 0, 1.0, vcc
	v_cmp_eq_u32_e32 vcc, 18, v68
	s_nop 1
	v_cndmask_b32_e64 v20, 0, 1.0, vcc
	v_cmp_eq_u32_e32 vcc, 21, v68
	s_nop 1
	v_cndmask_b32_e64 v23, 0, 1.0, vcc
	v_cmp_eq_u32_e32 vcc, 20, v68
	s_nop 1
	v_cndmask_b32_e64 v22, 0, 1.0, vcc
	v_cmp_eq_u32_e32 vcc, 23, v68
	s_nop 1
	v_cndmask_b32_e64 v25, 0, 1.0, vcc
	v_cmp_eq_u32_e32 vcc, 22, v68
	s_nop 1
	v_cndmask_b32_e64 v24, 0, 1.0, vcc
	v_cmp_eq_u32_e32 vcc, 25, v68
	s_nop 1
	v_cndmask_b32_e64 v27, 0, 1.0, vcc
	v_cmp_eq_u32_e32 vcc, 24, v68
	s_nop 1
	v_cndmask_b32_e64 v26, 0, 1.0, vcc
	v_cmp_eq_u32_e32 vcc, 27, v68
	s_nop 1
	v_cndmask_b32_e64 v29, 0, 1.0, vcc
	v_cmp_eq_u32_e32 vcc, 26, v68
	s_nop 1
	v_cndmask_b32_e64 v28, 0, 1.0, vcc
	v_cmp_eq_u32_e32 vcc, 29, v68
	s_nop 1
	v_cndmask_b32_e64 v31, 0, 1.0, vcc
	v_cmp_eq_u32_e32 vcc, 28, v68
	s_nop 1
	v_cndmask_b32_e64 v30, 0, 1.0, vcc
	v_cmp_eq_u32_e32 vcc, 31, v68
	s_nop 1
	v_cndmask_b32_e64 v33, 0, 1.0, vcc
	v_cmp_eq_u32_e32 vcc, 30, v68
	s_nop 1
	v_cndmask_b32_e64 v32, 0, 1.0, vcc
	v_cmp_eq_u32_e32 vcc, 33, v68
	s_waitcnt vmcnt(0)
	s_nop 0
	v_cndmask_b32_e64 v37, 0, 1.0, vcc
	v_cmp_eq_u32_e32 vcc, 32, v68
	s_nop 1
	v_cndmask_b32_e64 v36, 0, 1.0, vcc
	v_cmp_eq_u32_e32 vcc, 35, v68
	s_nop 1
	v_cndmask_b32_e64 v39, 0, 1.0, vcc
	v_cmp_eq_u32_e32 vcc, 34, v68
	s_nop 1
	v_cndmask_b32_e64 v38, 0, 1.0, vcc
	v_cmp_eq_u32_e32 vcc, 37, v68
	s_nop 1
	v_cndmask_b32_e64 v41, 0, 1.0, vcc
	v_cmp_eq_u32_e32 vcc, 36, v68
	s_nop 1
	v_cndmask_b32_e64 v40, 0, 1.0, vcc
	v_cmp_eq_u32_e32 vcc, 39, v68
	s_nop 1
	v_cndmask_b32_e64 v43, 0, 1.0, vcc
	v_cmp_eq_u32_e32 vcc, 38, v68
	s_nop 1
	v_cndmask_b32_e64 v42, 0, 1.0, vcc
	v_cmp_eq_u32_e32 vcc, 41, v68
	s_nop 1
	v_cndmask_b32_e64 v45, 0, 1.0, vcc
	v_cmp_eq_u32_e32 vcc, 40, v68
	s_nop 1
	v_cndmask_b32_e64 v44, 0, 1.0, vcc
	v_cmp_eq_u32_e32 vcc, 43, v68
	s_nop 1
	v_cndmask_b32_e64 v47, 0, 1.0, vcc
	v_cmp_eq_u32_e32 vcc, 42, v68
	s_nop 1
	v_cndmask_b32_e64 v46, 0, 1.0, vcc
	v_cmp_eq_u32_e32 vcc, 45, v68
	s_nop 1
	v_cndmask_b32_e64 v49, 0, 1.0, vcc
	v_cmp_eq_u32_e32 vcc, 44, v68
	s_nop 1
	v_cndmask_b32_e64 v48, 0, 1.0, vcc
	v_cmp_eq_u32_e32 vcc, 47, v68
	s_nop 1
	v_cndmask_b32_e64 v51, 0, 1.0, vcc
	v_cmp_eq_u32_e32 vcc, 46, v68
	s_nop 1
	v_cndmask_b32_e64 v50, 0, 1.0, vcc
	v_cmp_eq_u32_e32 vcc, 49, v68
	s_nop 1
	v_cndmask_b32_e64 v53, 0, 1.0, vcc
	v_cmp_eq_u32_e32 vcc, 48, v68
	s_nop 1
	v_cndmask_b32_e64 v52, 0, 1.0, vcc
	v_cmp_eq_u32_e32 vcc, 51, v68
	s_nop 1
	v_cndmask_b32_e64 v55, 0, 1.0, vcc
	v_cmp_eq_u32_e32 vcc, 50, v68
	s_nop 1
	v_cndmask_b32_e64 v54, 0, 1.0, vcc
	v_cmp_eq_u32_e32 vcc, 53, v68
	s_nop 1
	v_cndmask_b32_e64 v57, 0, 1.0, vcc
	v_cmp_eq_u32_e32 vcc, 52, v68
	s_nop 1
	v_cndmask_b32_e64 v56, 0, 1.0, vcc
	v_cmp_eq_u32_e32 vcc, 55, v68
	s_nop 1
	v_cndmask_b32_e64 v59, 0, 1.0, vcc
	v_cmp_eq_u32_e32 vcc, 54, v68
	s_nop 1
	v_cndmask_b32_e64 v58, 0, 1.0, vcc
	v_cmp_eq_u32_e32 vcc, 57, v68
	s_nop 1
	v_cndmask_b32_e64 v61, 0, 1.0, vcc
	v_cmp_eq_u32_e32 vcc, 56, v68
	s_nop 1
	v_cndmask_b32_e64 v60, 0, 1.0, vcc
	v_cmp_eq_u32_e32 vcc, 59, v68
	s_nop 1
	v_cndmask_b32_e64 v63, 0, 1.0, vcc
	v_cmp_eq_u32_e32 vcc, 58, v68
	s_nop 1
	v_cndmask_b32_e64 v62, 0, 1.0, vcc
	v_cmp_eq_u32_e32 vcc, 61, v68
	s_nop 1
	v_cndmask_b32_e64 v65, 0, 1.0, vcc
	v_cmp_eq_u32_e32 vcc, 60, v68
	s_nop 1
	v_cndmask_b32_e64 v64, 0, 1.0, vcc
	v_cmp_eq_u32_e32 vcc, 63, v68
	s_nop 1
	v_cndmask_b32_e64 v67, 0, 1.0, vcc
; template <bool SK>
; __device__ __forceinline__ void scan_task(const float* R, const float* W, const float* KX, const float* KK, const float* KKA, const float* V, float* OUT, float* STT, const float* S0, float* SOUT, int nstep, int lane) {
;     ...
;         for (int k = 0; k < 64; ++k) s[k] = SK ? 0.f : (k == lane ? 1.f : 0.f);
;     }
;     float pf0 = 0.f, pf1 = 0.f, pf2 = 0.f, pf3 = 0.f, pf4 = 0.f;
;     for (int t = 0; t < nstep; ++t) {
;         asm volatile("" :: "v"(pf0), "v"(pf1), "v"(pf2), "v"(pf3), "v"(pf4));
;         { const int tp = (t + 2 < nstep) ? t + 2 : t; const size_t po = (size_t)tp * BW + lane;
;           pf0 = KK[po]; pf1 = W[po]; pf2 = KKA[po]; pf3 = KX[po]; pf4 = R[po]; }
;         cfloat* kk = (cfloat*)(KK + (size_t)t * BW); cfloat* w = (cfloat*)(W + (size_t)t * BW); cfloat* kka = (cfloat*)(KKA + (size_t)t * BW);
;         cfloat* kx = (cfloat*)(KX + (size_t)t * BW); cfloat* r = (cfloat*)(R + (size_t)t * BW);
;         float d0 = 0.f, d1 = 0.f;
; #pragma unroll
;         for (int k = 0; k < 64; k += 2) { d0 = fmaf(s[k], kk[k], d0); d1 = fmaf(s[k + 1], kk[k + 1], d1); }
;         const float nd = -(d0 + d1);
	v_cmp_eq_u32_e32 vcc, 62, v68
	s_nop 1
	v_cndmask_b32_e64 v66, 0, 1.0, vcc
	v_readlane_b32 s8, v251, 3
	s_nop 3
	s_mul_i32 s8, s8, 0x3800
	s_nop 0
	v_lshl_add_u32 v1, v68, 2, s8
	ds_write_b32 v1, v92 offset:0
	ds_write_b32 v1, v93 offset:256
	ds_write_b32 v1, v94 offset:512
	ds_write_b32 v1, v95 offset:768
	ds_write_b32 v1, v96 offset:1024
	ds_write_b32 v1, v97 offset:1280
	ds_write_b32 v1, v98 offset:1536
	ds_write_b32 v1, v99 offset:1792
	ds_write_b32 v1, v100 offset:2048
	ds_write_b32 v1, v101 offset:2304
	ds_write_b32 v1, v102 offset:2560
	ds_write_b32 v1, v103 offset:2816
	ds_write_b32 v1, v104 offset:3072
	ds_write_b32 v1, v105 offset:3328
	ds_write_b32 v1, v106 offset:3584
	ds_write_b32 v1, v107 offset:3840
	ds_write_b32 v1, v108 offset:4096
	ds_write_b32 v1, v109 offset:4352
	ds_write_b32 v1, v110 offset:4608
	ds_write_b32 v1, v111 offset:4864
	ds_write_b32 v1, v112 offset:5120
	ds_write_b32 v1, v113 offset:5376
	ds_write_b32 v1, v114 offset:5632
	ds_write_b32 v1, v115 offset:5888
	ds_write_b32 v1, v116 offset:6144
	ds_write_b32 v1, v117 offset:6400
	ds_write_b32 v1, v118 offset:6656
	ds_write_b32 v1, v119 offset:6912
	ds_write_b32 v1, v120 offset:7168
	ds_write_b32 v1, v121 offset:7424
	ds_write_b32 v1, v122 offset:7680
	ds_write_b32 v1, v123 offset:7936
	ds_write_b32 v1, v124 offset:8192
	ds_write_b32 v1, v125 offset:8448
	ds_write_b32 v1, v126 offset:8704
	ds_write_b32 v1, v127 offset:8960
	ds_write_b32 v1, v128 offset:9216
	ds_write_b32 v1, v129 offset:9472
	ds_write_b32 v1, v130 offset:9728
	ds_write_b32 v1, v131 offset:9984
	ds_write_b32 v1, v132 offset:10240
	ds_write_b32 v1, v133 offset:10496
	ds_write_b32 v1, v134 offset:10752
	ds_write_b32 v1, v135 offset:11008
	v_readfirstlane_b32 s6, v72
	v_readfirstlane_b32 s7, v73
	s_waitcnt lgkmcnt(0)
	v_mov_b32_e32 v135, v1
	v_and_b32_e32 v133, 15, v68
	v_lshlrev_b32_e32 v133, 4, v133
	v_lshlrev_b32_e32 v134, 2, v68
	s_nop 0
	global_load_dwordx4 v[92:95], v133, s[72:73]
	global_load_dwordx4 v[96:99], v133, s[74:75]
	global_load_dwordx4 v[100:103], v133, s[76:77]
	global_load_dwordx4 v[104:107], v133, s[78:79]
	global_load_dwordx4 v[108:111], v133, s[72:73] offset:2048
	global_load_dwordx4 v[112:115], v133, s[74:75] offset:2048
	global_load_dwordx4 v[116:119], v133, s[76:77] offset:2048
	global_load_dwordx4 v[120:123], v133, s[78:79] offset:2048
	s_add_u32 s72, s72, 0x1000
	s_addc_u32 s73, s73, 0
	s_add_u32 s74, s74, 0x1000
	s_addc_u32 s75, s75, 0
	s_add_u32 s76, s76, 0x1000
	s_addc_u32 s77, s77, 0
	s_add_u32 s78, s78, 0x1000
	s_addc_u32 s79, s79, 0
	s_mov_b32 s9, 0
	s_waitcnt vmcnt(0)
.Lscan_p_loop:
	s_waitcnt vmcnt(6)
	v_mul_f32_dpp v124, v92, v2 row_newbcast:0 row_mask:0xf bank_mask:0xf
	v_mul_f32_dpp v125, v93, v3 row_newbcast:0 row_mask:0xf bank_mask:0xf
	v_mul_f32_dpp v126, v94, v4 row_newbcast:0 row_mask:0xf bank_mask:0xf
	v_mul_f32_dpp v127, v95, v5 row_newbcast:0 row_mask:0xf bank_mask:0xf
	v_fmac_f32_dpp v124, v92, v6 row_newbcast:1 row_mask:0xf bank_mask:0xf
	v_fmac_f32_dpp v125, v93, v7 row_newbcast:1 row_mask:0xf bank_mask:0xf
	v_fmac_f32_dpp v126, v94, v8 row_newbcast:1 row_mask:0xf bank_mask:0xf
	v_fmac_f32_dpp v127, v95, v9 row_newbcast:1 row_mask:0xf bank_mask:0xf
	v_fmac_f32_dpp v124, v92, v10 row_newbcast:2 row_mask:0xf bank_mask:0xf
	v_fmac_f32_dpp v125, v93, v11 row_newbcast:2 row_mask:0xf bank_mask:0xf
	v_fmac_f32_dpp v126, v94, v12 row_newbcast:2 row_mask:0xf bank_mask:0xf
	v_fmac_f32_dpp v127, v95, v13 row_newbcast:2 row_mask:0xf bank_mask:0xf
	v_fmac_f32_dpp v124, v92, v14 row_newbcast:3 row_mask:0xf bank_mask:0xf
	v_fmac_f32_dpp v125, v93, v15 row_newbcast:3 row_mask:0xf bank_mask:0xf
	v_fmac_f32_dpp v126, v94, v16 row_newbcast:3 row_mask:0xf bank_mask:0xf
	v_fmac_f32_dpp v127, v95, v17 row_newbcast:3 row_mask:0xf bank_mask:0xf
	v_fmac_f32_dpp v124, v92, v18 row_newbcast:4 row_mask:0xf bank_mask:0xf
	v_fmac_f32_dpp v125, v93, v19 row_newbcast:4 row_mask:0xf bank_mask:0xf
	v_fmac_f32_dpp v126, v94, v20 row_newbcast:4 row_mask:0xf bank_mask:0xf
	v_fmac_f32_dpp v127, v95, v21 row_newbcast:4 row_mask:0xf bank_mask:0xf
	v_fmac_f32_dpp v124, v92, v22 row_newbcast:5 row_mask:0xf bank_mask:0xf
	v_fmac_f32_dpp v125, v93, v23 row_newbcast:5 row_mask:0xf bank_mask:0xf
	v_fmac_f32_dpp v126, v94, v24 row_newbcast:5 row_mask:0xf bank_mask:0xf
	v_fmac_f32_dpp v127, v95, v25 row_newbcast:5 row_mask:0xf bank_mask:0xf
	v_fmac_f32_dpp v124, v92, v26 row_newbcast:6 row_mask:0xf bank_mask:0xf
	v_fmac_f32_dpp v125, v93, v27 row_newbcast:6 row_mask:0xf bank_mask:0xf
	v_fmac_f32_dpp v126, v94, v28 row_newbcast:6 row_mask:0xf bank_mask:0xf
	v_fmac_f32_dpp v127, v95, v29 row_newbcast:6 row_mask:0xf bank_mask:0xf
	v_fmac_f32_dpp v124, v92, v30 row_newbcast:7 row_mask:0xf bank_mask:0xf
	v_fmac_f32_dpp v125, v93, v31 row_newbcast:7 row_mask:0xf bank_mask:0xf
	v_fmac_f32_dpp v126, v94, v32 row_newbcast:7 row_mask:0xf bank_mask:0xf
	v_fmac_f32_dpp v127, v95, v33 row_newbcast:7 row_mask:0xf bank_mask:0xf
	v_fmac_f32_dpp v124, v92, v36 row_newbcast:8 row_mask:0xf bank_mask:0xf
	v_fmac_f32_dpp v125, v93, v37 row_newbcast:8 row_mask:0xf bank_mask:0xf
	v_fmac_f32_dpp v126, v94, v38 row_newbcast:8 row_mask:0xf bank_mask:0xf
	v_fmac_f32_dpp v127, v95, v39 row_newbcast:8 row_mask:0xf bank_mask:0xf
	v_fmac_f32_dpp v124, v92, v40 row_newbcast:9 row_mask:0xf bank_mask:0xf
	v_fmac_f32_dpp v125, v93, v41 row_newbcast:9 row_mask:0xf bank_mask:0xf
	v_fmac_f32_dpp v126, v94, v42 row_newbcast:9 row_mask:0xf bank_mask:0xf
	v_fmac_f32_dpp v127, v95, v43 row_newbcast:9 row_mask:0xf bank_mask:0xf
	v_fmac_f32_dpp v124, v92, v44 row_newbcast:10 row_mask:0xf bank_mask:0xf
; template <bool SK>
; __device__ __forceinline__ void scan_task(const float* R, const float* W, const float* KX, const float* KK, const float* KKA, const float* V, float* OUT, float* STT, const float* S0, float* SOUT, int nstep, int lane) {
;     ...
;         for (int k = 0; k < 64; k += 2) { d0 = fmaf(s[k], kk[k], d0); d1 = fmaf(s[k + 1], kk[k + 1], d1); }
;         const float nd = -(d0 + d1);
;         const float vt = SK ? V[(size_t)t * BW + lane] : 0.f;
;         float o0 = 0.f, o1 = 0.f;
; #pragma unroll
;         for (int k = 0; k < 64; k += 2) {
;             float x = s[k] * w[k]; x = fmaf(nd, kka[k], x); if (SK) x = fmaf(vt, kx[k], x); s[k] = x; o0 = fmaf(x, r[k], o0);
;             float y = s[k + 1] * w[k + 1]; y = fmaf(nd, kka[k + 1], y); if (SK) y = fmaf(vt, kx[k + 1], y); s[k + 1] = y; o1 = fmaf(y, r[k + 1], o1);
;         }
;         OUT[(size_t)t * BW + lane] = o0 + o1;
	v_fmac_f32_dpp v125, v93, v45 row_newbcast:10 row_mask:0xf bank_mask:0xf
	v_fmac_f32_dpp v126, v94, v46 row_newbcast:10 row_mask:0xf bank_mask:0xf
	v_fmac_f32_dpp v127, v95, v47 row_newbcast:10 row_mask:0xf bank_mask:0xf
	v_fmac_f32_dpp v124, v92, v48 row_newbcast:11 row_mask:0xf bank_mask:0xf
	v_fmac_f32_dpp v125, v93, v49 row_newbcast:11 row_mask:0xf bank_mask:0xf
	v_fmac_f32_dpp v126, v94, v50 row_newbcast:11 row_mask:0xf bank_mask:0xf
	v_fmac_f32_dpp v127, v95, v51 row_newbcast:11 row_mask:0xf bank_mask:0xf
	v_fmac_f32_dpp v124, v92, v52 row_newbcast:12 row_mask:0xf bank_mask:0xf
	v_fmac_f32_dpp v125, v93, v53 row_newbcast:12 row_mask:0xf bank_mask:0xf
	v_fmac_f32_dpp v126, v94, v54 row_newbcast:12 row_mask:0xf bank_mask:0xf
	v_fmac_f32_dpp v127, v95, v55 row_newbcast:12 row_mask:0xf bank_mask:0xf
	v_fmac_f32_dpp v124, v92, v56 row_newbcast:13 row_mask:0xf bank_mask:0xf
	v_fmac_f32_dpp v125, v93, v57 row_newbcast:13 row_mask:0xf bank_mask:0xf
	v_fmac_f32_dpp v126, v94, v58 row_newbcast:13 row_mask:0xf bank_mask:0xf
	v_fmac_f32_dpp v127, v95, v59 row_newbcast:13 row_mask:0xf bank_mask:0xf
	v_fmac_f32_dpp v124, v92, v60 row_newbcast:14 row_mask:0xf bank_mask:0xf
	v_fmac_f32_dpp v125, v93, v61 row_newbcast:14 row_mask:0xf bank_mask:0xf
	v_fmac_f32_dpp v126, v94, v62 row_newbcast:14 row_mask:0xf bank_mask:0xf
	v_fmac_f32_dpp v127, v95, v63 row_newbcast:14 row_mask:0xf bank_mask:0xf
	v_fmac_f32_dpp v124, v92, v64 row_newbcast:15 row_mask:0xf bank_mask:0xf
	v_fmac_f32_dpp v125, v93, v65 row_newbcast:15 row_mask:0xf bank_mask:0xf
	v_fmac_f32_dpp v126, v94, v66 row_newbcast:15 row_mask:0xf bank_mask:0xf
	v_fmac_f32_dpp v127, v95, v67 row_newbcast:15 row_mask:0xf bank_mask:0xf
	global_load_dwordx4 v[92:95], v133, s[72:73]
	v_add_f32_e32 v124, v124, v126
	v_add_f32_e32 v125, v125, v127
	v_add_f32_e32 v132, v124, v125
	v_xor_b32_e32 v132, 0x80000000, v132
	v_mul_f32_dpp v2, v96, v2 row_newbcast:0 row_mask:0xf bank_mask:0xf
	v_mul_f32_dpp v3, v97, v3 row_newbcast:0 row_mask:0xf bank_mask:0xf
	v_mul_f32_dpp v4, v98, v4 row_newbcast:0 row_mask:0xf bank_mask:0xf
	v_mul_f32_dpp v5, v99, v5 row_newbcast:0 row_mask:0xf bank_mask:0xf
	v_fmac_f32_dpp v2, v100, v132 row_newbcast:0 row_mask:0xf bank_mask:0xf
	v_fmac_f32_dpp v3, v101, v132 row_newbcast:0 row_mask:0xf bank_mask:0xf
	v_fmac_f32_dpp v4, v102, v132 row_newbcast:0 row_mask:0xf bank_mask:0xf
	v_fmac_f32_dpp v5, v103, v132 row_newbcast:0 row_mask:0xf bank_mask:0xf
	v_mul_f32_dpp v128, v104, v2 row_newbcast:0 row_mask:0xf bank_mask:0xf
	v_mul_f32_dpp v129, v105, v3 row_newbcast:0 row_mask:0xf bank_mask:0xf
	v_mul_f32_dpp v130, v106, v4 row_newbcast:0 row_mask:0xf bank_mask:0xf
	v_mul_f32_dpp v131, v107, v5 row_newbcast:0 row_mask:0xf bank_mask:0xf
	v_mul_f32_dpp v6, v96, v6 row_newbcast:1 row_mask:0xf bank_mask:0xf
	v_mul_f32_dpp v7, v97, v7 row_newbcast:1 row_mask:0xf bank_mask:0xf
	v_mul_f32_dpp v8, v98, v8 row_newbcast:1 row_mask:0xf bank_mask:0xf
	v_mul_f32_dpp v9, v99, v9 row_newbcast:1 row_mask:0xf bank_mask:0xf
	v_fmac_f32_dpp v6, v100, v132 row_newbcast:1 row_mask:0xf bank_mask:0xf
	v_fmac_f32_dpp v7, v101, v132 row_newbcast:1 row_mask:0xf bank_mask:0xf
	v_fmac_f32_dpp v8, v102, v132 row_newbcast:1 row_mask:0xf bank_mask:0xf
	v_fmac_f32_dpp v9, v103, v132 row_newbcast:1 row_mask:0xf bank_mask:0xf
	v_fmac_f32_dpp v128, v104, v6 row_newbcast:1 row_mask:0xf bank_mask:0xf
	v_fmac_f32_dpp v129, v105, v7 row_newbcast:1 row_mask:0xf bank_mask:0xf
	v_fmac_f32_dpp v130, v106, v8 row_newbcast:1 row_mask:0xf bank_mask:0xf
	v_fmac_f32_dpp v131, v107, v9 row_newbcast:1 row_mask:0xf bank_mask:0xf
	v_mul_f32_dpp v10, v96, v10 row_newbcast:2 row_mask:0xf bank_mask:0xf
	v_mul_f32_dpp v11, v97, v11 row_newbcast:2 row_mask:0xf bank_mask:0xf
	v_mul_f32_dpp v12, v98, v12 row_newbcast:2 row_mask:0xf bank_mask:0xf
	v_mul_f32_dpp v13, v99, v13 row_newbcast:2 row_mask:0xf bank_mask:0xf
	v_fmac_f32_dpp v10, v100, v132 row_newbcast:2 row_mask:0xf bank_mask:0xf
	v_fmac_f32_dpp v11, v101, v132 row_newbcast:2 row_mask:0xf bank_mask:0xf
	v_fmac_f32_dpp v12, v102, v132 row_newbcast:2 row_mask:0xf bank_mask:0xf
	v_fmac_f32_dpp v13, v103, v132 row_newbcast:2 row_mask:0xf bank_mask:0xf
	v_fmac_f32_dpp v128, v104, v10 row_newbcast:2 row_mask:0xf bank_mask:0xf
	v_fmac_f32_dpp v129, v105, v11 row_newbcast:2 row_mask:0xf bank_mask:0xf
	v_fmac_f32_dpp v130, v106, v12 row_newbcast:2 row_mask:0xf bank_mask:0xf
	v_fmac_f32_dpp v131, v107, v13 row_newbcast:2 row_mask:0xf bank_mask:0xf
	v_mul_f32_dpp v14, v96, v14 row_newbcast:3 row_mask:0xf bank_mask:0xf
	v_mul_f32_dpp v15, v97, v15 row_newbcast:3 row_mask:0xf bank_mask:0xf
	v_mul_f32_dpp v16, v98, v16 row_newbcast:3 row_mask:0xf bank_mask:0xf
	v_mul_f32_dpp v17, v99, v17 row_newbcast:3 row_mask:0xf bank_mask:0xf
	v_fmac_f32_dpp v14, v100, v132 row_newbcast:3 row_mask:0xf bank_mask:0xf
	v_fmac_f32_dpp v15, v101, v132 row_newbcast:3 row_mask:0xf bank_mask:0xf
	v_fmac_f32_dpp v16, v102, v132 row_newbcast:3 row_mask:0xf bank_mask:0xf
	v_fmac_f32_dpp v17, v103, v132 row_newbcast:3 row_mask:0xf bank_mask:0xf
	v_fmac_f32_dpp v128, v104, v14 row_newbcast:3 row_mask:0xf bank_mask:0xf
	v_fmac_f32_dpp v129, v105, v15 row_newbcast:3 row_mask:0xf bank_mask:0xf
	v_fmac_f32_dpp v130, v106, v16 row_newbcast:3 row_mask:0xf bank_mask:0xf
	v_fmac_f32_dpp v131, v107, v17 row_newbcast:3 row_mask:0xf bank_mask:0xf
	v_mul_f32_dpp v18, v96, v18 row_newbcast:4 row_mask:0xf bank_mask:0xf
	v_mul_f32_dpp v19, v97, v19 row_newbcast:4 row_mask:0xf bank_mask:0xf
	v_mul_f32_dpp v20, v98, v20 row_newbcast:4 row_mask:0xf bank_mask:0xf
	v_mul_f32_dpp v21, v99, v21 row_newbcast:4 row_mask:0xf bank_mask:0xf
; template <bool SK>
; __device__ __forceinline__ void scan_task(const float* R, const float* W, const float* KX, const float* KK, const float* KKA, const float* V, float* OUT, float* STT, const float* S0, float* SOUT, int nstep, int lane) {
;     ...
;         for (int k = 0; k < 64; k += 2) { d0 = fmaf(s[k], kk[k], d0); d1 = fmaf(s[k + 1], kk[k + 1], d1); }
;         const float nd = -(d0 + d1);
;         const float vt = SK ? V[(size_t)t * BW + lane] : 0.f;
;         float o0 = 0.f, o1 = 0.f;
; #pragma unroll
;         for (int k = 0; k < 64; k += 2) {
;             float x = s[k] * w[k]; x = fmaf(nd, kka[k], x); if (SK) x = fmaf(vt, kx[k], x); s[k] = x; o0 = fmaf(x, r[k], o0);
;             float y = s[k + 1] * w[k + 1]; y = fmaf(nd, kka[k + 1], y); if (SK) y = fmaf(vt, kx[k + 1], y); s[k + 1] = y; o1 = fmaf(y, r[k + 1], o1);
;         }
;         OUT[(size_t)t * BW + lane] = o0 + o1;
	v_fmac_f32_dpp v18, v100, v132 row_newbcast:4 row_mask:0xf bank_mask:0xf
	v_fmac_f32_dpp v19, v101, v132 row_newbcast:4 row_mask:0xf bank_mask:0xf
	v_fmac_f32_dpp v20, v102, v132 row_newbcast:4 row_mask:0xf bank_mask:0xf
	v_fmac_f32_dpp v21, v103, v132 row_newbcast:4 row_mask:0xf bank_mask:0xf
	v_fmac_f32_dpp v128, v104, v18 row_newbcast:4 row_mask:0xf bank_mask:0xf
	v_fmac_f32_dpp v129, v105, v19 row_newbcast:4 row_mask:0xf bank_mask:0xf
	v_fmac_f32_dpp v130, v106, v20 row_newbcast:4 row_mask:0xf bank_mask:0xf
	v_fmac_f32_dpp v131, v107, v21 row_newbcast:4 row_mask:0xf bank_mask:0xf
	v_mul_f32_dpp v22, v96, v22 row_newbcast:5 row_mask:0xf bank_mask:0xf
	v_mul_f32_dpp v23, v97, v23 row_newbcast:5 row_mask:0xf bank_mask:0xf
	v_mul_f32_dpp v24, v98, v24 row_newbcast:5 row_mask:0xf bank_mask:0xf
	v_mul_f32_dpp v25, v99, v25 row_newbcast:5 row_mask:0xf bank_mask:0xf
	v_fmac_f32_dpp v22, v100, v132 row_newbcast:5 row_mask:0xf bank_mask:0xf
	v_fmac_f32_dpp v23, v101, v132 row_newbcast:5 row_mask:0xf bank_mask:0xf
	v_fmac_f32_dpp v24, v102, v132 row_newbcast:5 row_mask:0xf bank_mask:0xf
	v_fmac_f32_dpp v25, v103, v132 row_newbcast:5 row_mask:0xf bank_mask:0xf
	v_fmac_f32_dpp v128, v104, v22 row_newbcast:5 row_mask:0xf bank_mask:0xf
	v_fmac_f32_dpp v129, v105, v23 row_newbcast:5 row_mask:0xf bank_mask:0xf
	v_fmac_f32_dpp v130, v106, v24 row_newbcast:5 row_mask:0xf bank_mask:0xf
	v_fmac_f32_dpp v131, v107, v25 row_newbcast:5 row_mask:0xf bank_mask:0xf
	v_mul_f32_dpp v26, v96, v26 row_newbcast:6 row_mask:0xf bank_mask:0xf
	v_mul_f32_dpp v27, v97, v27 row_newbcast:6 row_mask:0xf bank_mask:0xf
	v_mul_f32_dpp v28, v98, v28 row_newbcast:6 row_mask:0xf bank_mask:0xf
	v_mul_f32_dpp v29, v99, v29 row_newbcast:6 row_mask:0xf bank_mask:0xf
	v_fmac_f32_dpp v26, v100, v132 row_newbcast:6 row_mask:0xf bank_mask:0xf
	v_fmac_f32_dpp v27, v101, v132 row_newbcast:6 row_mask:0xf bank_mask:0xf
	v_fmac_f32_dpp v28, v102, v132 row_newbcast:6 row_mask:0xf bank_mask:0xf
	v_fmac_f32_dpp v29, v103, v132 row_newbcast:6 row_mask:0xf bank_mask:0xf
	v_fmac_f32_dpp v128, v104, v26 row_newbcast:6 row_mask:0xf bank_mask:0xf
	v_fmac_f32_dpp v129, v105, v27 row_newbcast:6 row_mask:0xf bank_mask:0xf
	v_fmac_f32_dpp v130, v106, v28 row_newbcast:6 row_mask:0xf bank_mask:0xf
	v_fmac_f32_dpp v131, v107, v29 row_newbcast:6 row_mask:0xf bank_mask:0xf
	v_mul_f32_dpp v30, v96, v30 row_newbcast:7 row_mask:0xf bank_mask:0xf
	v_mul_f32_dpp v31, v97, v31 row_newbcast:7 row_mask:0xf bank_mask:0xf
	v_mul_f32_dpp v32, v98, v32 row_newbcast:7 row_mask:0xf bank_mask:0xf
	v_mul_f32_dpp v33, v99, v33 row_newbcast:7 row_mask:0xf bank_mask:0xf
	v_fmac_f32_dpp v30, v100, v132 row_newbcast:7 row_mask:0xf bank_mask:0xf
	v_fmac_f32_dpp v31, v101, v132 row_newbcast:7 row_mask:0xf bank_mask:0xf
	v_fmac_f32_dpp v32, v102, v132 row_newbcast:7 row_mask:0xf bank_mask:0xf
	v_fmac_f32_dpp v33, v103, v132 row_newbcast:7 row_mask:0xf bank_mask:0xf
	v_fmac_f32_dpp v128, v104, v30 row_newbcast:7 row_mask:0xf bank_mask:0xf
	v_fmac_f32_dpp v129, v105, v31 row_newbcast:7 row_mask:0xf bank_mask:0xf
	v_fmac_f32_dpp v130, v106, v32 row_newbcast:7 row_mask:0xf bank_mask:0xf
	v_fmac_f32_dpp v131, v107, v33 row_newbcast:7 row_mask:0xf bank_mask:0xf
	v_mul_f32_dpp v36, v96, v36 row_newbcast:8 row_mask:0xf bank_mask:0xf
	v_mul_f32_dpp v37, v97, v37 row_newbcast:8 row_mask:0xf bank_mask:0xf
	v_mul_f32_dpp v38, v98, v38 row_newbcast:8 row_mask:0xf bank_mask:0xf
	v_mul_f32_dpp v39, v99, v39 row_newbcast:8 row_mask:0xf bank_mask:0xf
	v_fmac_f32_dpp v36, v100, v132 row_newbcast:8 row_mask:0xf bank_mask:0xf
	v_fmac_f32_dpp v37, v101, v132 row_newbcast:8 row_mask:0xf bank_mask:0xf
	v_fmac_f32_dpp v38, v102, v132 row_newbcast:8 row_mask:0xf bank_mask:0xf
	v_fmac_f32_dpp v39, v103, v132 row_newbcast:8 row_mask:0xf bank_mask:0xf
	v_fmac_f32_dpp v128, v104, v36 row_newbcast:8 row_mask:0xf bank_mask:0xf
	v_fmac_f32_dpp v129, v105, v37 row_newbcast:8 row_mask:0xf bank_mask:0xf
	v_fmac_f32_dpp v130, v106, v38 row_newbcast:8 row_mask:0xf bank_mask:0xf
	v_fmac_f32_dpp v131, v107, v39 row_newbcast:8 row_mask:0xf bank_mask:0xf
	v_mul_f32_dpp v40, v96, v40 row_newbcast:9 row_mask:0xf bank_mask:0xf
	v_mul_f32_dpp v41, v97, v41 row_newbcast:9 row_mask:0xf bank_mask:0xf
	v_mul_f32_dpp v42, v98, v42 row_newbcast:9 row_mask:0xf bank_mask:0xf
	v_mul_f32_dpp v43, v99, v43 row_newbcast:9 row_mask:0xf bank_mask:0xf
	v_fmac_f32_dpp v40, v100, v132 row_newbcast:9 row_mask:0xf bank_mask:0xf
	v_fmac_f32_dpp v41, v101, v132 row_newbcast:9 row_mask:0xf bank_mask:0xf
	v_fmac_f32_dpp v42, v102, v132 row_newbcast:9 row_mask:0xf bank_mask:0xf
	v_fmac_f32_dpp v43, v103, v132 row_newbcast:9 row_mask:0xf bank_mask:0xf
	v_fmac_f32_dpp v128, v104, v40 row_newbcast:9 row_mask:0xf bank_mask:0xf
	v_fmac_f32_dpp v129, v105, v41 row_newbcast:9 row_mask:0xf bank_mask:0xf
	v_fmac_f32_dpp v130, v106, v42 row_newbcast:9 row_mask:0xf bank_mask:0xf
	v_fmac_f32_dpp v131, v107, v43 row_newbcast:9 row_mask:0xf bank_mask:0xf
	v_mul_f32_dpp v44, v96, v44 row_newbcast:10 row_mask:0xf bank_mask:0xf
	v_mul_f32_dpp v45, v97, v45 row_newbcast:10 row_mask:0xf bank_mask:0xf
	v_mul_f32_dpp v46, v98, v46 row_newbcast:10 row_mask:0xf bank_mask:0xf
	v_mul_f32_dpp v47, v99, v47 row_newbcast:10 row_mask:0xf bank_mask:0xf
	v_fmac_f32_dpp v44, v100, v132 row_newbcast:10 row_mask:0xf bank_mask:0xf
	v_fmac_f32_dpp v45, v101, v132 row_newbcast:10 row_mask:0xf bank_mask:0xf
	v_fmac_f32_dpp v46, v102, v132 row_newbcast:10 row_mask:0xf bank_mask:0xf
	v_fmac_f32_dpp v47, v103, v132 row_newbcast:10 row_mask:0xf bank_mask:0xf
	v_fmac_f32_dpp v128, v104, v44 row_newbcast:10 row_mask:0xf bank_mask:0xf
; template <bool SK>
; __device__ __forceinline__ void scan_task(const float* R, const float* W, const float* KX, const float* KK, const float* KKA, const float* V, float* OUT, float* STT, const float* S0, float* SOUT, int nstep, int lane) {
;     ...
;         for (int k = 0; k < 64; k += 2) { d0 = fmaf(s[k], kk[k], d0); d1 = fmaf(s[k + 1], kk[k + 1], d1); }
;         const float nd = -(d0 + d1);
;         const float vt = SK ? V[(size_t)t * BW + lane] : 0.f;
;         float o0 = 0.f, o1 = 0.f;
; #pragma unroll
;         for (int k = 0; k < 64; k += 2) {
;             float x = s[k] * w[k]; x = fmaf(nd, kka[k], x); if (SK) x = fmaf(vt, kx[k], x); s[k] = x; o0 = fmaf(x, r[k], o0);
;             float y = s[k + 1] * w[k + 1]; y = fmaf(nd, kka[k + 1], y); if (SK) y = fmaf(vt, kx[k + 1], y); s[k + 1] = y; o1 = fmaf(y, r[k + 1], o1);
;         }
;         OUT[(size_t)t * BW + lane] = o0 + o1;
	v_fmac_f32_dpp v129, v105, v45 row_newbcast:10 row_mask:0xf bank_mask:0xf
	v_fmac_f32_dpp v130, v106, v46 row_newbcast:10 row_mask:0xf bank_mask:0xf
	v_fmac_f32_dpp v131, v107, v47 row_newbcast:10 row_mask:0xf bank_mask:0xf
	v_mul_f32_dpp v48, v96, v48 row_newbcast:11 row_mask:0xf bank_mask:0xf
	v_mul_f32_dpp v49, v97, v49 row_newbcast:11 row_mask:0xf bank_mask:0xf
	v_mul_f32_dpp v50, v98, v50 row_newbcast:11 row_mask:0xf bank_mask:0xf
	v_mul_f32_dpp v51, v99, v51 row_newbcast:11 row_mask:0xf bank_mask:0xf
	v_fmac_f32_dpp v48, v100, v132 row_newbcast:11 row_mask:0xf bank_mask:0xf
	v_fmac_f32_dpp v49, v101, v132 row_newbcast:11 row_mask:0xf bank_mask:0xf
	v_fmac_f32_dpp v50, v102, v132 row_newbcast:11 row_mask:0xf bank_mask:0xf
	v_fmac_f32_dpp v51, v103, v132 row_newbcast:11 row_mask:0xf bank_mask:0xf
	v_fmac_f32_dpp v128, v104, v48 row_newbcast:11 row_mask:0xf bank_mask:0xf
	v_fmac_f32_dpp v129, v105, v49 row_newbcast:11 row_mask:0xf bank_mask:0xf
	v_fmac_f32_dpp v130, v106, v50 row_newbcast:11 row_mask:0xf bank_mask:0xf
	v_fmac_f32_dpp v131, v107, v51 row_newbcast:11 row_mask:0xf bank_mask:0xf
	v_mul_f32_dpp v52, v96, v52 row_newbcast:12 row_mask:0xf bank_mask:0xf
	v_mul_f32_dpp v53, v97, v53 row_newbcast:12 row_mask:0xf bank_mask:0xf
	v_mul_f32_dpp v54, v98, v54 row_newbcast:12 row_mask:0xf bank_mask:0xf
	v_mul_f32_dpp v55, v99, v55 row_newbcast:12 row_mask:0xf bank_mask:0xf
	v_fmac_f32_dpp v52, v100, v132 row_newbcast:12 row_mask:0xf bank_mask:0xf
	v_fmac_f32_dpp v53, v101, v132 row_newbcast:12 row_mask:0xf bank_mask:0xf
	v_fmac_f32_dpp v54, v102, v132 row_newbcast:12 row_mask:0xf bank_mask:0xf
	v_fmac_f32_dpp v55, v103, v132 row_newbcast:12 row_mask:0xf bank_mask:0xf
	v_fmac_f32_dpp v128, v104, v52 row_newbcast:12 row_mask:0xf bank_mask:0xf
	v_fmac_f32_dpp v129, v105, v53 row_newbcast:12 row_mask:0xf bank_mask:0xf
	v_fmac_f32_dpp v130, v106, v54 row_newbcast:12 row_mask:0xf bank_mask:0xf
	v_fmac_f32_dpp v131, v107, v55 row_newbcast:12 row_mask:0xf bank_mask:0xf
	v_mul_f32_dpp v56, v96, v56 row_newbcast:13 row_mask:0xf bank_mask:0xf
	v_mul_f32_dpp v57, v97, v57 row_newbcast:13 row_mask:0xf bank_mask:0xf
	v_mul_f32_dpp v58, v98, v58 row_newbcast:13 row_mask:0xf bank_mask:0xf
	v_mul_f32_dpp v59, v99, v59 row_newbcast:13 row_mask:0xf bank_mask:0xf
	v_fmac_f32_dpp v56, v100, v132 row_newbcast:13 row_mask:0xf bank_mask:0xf
	v_fmac_f32_dpp v57, v101, v132 row_newbcast:13 row_mask:0xf bank_mask:0xf
	v_fmac_f32_dpp v58, v102, v132 row_newbcast:13 row_mask:0xf bank_mask:0xf
	v_fmac_f32_dpp v59, v103, v132 row_newbcast:13 row_mask:0xf bank_mask:0xf
	v_fmac_f32_dpp v128, v104, v56 row_newbcast:13 row_mask:0xf bank_mask:0xf
	v_fmac_f32_dpp v129, v105, v57 row_newbcast:13 row_mask:0xf bank_mask:0xf
	v_fmac_f32_dpp v130, v106, v58 row_newbcast:13 row_mask:0xf bank_mask:0xf
	v_fmac_f32_dpp v131, v107, v59 row_newbcast:13 row_mask:0xf bank_mask:0xf
	v_mul_f32_dpp v60, v96, v60 row_newbcast:14 row_mask:0xf bank_mask:0xf
	v_mul_f32_dpp v61, v97, v61 row_newbcast:14 row_mask:0xf bank_mask:0xf
	v_mul_f32_dpp v62, v98, v62 row_newbcast:14 row_mask:0xf bank_mask:0xf
	v_mul_f32_dpp v63, v99, v63 row_newbcast:14 row_mask:0xf bank_mask:0xf
	v_fmac_f32_dpp v60, v100, v132 row_newbcast:14 row_mask:0xf bank_mask:0xf
	v_fmac_f32_dpp v61, v101, v132 row_newbcast:14 row_mask:0xf bank_mask:0xf
	v_fmac_f32_dpp v62, v102, v132 row_newbcast:14 row_mask:0xf bank_mask:0xf
	v_fmac_f32_dpp v63, v103, v132 row_newbcast:14 row_mask:0xf bank_mask:0xf
	v_fmac_f32_dpp v128, v104, v60 row_newbcast:14 row_mask:0xf bank_mask:0xf
	v_fmac_f32_dpp v129, v105, v61 row_newbcast:14 row_mask:0xf bank_mask:0xf
	v_fmac_f32_dpp v130, v106, v62 row_newbcast:14 row_mask:0xf bank_mask:0xf
	v_fmac_f32_dpp v131, v107, v63 row_newbcast:14 row_mask:0xf bank_mask:0xf
	v_mul_f32_dpp v64, v96, v64 row_newbcast:15 row_mask:0xf bank_mask:0xf
	v_mul_f32_dpp v65, v97, v65 row_newbcast:15 row_mask:0xf bank_mask:0xf
	v_mul_f32_dpp v66, v98, v66 row_newbcast:15 row_mask:0xf bank_mask:0xf
	v_mul_f32_dpp v67, v99, v67 row_newbcast:15 row_mask:0xf bank_mask:0xf
	v_fmac_f32_dpp v64, v100, v132 row_newbcast:15 row_mask:0xf bank_mask:0xf
	v_fmac_f32_dpp v65, v101, v132 row_newbcast:15 row_mask:0xf bank_mask:0xf
	v_fmac_f32_dpp v66, v102, v132 row_newbcast:15 row_mask:0xf bank_mask:0xf
	v_fmac_f32_dpp v67, v103, v132 row_newbcast:15 row_mask:0xf bank_mask:0xf
	v_fmac_f32_dpp v128, v104, v64 row_newbcast:15 row_mask:0xf bank_mask:0xf
	v_fmac_f32_dpp v129, v105, v65 row_newbcast:15 row_mask:0xf bank_mask:0xf
	v_fmac_f32_dpp v130, v106, v66 row_newbcast:15 row_mask:0xf bank_mask:0xf
	v_fmac_f32_dpp v131, v107, v67 row_newbcast:15 row_mask:0xf bank_mask:0xf
	global_load_dwordx4 v[96:99], v133, s[74:75]
	global_load_dwordx4 v[100:103], v133, s[76:77]
	global_load_dwordx4 v[104:107], v133, s[78:79]
	v_add_f32_e32 v128, v128, v130
	v_add_f32_e32 v129, v129, v131
	v_add_f32_e32 v128, v128, v129
	global_store_dword v134, v128, s[6:7]
	s_waitcnt vmcnt(6)
; template <bool SK>
; __device__ __forceinline__ void scan_task(const float* R, const float* W, const float* KX, const float* KK, const float* KKA, const float* V, float* OUT, float* STT, const float* S0, float* SOUT, int nstep, int lane) {
;     ...
;         for (int k = 0; k < 64; k += 2) { d0 = fmaf(s[k], kk[k], d0); d1 = fmaf(s[k + 1], kk[k + 1], d1); }
;         const float nd = -(d0 + d1);
;         const float vt = SK ? V[(size_t)t * BW + lane] : 0.f;
;         float o0 = 0.f, o1 = 0.f;
; #pragma unroll
;         for (int k = 0; k < 64; k += 2) {
;             float x = s[k] * w[k]; x = fmaf(nd, kka[k], x); if (SK) x = fmaf(vt, kx[k], x); s[k] = x; o0 = fmaf(x, r[k], o0);
;             float y = s[k + 1] * w[k + 1]; y = fmaf(nd, kka[k + 1], y); if (SK) y = fmaf(vt, kx[k + 1], y); s[k + 1] = y; o1 = fmaf(y, r[k + 1], o1);
;         }
;         OUT[(size_t)t * BW + lane] = o0 + o1;
	v_mul_f32_dpp v124, v108, v2 row_newbcast:0 row_mask:0xf bank_mask:0xf
	v_mul_f32_dpp v125, v109, v3 row_newbcast:0 row_mask:0xf bank_mask:0xf
	v_mul_f32_dpp v126, v110, v4 row_newbcast:0 row_mask:0xf bank_mask:0xf
	v_mul_f32_dpp v127, v111, v5 row_newbcast:0 row_mask:0xf bank_mask:0xf
	v_fmac_f32_dpp v124, v108, v6 row_newbcast:1 row_mask:0xf bank_mask:0xf
	v_fmac_f32_dpp v125, v109, v7 row_newbcast:1 row_mask:0xf bank_mask:0xf
	v_fmac_f32_dpp v126, v110, v8 row_newbcast:1 row_mask:0xf bank_mask:0xf
	v_fmac_f32_dpp v127, v111, v9 row_newbcast:1 row_mask:0xf bank_mask:0xf
	v_fmac_f32_dpp v124, v108, v10 row_newbcast:2 row_mask:0xf bank_mask:0xf
	v_fmac_f32_dpp v125, v109, v11 row_newbcast:2 row_mask:0xf bank_mask:0xf
	v_fmac_f32_dpp v126, v110, v12 row_newbcast:2 row_mask:0xf bank_mask:0xf
	v_fmac_f32_dpp v127, v111, v13 row_newbcast:2 row_mask:0xf bank_mask:0xf
	v_fmac_f32_dpp v124, v108, v14 row_newbcast:3 row_mask:0xf bank_mask:0xf
	v_fmac_f32_dpp v125, v109, v15 row_newbcast:3 row_mask:0xf bank_mask:0xf
	v_fmac_f32_dpp v126, v110, v16 row_newbcast:3 row_mask:0xf bank_mask:0xf
	v_fmac_f32_dpp v127, v111, v17 row_newbcast:3 row_mask:0xf bank_mask:0xf
	v_fmac_f32_dpp v124, v108, v18 row_newbcast:4 row_mask:0xf bank_mask:0xf
	v_fmac_f32_dpp v125, v109, v19 row_newbcast:4 row_mask:0xf bank_mask:0xf
	v_fmac_f32_dpp v126, v110, v20 row_newbcast:4 row_mask:0xf bank_mask:0xf
	v_fmac_f32_dpp v127, v111, v21 row_newbcast:4 row_mask:0xf bank_mask:0xf
	v_fmac_f32_dpp v124, v108, v22 row_newbcast:5 row_mask:0xf bank_mask:0xf
	v_fmac_f32_dpp v125, v109, v23 row_newbcast:5 row_mask:0xf bank_mask:0xf
	v_fmac_f32_dpp v126, v110, v24 row_newbcast:5 row_mask:0xf bank_mask:0xf
	v_fmac_f32_dpp v127, v111, v25 row_newbcast:5 row_mask:0xf bank_mask:0xf
	v_fmac_f32_dpp v124, v108, v26 row_newbcast:6 row_mask:0xf bank_mask:0xf
	v_fmac_f32_dpp v125, v109, v27 row_newbcast:6 row_mask:0xf bank_mask:0xf
	v_fmac_f32_dpp v126, v110, v28 row_newbcast:6 row_mask:0xf bank_mask:0xf
	v_fmac_f32_dpp v127, v111, v29 row_newbcast:6 row_mask:0xf bank_mask:0xf
	v_fmac_f32_dpp v124, v108, v30 row_newbcast:7 row_mask:0xf bank_mask:0xf
	v_fmac_f32_dpp v125, v109, v31 row_newbcast:7 row_mask:0xf bank_mask:0xf
	v_fmac_f32_dpp v126, v110, v32 row_newbcast:7 row_mask:0xf bank_mask:0xf
	v_fmac_f32_dpp v127, v111, v33 row_newbcast:7 row_mask:0xf bank_mask:0xf
	v_fmac_f32_dpp v124, v108, v36 row_newbcast:8 row_mask:0xf bank_mask:0xf
	v_fmac_f32_dpp v125, v109, v37 row_newbcast:8 row_mask:0xf bank_mask:0xf
	v_fmac_f32_dpp v126, v110, v38 row_newbcast:8 row_mask:0xf bank_mask:0xf
	v_fmac_f32_dpp v127, v111, v39 row_newbcast:8 row_mask:0xf bank_mask:0xf
	v_fmac_f32_dpp v124, v108, v40 row_newbcast:9 row_mask:0xf bank_mask:0xf
	v_fmac_f32_dpp v125, v109, v41 row_newbcast:9 row_mask:0xf bank_mask:0xf
	v_fmac_f32_dpp v126, v110, v42 row_newbcast:9 row_mask:0xf bank_mask:0xf
	v_fmac_f32_dpp v127, v111, v43 row_newbcast:9 row_mask:0xf bank_mask:0xf
	v_fmac_f32_dpp v124, v108, v44 row_newbcast:10 row_mask:0xf bank_mask:0xf
	v_fmac_f32_dpp v125, v109, v45 row_newbcast:10 row_mask:0xf bank_mask:0xf
	v_fmac_f32_dpp v126, v110, v46 row_newbcast:10 row_mask:0xf bank_mask:0xf
	v_fmac_f32_dpp v127, v111, v47 row_newbcast:10 row_mask:0xf bank_mask:0xf
	v_fmac_f32_dpp v124, v108, v48 row_newbcast:11 row_mask:0xf bank_mask:0xf
	v_fmac_f32_dpp v125, v109, v49 row_newbcast:11 row_mask:0xf bank_mask:0xf
	v_fmac_f32_dpp v126, v110, v50 row_newbcast:11 row_mask:0xf bank_mask:0xf
	v_fmac_f32_dpp v127, v111, v51 row_newbcast:11 row_mask:0xf bank_mask:0xf
	v_fmac_f32_dpp v124, v108, v52 row_newbcast:12 row_mask:0xf bank_mask:0xf
	v_fmac_f32_dpp v125, v109, v53 row_newbcast:12 row_mask:0xf bank_mask:0xf
	v_fmac_f32_dpp v126, v110, v54 row_newbcast:12 row_mask:0xf bank_mask:0xf
	v_fmac_f32_dpp v127, v111, v55 row_newbcast:12 row_mask:0xf bank_mask:0xf
	v_fmac_f32_dpp v124, v108, v56 row_newbcast:13 row_mask:0xf bank_mask:0xf
	v_fmac_f32_dpp v125, v109, v57 row_newbcast:13 row_mask:0xf bank_mask:0xf
	v_fmac_f32_dpp v126, v110, v58 row_newbcast:13 row_mask:0xf bank_mask:0xf
	v_fmac_f32_dpp v127, v111, v59 row_newbcast:13 row_mask:0xf bank_mask:0xf
	v_fmac_f32_dpp v124, v108, v60 row_newbcast:14 row_mask:0xf bank_mask:0xf
	v_fmac_f32_dpp v125, v109, v61 row_newbcast:14 row_mask:0xf bank_mask:0xf
	v_fmac_f32_dpp v126, v110, v62 row_newbcast:14 row_mask:0xf bank_mask:0xf
	v_fmac_f32_dpp v127, v111, v63 row_newbcast:14 row_mask:0xf bank_mask:0xf
	v_fmac_f32_dpp v124, v108, v64 row_newbcast:15 row_mask:0xf bank_mask:0xf
	v_fmac_f32_dpp v125, v109, v65 row_newbcast:15 row_mask:0xf bank_mask:0xf
	v_fmac_f32_dpp v126, v110, v66 row_newbcast:15 row_mask:0xf bank_mask:0xf
	v_fmac_f32_dpp v127, v111, v67 row_newbcast:15 row_mask:0xf bank_mask:0xf
	global_load_dwordx4 v[108:111], v133, s[72:73] offset:2048
	v_add_f32_e32 v124, v124, v126
	v_add_f32_e32 v125, v125, v127
	v_add_f32_e32 v132, v124, v125
	v_xor_b32_e32 v132, 0x80000000, v132
	v_mul_f32_dpp v2, v112, v2 row_newbcast:0 row_mask:0xf bank_mask:0xf
	v_mul_f32_dpp v3, v113, v3 row_newbcast:0 row_mask:0xf bank_mask:0xf
	v_mul_f32_dpp v4, v114, v4 row_newbcast:0 row_mask:0xf bank_mask:0xf
	v_mul_f32_dpp v5, v115, v5 row_newbcast:0 row_mask:0xf bank_mask:0xf
	v_fmac_f32_dpp v2, v116, v132 row_newbcast:0 row_mask:0xf bank_mask:0xf
	v_fmac_f32_dpp v3, v117, v132 row_newbcast:0 row_mask:0xf bank_mask:0xf
	v_fmac_f32_dpp v4, v118, v132 row_newbcast:0 row_mask:0xf bank_mask:0xf
	v_fmac_f32_dpp v5, v119, v132 row_newbcast:0 row_mask:0xf bank_mask:0xf
	v_mul_f32_dpp v128, v120, v2 row_newbcast:0 row_mask:0xf bank_mask:0xf
	v_mul_f32_dpp v129, v121, v3 row_newbcast:0 row_mask:0xf bank_mask:0xf
; template <bool SK>
; __device__ __forceinline__ void scan_task(const float* R, const float* W, const float* KX, const float* KK, const float* KKA, const float* V, float* OUT, float* STT, const float* S0, float* SOUT, int nstep, int lane) {
;     ...
;         for (int k = 0; k < 64; k += 2) { d0 = fmaf(s[k], kk[k], d0); d1 = fmaf(s[k + 1], kk[k + 1], d1); }
;         const float nd = -(d0 + d1);
;         const float vt = SK ? V[(size_t)t * BW + lane] : 0.f;
;         float o0 = 0.f, o1 = 0.f;
; #pragma unroll
;         for (int k = 0; k < 64; k += 2) {
;             float x = s[k] * w[k]; x = fmaf(nd, kka[k], x); if (SK) x = fmaf(vt, kx[k], x); s[k] = x; o0 = fmaf(x, r[k], o0);
;             float y = s[k + 1] * w[k + 1]; y = fmaf(nd, kka[k + 1], y); if (SK) y = fmaf(vt, kx[k + 1], y); s[k + 1] = y; o1 = fmaf(y, r[k + 1], o1);
;         }
;         OUT[(size_t)t * BW + lane] = o0 + o1;
	v_mul_f32_dpp v130, v122, v4 row_newbcast:0 row_mask:0xf bank_mask:0xf
	v_mul_f32_dpp v131, v123, v5 row_newbcast:0 row_mask:0xf bank_mask:0xf
	v_mul_f32_dpp v6, v112, v6 row_newbcast:1 row_mask:0xf bank_mask:0xf
	v_mul_f32_dpp v7, v113, v7 row_newbcast:1 row_mask:0xf bank_mask:0xf
	v_mul_f32_dpp v8, v114, v8 row_newbcast:1 row_mask:0xf bank_mask:0xf
	v_mul_f32_dpp v9, v115, v9 row_newbcast:1 row_mask:0xf bank_mask:0xf
	v_fmac_f32_dpp v6, v116, v132 row_newbcast:1 row_mask:0xf bank_mask:0xf
	v_fmac_f32_dpp v7, v117, v132 row_newbcast:1 row_mask:0xf bank_mask:0xf
	v_fmac_f32_dpp v8, v118, v132 row_newbcast:1 row_mask:0xf bank_mask:0xf
	v_fmac_f32_dpp v9, v119, v132 row_newbcast:1 row_mask:0xf bank_mask:0xf
	v_fmac_f32_dpp v128, v120, v6 row_newbcast:1 row_mask:0xf bank_mask:0xf
	v_fmac_f32_dpp v129, v121, v7 row_newbcast:1 row_mask:0xf bank_mask:0xf
	v_fmac_f32_dpp v130, v122, v8 row_newbcast:1 row_mask:0xf bank_mask:0xf
	v_fmac_f32_dpp v131, v123, v9 row_newbcast:1 row_mask:0xf bank_mask:0xf
	v_mul_f32_dpp v10, v112, v10 row_newbcast:2 row_mask:0xf bank_mask:0xf
	v_mul_f32_dpp v11, v113, v11 row_newbcast:2 row_mask:0xf bank_mask:0xf
	v_mul_f32_dpp v12, v114, v12 row_newbcast:2 row_mask:0xf bank_mask:0xf
	v_mul_f32_dpp v13, v115, v13 row_newbcast:2 row_mask:0xf bank_mask:0xf
	v_fmac_f32_dpp v10, v116, v132 row_newbcast:2 row_mask:0xf bank_mask:0xf
	v_fmac_f32_dpp v11, v117, v132 row_newbcast:2 row_mask:0xf bank_mask:0xf
	v_fmac_f32_dpp v12, v118, v132 row_newbcast:2 row_mask:0xf bank_mask:0xf
	v_fmac_f32_dpp v13, v119, v132 row_newbcast:2 row_mask:0xf bank_mask:0xf
	v_fmac_f32_dpp v128, v120, v10 row_newbcast:2 row_mask:0xf bank_mask:0xf
	v_fmac_f32_dpp v129, v121, v11 row_newbcast:2 row_mask:0xf bank_mask:0xf
	v_fmac_f32_dpp v130, v122, v12 row_newbcast:2 row_mask:0xf bank_mask:0xf
	v_fmac_f32_dpp v131, v123, v13 row_newbcast:2 row_mask:0xf bank_mask:0xf
	v_mul_f32_dpp v14, v112, v14 row_newbcast:3 row_mask:0xf bank_mask:0xf
	v_mul_f32_dpp v15, v113, v15 row_newbcast:3 row_mask:0xf bank_mask:0xf
	v_mul_f32_dpp v16, v114, v16 row_newbcast:3 row_mask:0xf bank_mask:0xf
	v_mul_f32_dpp v17, v115, v17 row_newbcast:3 row_mask:0xf bank_mask:0xf
	v_fmac_f32_dpp v14, v116, v132 row_newbcast:3 row_mask:0xf bank_mask:0xf
	v_fmac_f32_dpp v15, v117, v132 row_newbcast:3 row_mask:0xf bank_mask:0xf
	v_fmac_f32_dpp v16, v118, v132 row_newbcast:3 row_mask:0xf bank_mask:0xf
	v_fmac_f32_dpp v17, v119, v132 row_newbcast:3 row_mask:0xf bank_mask:0xf
	v_fmac_f32_dpp v128, v120, v14 row_newbcast:3 row_mask:0xf bank_mask:0xf
	v_fmac_f32_dpp v129, v121, v15 row_newbcast:3 row_mask:0xf bank_mask:0xf
	v_fmac_f32_dpp v130, v122, v16 row_newbcast:3 row_mask:0xf bank_mask:0xf
	v_fmac_f32_dpp v131, v123, v17 row_newbcast:3 row_mask:0xf bank_mask:0xf
	v_mul_f32_dpp v18, v112, v18 row_newbcast:4 row_mask:0xf bank_mask:0xf
	v_mul_f32_dpp v19, v113, v19 row_newbcast:4 row_mask:0xf bank_mask:0xf
	v_mul_f32_dpp v20, v114, v20 row_newbcast:4 row_mask:0xf bank_mask:0xf
	v_mul_f32_dpp v21, v115, v21 row_newbcast:4 row_mask:0xf bank_mask:0xf
	v_fmac_f32_dpp v18, v116, v132 row_newbcast:4 row_mask:0xf bank_mask:0xf
	v_fmac_f32_dpp v19, v117, v132 row_newbcast:4 row_mask:0xf bank_mask:0xf
	v_fmac_f32_dpp v20, v118, v132 row_newbcast:4 row_mask:0xf bank_mask:0xf
	v_fmac_f32_dpp v21, v119, v132 row_newbcast:4 row_mask:0xf bank_mask:0xf
	v_fmac_f32_dpp v128, v120, v18 row_newbcast:4 row_mask:0xf bank_mask:0xf
	v_fmac_f32_dpp v129, v121, v19 row_newbcast:4 row_mask:0xf bank_mask:0xf
	v_fmac_f32_dpp v130, v122, v20 row_newbcast:4 row_mask:0xf bank_mask:0xf
	v_fmac_f32_dpp v131, v123, v21 row_newbcast:4 row_mask:0xf bank_mask:0xf
	v_mul_f32_dpp v22, v112, v22 row_newbcast:5 row_mask:0xf bank_mask:0xf
	v_mul_f32_dpp v23, v113, v23 row_newbcast:5 row_mask:0xf bank_mask:0xf
	v_mul_f32_dpp v24, v114, v24 row_newbcast:5 row_mask:0xf bank_mask:0xf
	v_mul_f32_dpp v25, v115, v25 row_newbcast:5 row_mask:0xf bank_mask:0xf
	v_fmac_f32_dpp v22, v116, v132 row_newbcast:5 row_mask:0xf bank_mask:0xf
	v_fmac_f32_dpp v23, v117, v132 row_newbcast:5 row_mask:0xf bank_mask:0xf
	v_fmac_f32_dpp v24, v118, v132 row_newbcast:5 row_mask:0xf bank_mask:0xf
	v_fmac_f32_dpp v25, v119, v132 row_newbcast:5 row_mask:0xf bank_mask:0xf
	v_fmac_f32_dpp v128, v120, v22 row_newbcast:5 row_mask:0xf bank_mask:0xf
	v_fmac_f32_dpp v129, v121, v23 row_newbcast:5 row_mask:0xf bank_mask:0xf
	v_fmac_f32_dpp v130, v122, v24 row_newbcast:5 row_mask:0xf bank_mask:0xf
	v_fmac_f32_dpp v131, v123, v25 row_newbcast:5 row_mask:0xf bank_mask:0xf
	v_mul_f32_dpp v26, v112, v26 row_newbcast:6 row_mask:0xf bank_mask:0xf
	v_mul_f32_dpp v27, v113, v27 row_newbcast:6 row_mask:0xf bank_mask:0xf
	v_mul_f32_dpp v28, v114, v28 row_newbcast:6 row_mask:0xf bank_mask:0xf
	v_mul_f32_dpp v29, v115, v29 row_newbcast:6 row_mask:0xf bank_mask:0xf
	v_fmac_f32_dpp v26, v116, v132 row_newbcast:6 row_mask:0xf bank_mask:0xf
	v_fmac_f32_dpp v27, v117, v132 row_newbcast:6 row_mask:0xf bank_mask:0xf
	v_fmac_f32_dpp v28, v118, v132 row_newbcast:6 row_mask:0xf bank_mask:0xf
	v_fmac_f32_dpp v29, v119, v132 row_newbcast:6 row_mask:0xf bank_mask:0xf
	v_fmac_f32_dpp v128, v120, v26 row_newbcast:6 row_mask:0xf bank_mask:0xf
	v_fmac_f32_dpp v129, v121, v27 row_newbcast:6 row_mask:0xf bank_mask:0xf
	v_fmac_f32_dpp v130, v122, v28 row_newbcast:6 row_mask:0xf bank_mask:0xf
	v_fmac_f32_dpp v131, v123, v29 row_newbcast:6 row_mask:0xf bank_mask:0xf
	v_mul_f32_dpp v30, v112, v30 row_newbcast:7 row_mask:0xf bank_mask:0xf
	v_mul_f32_dpp v31, v113, v31 row_newbcast:7 row_mask:0xf bank_mask:0xf
	v_mul_f32_dpp v32, v114, v32 row_newbcast:7 row_mask:0xf bank_mask:0xf
; template <bool SK>
; __device__ __forceinline__ void scan_task(const float* R, const float* W, const float* KX, const float* KK, const float* KKA, const float* V, float* OUT, float* STT, const float* S0, float* SOUT, int nstep, int lane) {
;     ...
;         for (int k = 0; k < 64; k += 2) { d0 = fmaf(s[k], kk[k], d0); d1 = fmaf(s[k + 1], kk[k + 1], d1); }
;         const float nd = -(d0 + d1);
;         const float vt = SK ? V[(size_t)t * BW + lane] : 0.f;
;         float o0 = 0.f, o1 = 0.f;
; #pragma unroll
;         for (int k = 0; k < 64; k += 2) {
;             float x = s[k] * w[k]; x = fmaf(nd, kka[k], x); if (SK) x = fmaf(vt, kx[k], x); s[k] = x; o0 = fmaf(x, r[k], o0);
;             float y = s[k + 1] * w[k + 1]; y = fmaf(nd, kka[k + 1], y); if (SK) y = fmaf(vt, kx[k + 1], y); s[k + 1] = y; o1 = fmaf(y, r[k + 1], o1);
;         }
;         OUT[(size_t)t * BW + lane] = o0 + o1;
	v_mul_f32_dpp v33, v115, v33 row_newbcast:7 row_mask:0xf bank_mask:0xf
	v_fmac_f32_dpp v30, v116, v132 row_newbcast:7 row_mask:0xf bank_mask:0xf
	v_fmac_f32_dpp v31, v117, v132 row_newbcast:7 row_mask:0xf bank_mask:0xf
	v_fmac_f32_dpp v32, v118, v132 row_newbcast:7 row_mask:0xf bank_mask:0xf
	v_fmac_f32_dpp v33, v119, v132 row_newbcast:7 row_mask:0xf bank_mask:0xf
	v_fmac_f32_dpp v128, v120, v30 row_newbcast:7 row_mask:0xf bank_mask:0xf
	v_fmac_f32_dpp v129, v121, v31 row_newbcast:7 row_mask:0xf bank_mask:0xf
	v_fmac_f32_dpp v130, v122, v32 row_newbcast:7 row_mask:0xf bank_mask:0xf
	v_fmac_f32_dpp v131, v123, v33 row_newbcast:7 row_mask:0xf bank_mask:0xf
	v_mul_f32_dpp v36, v112, v36 row_newbcast:8 row_mask:0xf bank_mask:0xf
	v_mul_f32_dpp v37, v113, v37 row_newbcast:8 row_mask:0xf bank_mask:0xf
	v_mul_f32_dpp v38, v114, v38 row_newbcast:8 row_mask:0xf bank_mask:0xf
	v_mul_f32_dpp v39, v115, v39 row_newbcast:8 row_mask:0xf bank_mask:0xf
	v_fmac_f32_dpp v36, v116, v132 row_newbcast:8 row_mask:0xf bank_mask:0xf
	v_fmac_f32_dpp v37, v117, v132 row_newbcast:8 row_mask:0xf bank_mask:0xf
	v_fmac_f32_dpp v38, v118, v132 row_newbcast:8 row_mask:0xf bank_mask:0xf
	v_fmac_f32_dpp v39, v119, v132 row_newbcast:8 row_mask:0xf bank_mask:0xf
	v_fmac_f32_dpp v128, v120, v36 row_newbcast:8 row_mask:0xf bank_mask:0xf
	v_fmac_f32_dpp v129, v121, v37 row_newbcast:8 row_mask:0xf bank_mask:0xf
	v_fmac_f32_dpp v130, v122, v38 row_newbcast:8 row_mask:0xf bank_mask:0xf
	v_fmac_f32_dpp v131, v123, v39 row_newbcast:8 row_mask:0xf bank_mask:0xf
	v_mul_f32_dpp v40, v112, v40 row_newbcast:9 row_mask:0xf bank_mask:0xf
	v_mul_f32_dpp v41, v113, v41 row_newbcast:9 row_mask:0xf bank_mask:0xf
	v_mul_f32_dpp v42, v114, v42 row_newbcast:9 row_mask:0xf bank_mask:0xf
	v_mul_f32_dpp v43, v115, v43 row_newbcast:9 row_mask:0xf bank_mask:0xf
	v_fmac_f32_dpp v40, v116, v132 row_newbcast:9 row_mask:0xf bank_mask:0xf
	v_fmac_f32_dpp v41, v117, v132 row_newbcast:9 row_mask:0xf bank_mask:0xf
	v_fmac_f32_dpp v42, v118, v132 row_newbcast:9 row_mask:0xf bank_mask:0xf
	v_fmac_f32_dpp v43, v119, v132 row_newbcast:9 row_mask:0xf bank_mask:0xf
	v_fmac_f32_dpp v128, v120, v40 row_newbcast:9 row_mask:0xf bank_mask:0xf
	v_fmac_f32_dpp v129, v121, v41 row_newbcast:9 row_mask:0xf bank_mask:0xf
	v_fmac_f32_dpp v130, v122, v42 row_newbcast:9 row_mask:0xf bank_mask:0xf
	v_fmac_f32_dpp v131, v123, v43 row_newbcast:9 row_mask:0xf bank_mask:0xf
	v_mul_f32_dpp v44, v112, v44 row_newbcast:10 row_mask:0xf bank_mask:0xf
	v_mul_f32_dpp v45, v113, v45 row_newbcast:10 row_mask:0xf bank_mask:0xf
	v_mul_f32_dpp v46, v114, v46 row_newbcast:10 row_mask:0xf bank_mask:0xf
	v_mul_f32_dpp v47, v115, v47 row_newbcast:10 row_mask:0xf bank_mask:0xf
	v_fmac_f32_dpp v44, v116, v132 row_newbcast:10 row_mask:0xf bank_mask:0xf
	v_fmac_f32_dpp v45, v117, v132 row_newbcast:10 row_mask:0xf bank_mask:0xf
	v_fmac_f32_dpp v46, v118, v132 row_newbcast:10 row_mask:0xf bank_mask:0xf
	v_fmac_f32_dpp v47, v119, v132 row_newbcast:10 row_mask:0xf bank_mask:0xf
	v_fmac_f32_dpp v128, v120, v44 row_newbcast:10 row_mask:0xf bank_mask:0xf
	v_fmac_f32_dpp v129, v121, v45 row_newbcast:10 row_mask:0xf bank_mask:0xf
	v_fmac_f32_dpp v130, v122, v46 row_newbcast:10 row_mask:0xf bank_mask:0xf
	v_fmac_f32_dpp v131, v123, v47 row_newbcast:10 row_mask:0xf bank_mask:0xf
	v_mul_f32_dpp v48, v112, v48 row_newbcast:11 row_mask:0xf bank_mask:0xf
	v_mul_f32_dpp v49, v113, v49 row_newbcast:11 row_mask:0xf bank_mask:0xf
	v_mul_f32_dpp v50, v114, v50 row_newbcast:11 row_mask:0xf bank_mask:0xf
	v_mul_f32_dpp v51, v115, v51 row_newbcast:11 row_mask:0xf bank_mask:0xf
	v_fmac_f32_dpp v48, v116, v132 row_newbcast:11 row_mask:0xf bank_mask:0xf
	v_fmac_f32_dpp v49, v117, v132 row_newbcast:11 row_mask:0xf bank_mask:0xf
	v_fmac_f32_dpp v50, v118, v132 row_newbcast:11 row_mask:0xf bank_mask:0xf
	v_fmac_f32_dpp v51, v119, v132 row_newbcast:11 row_mask:0xf bank_mask:0xf
	v_fmac_f32_dpp v128, v120, v48 row_newbcast:11 row_mask:0xf bank_mask:0xf
	v_fmac_f32_dpp v129, v121, v49 row_newbcast:11 row_mask:0xf bank_mask:0xf
	v_fmac_f32_dpp v130, v122, v50 row_newbcast:11 row_mask:0xf bank_mask:0xf
	v_fmac_f32_dpp v131, v123, v51 row_newbcast:11 row_mask:0xf bank_mask:0xf
	v_mul_f32_dpp v52, v112, v52 row_newbcast:12 row_mask:0xf bank_mask:0xf
	v_mul_f32_dpp v53, v113, v53 row_newbcast:12 row_mask:0xf bank_mask:0xf
	v_mul_f32_dpp v54, v114, v54 row_newbcast:12 row_mask:0xf bank_mask:0xf
	v_mul_f32_dpp v55, v115, v55 row_newbcast:12 row_mask:0xf bank_mask:0xf
	v_fmac_f32_dpp v52, v116, v132 row_newbcast:12 row_mask:0xf bank_mask:0xf
	v_fmac_f32_dpp v53, v117, v132 row_newbcast:12 row_mask:0xf bank_mask:0xf
	v_fmac_f32_dpp v54, v118, v132 row_newbcast:12 row_mask:0xf bank_mask:0xf
	v_fmac_f32_dpp v55, v119, v132 row_newbcast:12 row_mask:0xf bank_mask:0xf
	v_fmac_f32_dpp v128, v120, v52 row_newbcast:12 row_mask:0xf bank_mask:0xf
	v_fmac_f32_dpp v129, v121, v53 row_newbcast:12 row_mask:0xf bank_mask:0xf
	v_fmac_f32_dpp v130, v122, v54 row_newbcast:12 row_mask:0xf bank_mask:0xf
	v_fmac_f32_dpp v131, v123, v55 row_newbcast:12 row_mask:0xf bank_mask:0xf
	v_mul_f32_dpp v56, v112, v56 row_newbcast:13 row_mask:0xf bank_mask:0xf
	v_mul_f32_dpp v57, v113, v57 row_newbcast:13 row_mask:0xf bank_mask:0xf
	v_mul_f32_dpp v58, v114, v58 row_newbcast:13 row_mask:0xf bank_mask:0xf
	v_mul_f32_dpp v59, v115, v59 row_newbcast:13 row_mask:0xf bank_mask:0xf
	v_fmac_f32_dpp v56, v116, v132 row_newbcast:13 row_mask:0xf bank_mask:0xf
	v_fmac_f32_dpp v57, v117, v132 row_newbcast:13 row_mask:0xf bank_mask:0xf
	v_fmac_f32_dpp v58, v118, v132 row_newbcast:13 row_mask:0xf bank_mask:0xf
; template <bool SK>
; __device__ __forceinline__ void scan_task(const float* R, const float* W, const float* KX, const float* KK, const float* KKA, const float* V, float* OUT, float* STT, const float* S0, float* SOUT, int nstep, int lane) {
;     ...
;         for (int k = 0; k < 64; k += 2) {
;             float x = s[k] * w[k]; x = fmaf(nd, kka[k], x); if (SK) x = fmaf(vt, kx[k], x); s[k] = x; o0 = fmaf(x, r[k], o0);
;             float y = s[k + 1] * w[k + 1]; y = fmaf(nd, kka[k + 1], y); if (SK) y = fmaf(vt, kx[k + 1], y); s[k + 1] = y; o1 = fmaf(y, r[k + 1], o1);
;         }
;         OUT[(size_t)t * BW + lane] = o0 + o1;
;     }
;     asm volatile("" :: "v"(pf0), "v"(pf1), "v"(pf2), "v"(pf3), "v"(pf4));
;     if (STT) {
; #pragma unroll
;         for (int k = 0; k < 64; ++k) STT[k * 64 + lane] = s[k];
;     }
;     if (SOUT) {
; #pragma unroll
;         for (int k4 = 0; k4 < 16; ++k4) *(f32x4*)(SOUT + lane * 64 + 4 * k4) = (f32x4){s[4 * k4], s[4 * k4 + 1], s[4 * k4 + 2], s[4 * k4 + 3]};
;     }
	v_fmac_f32_dpp v59, v119, v132 row_newbcast:13 row_mask:0xf bank_mask:0xf
	v_fmac_f32_dpp v128, v120, v56 row_newbcast:13 row_mask:0xf bank_mask:0xf
	v_fmac_f32_dpp v129, v121, v57 row_newbcast:13 row_mask:0xf bank_mask:0xf
	v_fmac_f32_dpp v130, v122, v58 row_newbcast:13 row_mask:0xf bank_mask:0xf
	v_fmac_f32_dpp v131, v123, v59 row_newbcast:13 row_mask:0xf bank_mask:0xf
	v_mul_f32_dpp v60, v112, v60 row_newbcast:14 row_mask:0xf bank_mask:0xf
	v_mul_f32_dpp v61, v113, v61 row_newbcast:14 row_mask:0xf bank_mask:0xf
	v_mul_f32_dpp v62, v114, v62 row_newbcast:14 row_mask:0xf bank_mask:0xf
	v_mul_f32_dpp v63, v115, v63 row_newbcast:14 row_mask:0xf bank_mask:0xf
	v_fmac_f32_dpp v60, v116, v132 row_newbcast:14 row_mask:0xf bank_mask:0xf
	v_fmac_f32_dpp v61, v117, v132 row_newbcast:14 row_mask:0xf bank_mask:0xf
	v_fmac_f32_dpp v62, v118, v132 row_newbcast:14 row_mask:0xf bank_mask:0xf
	v_fmac_f32_dpp v63, v119, v132 row_newbcast:14 row_mask:0xf bank_mask:0xf
	v_fmac_f32_dpp v128, v120, v60 row_newbcast:14 row_mask:0xf bank_mask:0xf
	v_fmac_f32_dpp v129, v121, v61 row_newbcast:14 row_mask:0xf bank_mask:0xf
	v_fmac_f32_dpp v130, v122, v62 row_newbcast:14 row_mask:0xf bank_mask:0xf
	v_fmac_f32_dpp v131, v123, v63 row_newbcast:14 row_mask:0xf bank_mask:0xf
	v_mul_f32_dpp v64, v112, v64 row_newbcast:15 row_mask:0xf bank_mask:0xf
	v_mul_f32_dpp v65, v113, v65 row_newbcast:15 row_mask:0xf bank_mask:0xf
	v_mul_f32_dpp v66, v114, v66 row_newbcast:15 row_mask:0xf bank_mask:0xf
	v_mul_f32_dpp v67, v115, v67 row_newbcast:15 row_mask:0xf bank_mask:0xf
	v_fmac_f32_dpp v64, v116, v132 row_newbcast:15 row_mask:0xf bank_mask:0xf
	v_fmac_f32_dpp v65, v117, v132 row_newbcast:15 row_mask:0xf bank_mask:0xf
	v_fmac_f32_dpp v66, v118, v132 row_newbcast:15 row_mask:0xf bank_mask:0xf
	v_fmac_f32_dpp v67, v119, v132 row_newbcast:15 row_mask:0xf bank_mask:0xf
	v_fmac_f32_dpp v128, v120, v64 row_newbcast:15 row_mask:0xf bank_mask:0xf
	v_fmac_f32_dpp v129, v121, v65 row_newbcast:15 row_mask:0xf bank_mask:0xf
	v_fmac_f32_dpp v130, v122, v66 row_newbcast:15 row_mask:0xf bank_mask:0xf
	v_fmac_f32_dpp v131, v123, v67 row_newbcast:15 row_mask:0xf bank_mask:0xf
	global_load_dwordx4 v[112:115], v133, s[74:75] offset:2048
	global_load_dwordx4 v[116:119], v133, s[76:77] offset:2048
	global_load_dwordx4 v[120:123], v133, s[78:79] offset:2048
	v_add_f32_e32 v128, v128, v130
	v_add_f32_e32 v129, v129, v131
	v_add_f32_e32 v128, v128, v129
	global_store_dword v134, v128, s[6:7] offset:2048
	s_add_u32 s72, s72, 0x1000
	s_addc_u32 s73, s73, 0
	s_add_u32 s74, s74, 0x1000
	s_addc_u32 s75, s75, 0
	s_add_u32 s76, s76, 0x1000
	s_addc_u32 s77, s77, 0
	s_add_u32 s78, s78, 0x1000
	s_addc_u32 s79, s79, 0
	s_add_u32 s6, s6, 0x1000
	s_addc_u32 s7, s7, 0
	s_add_i32 s9, s9, 1
	s_cmp_lg_u32 s9, 32
	s_cbranch_scc1 .Lscan_p_loop
	s_waitcnt vmcnt(0)
	v_mov_b32_e32 v1, v135
	s_nop 0
	ds_read_b32 v92, v1 offset:0
	ds_read_b32 v93, v1 offset:256
	ds_read_b32 v94, v1 offset:512
	ds_read_b32 v95, v1 offset:768
	ds_read_b32 v96, v1 offset:1024
	ds_read_b32 v97, v1 offset:1280
	ds_read_b32 v98, v1 offset:1536
	ds_read_b32 v99, v1 offset:1792
	ds_read_b32 v100, v1 offset:2048
	ds_read_b32 v101, v1 offset:2304
	ds_read_b32 v102, v1 offset:2560
	ds_read_b32 v103, v1 offset:2816
	ds_read_b32 v104, v1 offset:3072
	ds_read_b32 v105, v1 offset:3328
	ds_read_b32 v106, v1 offset:3584
	ds_read_b32 v107, v1 offset:3840
	ds_read_b32 v108, v1 offset:4096
	ds_read_b32 v109, v1 offset:4352
	ds_read_b32 v110, v1 offset:4608
	ds_read_b32 v111, v1 offset:4864
	ds_read_b32 v112, v1 offset:5120
	ds_read_b32 v113, v1 offset:5376
	ds_read_b32 v114, v1 offset:5632
	ds_read_b32 v115, v1 offset:5888
	ds_read_b32 v116, v1 offset:6144
	ds_read_b32 v117, v1 offset:6400
	ds_read_b32 v118, v1 offset:6656
	ds_read_b32 v119, v1 offset:6912
	ds_read_b32 v120, v1 offset:7168
	ds_read_b32 v121, v1 offset:7424
	ds_read_b32 v122, v1 offset:7680
	ds_read_b32 v123, v1 offset:7936
	ds_read_b32 v124, v1 offset:8192
	ds_read_b32 v125, v1 offset:8448
	ds_read_b32 v126, v1 offset:8704
	ds_read_b32 v127, v1 offset:8960
	ds_read_b32 v128, v1 offset:9216
	ds_read_b32 v129, v1 offset:9472
	ds_read_b32 v130, v1 offset:9728
	ds_read_b32 v131, v1 offset:9984
	ds_read_b32 v132, v1 offset:10240
	ds_read_b32 v133, v1 offset:10496
	ds_read_b32 v134, v1 offset:10752
	ds_read_b32 v135, v1 offset:11008
	s_waitcnt lgkmcnt(0)
	v_lshlrev_b64 v[70:71], 2, v[70:71]
	v_lshlrev_b32_e32 v68, 6, v68
	v_lshl_add_u64 v[70:71], s[82:83], 0, v[70:71]
	v_ashrrev_i32_e32 v69, 31, v68
	v_lshl_add_u64 v[68:69], v[68:69], 2, v[70:71]
	s_mov_b64 s[0:1], 0x43b00000
	v_lshl_add_u64 v[70:71], v[68:69], 0, s[0:1]
	v_add_co_u32_e32 v68, vcc, 0x43b00000, v68
	v_readlane_b32 s82, v254, 57
	v_readlane_b32 s84, v254, 59
	v_readlane_b32 s86, v254, 61
	v_readlane_b32 s88, v254, 63
	v_readlane_b32 s76, v255, 1
	v_readlane_b32 s78, v255, 3
	v_readlane_b32 s90, v255, 5
	v_readlane_b32 s56, v255, 7
	v_readlane_b32 s60, v255, 9
	v_readlane_b32 s74, v255, 15
	s_movk_i32 s64, 0xf800
	v_addc_co_u32_e32 v69, vcc, 0, v69, vcc
	v_readlane_b32 s83, v254, 58
	v_readlane_b32 s85, v254, 60
	v_readlane_b32 s87, v254, 62
	v_readlane_b32 s89, v255, 0
	v_readlane_b32 s77, v255, 2
	v_readlane_b32 s79, v255, 4
	v_readlane_b32 s91, v255, 6
	v_readlane_b32 s57, v255, 8
	v_readlane_b32 s61, v255, 10
	v_readlane_b32 s62, v255, 11
	v_readlane_b32 s63, v255, 12
	s_mov_b32 s67, 0xf800000
	s_movk_i32 s68, 0x2a00
	s_movk_i32 s69, 0x1000
	s_movk_i32 s70, 0x1c00
	s_mov_b32 s71, 0x92492493
	v_readlane_b32 s72, v255, 14
	v_readlane_b32 s75, v255, 16
	s_mov_b32 s65, -1
	v_readlane_b32 s66, v255, 22
	s_waitcnt vmcnt(0)
	global_store_dwordx4 v[68:69], v[2:5], off
	global_store_dwordx4 v[70:71], v[6:9], off offset:16
	global_store_dwordx4 v[70:71], v[10:13], off offset:32
	global_store_dwordx4 v[70:71], v[14:17], off offset:48
	global_store_dwordx4 v[70:71], v[18:21], off offset:64
	global_store_dwordx4 v[70:71], v[22:25], off offset:80
	global_store_dwordx4 v[70:71], v[26:29], off offset:96
	global_store_dwordx4 v[70:71], v[30:33], off offset:112
	global_store_dwordx4 v[70:71], v[36:39], off offset:128
	global_store_dwordx4 v[70:71], v[40:43], off offset:144
	global_store_dwordx4 v[70:71], v[44:47], off offset:160
	global_store_dwordx4 v[70:71], v[48:51], off offset:176
	global_store_dwordx4 v[70:71], v[52:55], off offset:192
	global_store_dwordx4 v[70:71], v[56:59], off offset:208
	global_store_dwordx4 v[70:71], v[60:63], off offset:224
	global_store_dwordx4 v[70:71], v[64:67], off offset:240
	s_branch .LBB0_903
